# combination of timing-only edits: saddr DMA form, pass1 gate reads issued together, setprio outside barrier handoff, relaxed third wait in P1 woven iteration
# baseline (speedup 1.0000x reference)
; #define PG8_STAGE(bufoff, gbase, voff) do { _Pragma("unroll") for (int _i = 0; _i < 2; ++_i) \
;         __builtin_amdgcn_global_load_lds((const unsigned*)((const char*)(gbase) + (voff)[_i]), (PG8_LAS unsigned*)(lds + (bufoff) + ldsw + _i * 8192), 16, 0, 0); } while (0)
; #define PG8_BAR __builtin_amdgcn_s_barrier()
; template <class Epi, class Sched, bool ALIGN_EPI = false, bool SP2 = false>
; __device__ __forceinline__ void gemm_phase(PG8_LAS unsigned char* lds, const Gemm g, const Sched& S, const Epi& E) {
;     ...
;         const bool has_next = S.next(ui + 1, nxt);
;         const char* nA = has_next ? (const char*)g.A + (size_t)nxt.pm * tstep : cA; const char* nB = has_next ? (const char*)g.Bt + (size_t)nxt.pn * tstep : cB;
;         for (int t = 0; t < nt; t += 2) {
;             const bool last = (t == nt - 2);
;             const char* a1 = cA + (size_t)(t + 1) * kstep;
;             const char* a2 = last ? nA : cA + (size_t)(t + 2) * kstep; const char* b2 = last ? nB : cB + (size_t)(t + 2) * kstep;
;             const char* a3 = a2 + kstep; const char* b3 = b2 + kstep;
;             if (last && has_next) S.a_ready(nxt);
;             if constexpr (SP2) {
;             PG8_LDB(B0, 0, 0); PG8_LDB(B1, 0, 1); PG8_SCHED; PG8_LDA(At, 0, 0); PG8_STAGE(PG8_SA(1, 1), a1 + hstep, voffA);
;             PG8_WAIT_V(8); PG8_WAIT_L(0); PG8_BAR; PG8_MMA(0, 0, At, B0); PG8_MMA(0, 1, At, B1); PG8_BAR; PG8_SCHED;
;     __device__ __forceinline__ void operator()(const f32x4 (&acc)[2][2][4][2], const pg8::Unit& u, int wr, int wc, int fr, int fq) const {
;         const int row0 = u.pm * 256 + wr * 64 + fr, col = u.pn * 128 + wc * 32 + 8 * fq;
; #pragma unroll
;         for (int ai = 0; ai < 2; ++ai)
; #pragma unroll
;             for (int m = 0; m < 4; ++m) {
;                 const int row = row0 + ai * 128 + m * 16;
;                 const float rs = sumsq ? rsqrtf(sumsq[row] * (1.f / 1024.f) + EPS) : 1.f;
;                 float o[8];
; #pragma unroll
;                 for (int n = 0; n < 2; ++n)
; #pragma unroll
;                     for (int e = 0; e < 4; ++e) { const float g = acc[ai][0][m][n][e] * rs, up = acc[ai][1][m][n][e] * rs; o[4 * n + e] = silu_f(g) * up; }
;                 u32x4 w; w.x = pk2(o[0], o[1]); w.y = pk2(o[2], o[3]); w.z = pk2(o[4], o[5]); w.w = pk2(o[6], o[7]);
;                 *(u32x4*)(H + (size_t)row * DFF + col) = w;
.LBB0_191:
	s_ashr_i32 s15, s14, 31
	s_lshl_b64 s[16:17], s[14:15], 19
	v_readlane_b32 s18, v235, 31
	v_readlane_b32 s19, v235, 32
	s_add_u32 s16, s18, s16
	s_addc_u32 s17, s19, s17
	s_and_b64 s[18:19], s[0:1], exec
	s_cselect_b32 s15, s17, s23
	s_cselect_b32 s50, s16, s22
	s_ashr_i32 s9, s8, 31
	s_lshl_b64 s[18:19], s[8:9], 19
	s_add_u32 s18, s33, s18
	s_addc_u32 s19, s34, s19
	s_and_b64 s[30:31], s[0:1], exec
	s_cselect_b32 s9, s19, s25
	s_cselect_b32 s51, s18, s24
	s_add_u32 s22, s22, 0x40080
	s_addc_u32 s23, s23, 0
	s_add_u32 s52, s24, 0x100
	s_addc_u32 s53, s25, 0
	s_mov_b32 s54, -2
	s_cmp_eq_u32 s98, 0
	s_cbranch_scc1 .Lp1_plain
	ds_read_b128 v[150:153], v147
	ds_read_b128 v[154:157], v147 offset:1024
	ds_read_b128 v[158:161], v147 offset:2048
	ds_read_b128 v[162:165], v147 offset:3072
	ds_read_b128 v[166:169], v148
	ds_read_b128 v[170:173], v148 offset:1024
	ds_read_b128 v[174:177], v148 offset:2048
	ds_read_b128 v[178:181], v148 offset:3072
	s_add_u32 s24, s22, 0xfffc0080
	s_addc_u32 s25, s23, -1
	s_cmp_eq_u32 s54, 12
	s_cselect_b32 s31, s15, s25
	s_cselect_b32 s30, s50, s24
	s_cselect_b32 s25, s9, s53
	s_cselect_b32 s24, s51, s52
	s_add_i32 m0, s21, 0xc000
	ds_read_b128 v[182:185], v149
	ds_read_b128 v[192:195], v149 offset:1024
	ds_read_b128 v[196:199], v149 offset:2048
	ds_read_b128 v[200:203], v149 offset:3072
	ds_read_b128 v[204:207], v149 offset:4096
	ds_read_b128 v[208:211], v149 offset:5120
	ds_read_b128 v[212:215], v149 offset:6144
	ds_read_b128 v[216:219], v149 offset:7168
	global_load_lds_dwordx4 v136, s[22:23]
	s_add_i32 m0, s21, 0xe000
	s_nop 0
	global_load_lds_dwordx4 v138, s[22:23]
	s_nop 1
	v_add_f32_e32 v64, 1.0, v70
	v_rcp_f32_e32 v64, v64
	v_add_f32_e32 v65, 1.0, v71
	v_rcp_f32_e32 v65, v65
	v_add_u32_e32 v66, 0x80, v228
	v_mul_f32_e32 v60, v60, v64
	v_mul_f32_e32 v52, v60, v52
	v_mul_f32_e32 v60, v61, v65
	v_mul_f32_e32 v61, 0xbfb8aa3b, v62
	v_exp_f32_e32 v61, v61
	v_mul_f32_e32 v64, 0xbfb8aa3b, v63
	v_exp_f32_e32 v64, v64
	v_mul_f32_e32 v53, v60, v53
	v_add_f32_e32 v60, 1.0, v61
	v_rcp_f32_e32 v60, v60
	v_add_f32_e32 v61, 1.0, v64
	v_mul_f32_e32 v64, 0xbfb8aa3b, v56
	v_rcp_f32_e32 v61, v61
	v_exp_f32_e32 v64, v64
	v_mul_f32_e32 v60, v62, v60
	v_mul_f32_e32 v54, v60, v54
	v_mul_f32_e32 v60, v63, v61
	v_add_f32_e32 v61, 1.0, v64
	v_rcp_f32_e32 v61, v61
	v_mul_f32_e32 v62, 0xbfb8aa3b, v57
	v_exp_f32_e32 v62, v62
	v_mul_f32_e32 v55, v60, v55
	v_mul_f32_e32 v56, v56, v61
	v_mul_f32_e32 v56, v56, v48
	v_add_f32_e32 v48, 1.0, v62
	v_mul_f32_e32 v60, 0xbfb8aa3b, v58
	v_rcp_f32_e32 v48, v48
	v_exp_f32_e32 v60, v60
	v_mul_f32_e32 v61, 0xbfb8aa3b, v59
	v_exp_f32_e32 v61, v61
	v_mul_f32_e32 v48, v57, v48
	v_add_f32_e32 v57, 1.0, v60
	v_rcp_f32_e32 v57, v57
	v_add_f32_e32 v60, 1.0, v61
	v_rcp_f32_e32 v60, v60
	v_mul_f32_e32 v61, v48, v49
	v_mul_f32_e32 v48, v58, v57
	v_mul_f32_e32 v57, v48, v50
	v_mul_f32_e32 v48, v59, v60
	v_mul_f32_e32 v51, v48, v51
	v_cvt_pk_bf16_f32 v48, v52, v53
	v_cvt_pk_bf16_f32 v49, v54, v55
	v_mul_f32_e32 v54, 0xbfb8aa3b, v44
	v_exp_f32_e32 v54, v54
	v_mul_f32_e32 v55, 0xbfb8aa3b, v45
	v_exp_f32_e32 v55, v55
	v_mad_i64_i32 v[52:53], s[100:101], v66, s48, v[112:113]
	v_lshl_add_u64 v[52:53], v[52:53], 0, v[114:115]
	v_cvt_pk_bf16_f32 v50, v56, v61
	v_cvt_pk_bf16_f32 v51, v57, v51
	global_store_dwordx4 v[52:53], v[48:51], off
	s_nop 1
	v_add_f32_e32 v48, 1.0, v54
	v_rcp_f32_e32 v48, v48
	v_add_f32_e32 v49, 1.0, v55
	v_rcp_f32_e32 v49, v49
	v_add_u32_e32 v50, 0x90, v228
	v_mul_f32_e32 v44, v44, v48
	v_mul_f32_e32 v36, v44, v36
	v_mul_f32_e32 v44, v45, v49
	v_mul_f32_e32 v45, 0xbfb8aa3b, v46
	v_exp_f32_e32 v45, v45
	v_mul_f32_e32 v48, 0xbfb8aa3b, v47
	v_exp_f32_e32 v48, v48
	v_mul_f32_e32 v37, v44, v37
	v_add_f32_e32 v44, 1.0, v45
	v_rcp_f32_e32 v44, v44
	v_add_f32_e32 v45, 1.0, v48
	v_mul_f32_e32 v48, 0xbfb8aa3b, v40
	v_rcp_f32_e32 v45, v45
	v_exp_f32_e32 v48, v48
	v_mul_f32_e32 v44, v46, v44
	v_mul_f32_e32 v38, v44, v38
	v_mul_f32_e32 v44, v47, v45
	v_add_f32_e32 v45, 1.0, v48
	v_rcp_f32_e32 v45, v45
	v_mul_f32_e32 v46, 0xbfb8aa3b, v41
	v_exp_f32_e32 v46, v46
	v_mul_f32_e32 v39, v44, v39
	v_mul_f32_e32 v40, v40, v45
	v_mul_f32_e32 v40, v40, v32
	v_add_f32_e32 v32, 1.0, v46
	v_mul_f32_e32 v44, 0xbfb8aa3b, v42
	v_rcp_f32_e32 v32, v32
	v_exp_f32_e32 v44, v44
	v_mul_f32_e32 v45, 0xbfb8aa3b, v43
	v_exp_f32_e32 v45, v45
	v_mul_f32_e32 v32, v41, v32
	v_add_f32_e32 v41, 1.0, v44
	v_rcp_f32_e32 v41, v41
	v_add_f32_e32 v44, 1.0, v45
	v_rcp_f32_e32 v44, v44
	v_mul_f32_e32 v45, v32, v33
	v_mul_f32_e32 v32, v42, v41
	v_mul_f32_e32 v41, v32, v34
	v_mul_f32_e32 v32, v43, v44
	v_mul_f32_e32 v35, v32, v35
	v_cvt_pk_bf16_f32 v32, v36, v37
	v_cvt_pk_bf16_f32 v33, v38, v39
	v_mul_f32_e32 v38, 0xbfb8aa3b, v28
	v_exp_f32_e32 v38, v38
	v_mul_f32_e32 v39, 0xbfb8aa3b, v29
	v_exp_f32_e32 v39, v39
	v_mad_i64_i32 v[36:37], s[100:101], v50, s48, v[112:113]
	v_lshl_add_u64 v[36:37], v[36:37], 0, v[114:115]
	v_cvt_pk_bf16_f32 v34, v40, v45
	v_cvt_pk_bf16_f32 v35, v41, v35
	global_store_dwordx4 v[36:37], v[32:35], off
	s_nop 1
	v_add_f32_e32 v32, 1.0, v38
	v_rcp_f32_e32 v32, v32
	v_add_f32_e32 v33, 1.0, v39
	v_rcp_f32_e32 v33, v33
	v_add_u32_e32 v34, 0xa0, v228
	v_mul_f32_e32 v28, v28, v32
	v_mul_f32_e32 v20, v28, v20
	v_mul_f32_e32 v28, v29, v33
	v_mul_f32_e32 v29, 0xbfb8aa3b, v30
	v_exp_f32_e32 v29, v29
	v_mul_f32_e32 v32, 0xbfb8aa3b, v31
	v_exp_f32_e32 v32, v32
	v_mul_f32_e32 v21, v28, v21
	v_add_f32_e32 v28, 1.0, v29
	v_rcp_f32_e32 v28, v28
	v_add_f32_e32 v29, 1.0, v32
	v_mul_f32_e32 v32, 0xbfb8aa3b, v24
	v_rcp_f32_e32 v29, v29
	v_exp_f32_e32 v32, v32
	v_mul_f32_e32 v28, v30, v28
	v_mul_f32_e32 v22, v28, v22
; #define PG8_STAGE(bufoff, gbase, voff) do { _Pragma("unroll") for (int _i = 0; _i < 2; ++_i) \
;         __builtin_amdgcn_global_load_lds((const unsigned*)((const char*)(gbase) + (voff)[_i]), (PG8_LAS unsigned*)(lds + (bufoff) + ldsw + _i * 8192), 16, 0, 0); } while (0)
; #define PG8_LDA(dst, b, h) do { _Pragma("unroll") for (int m = 0; m < 4; ++m) _Pragma("unroll") for (int k = 0; k < 2; ++k) dst[m][k] = *(const PG8_LAS bf16x8*)(lds + PG8_SA(b, h) + aoff + m * 2048 + k * 1024); } while (0)
; #define PG8_LDB(dst, b, h) do { _Pragma("unroll") for (int n = 0; n < 2; ++n) _Pragma("unroll") for (int k = 0; k < 2; ++k) dst[n][k] = *(const PG8_LAS bf16x8*)(lds + PG8_SB(b, h) + boff + n * 2048 + k * 1024); } while (0)
; template <class Epi, class Sched, bool ALIGN_EPI = false, bool SP2 = false>
; __device__ __forceinline__ void gemm_phase(PG8_LAS unsigned char* lds, const Gemm g, const Sched& S, const Epi& E) {
;     ...
;             PG8_LDB(B0, 0, 0); PG8_LDB(B1, 0, 1); PG8_SCHED; PG8_LDA(At, 0, 0); PG8_STAGE(PG8_SA(1, 1), a1 + hstep, voffA);
;             PG8_WAIT_V(8); PG8_WAIT_L(0); PG8_BAR; PG8_MMA(0, 0, At, B0); PG8_MMA(0, 1, At, B1); PG8_BAR; PG8_SCHED;
;             PG8_LDA(At, 0, 1); PG8_STAGE(PG8_SB(0, 0), b2, voffB); PG8_STAGE(PG8_SB(0, 1), b2 + hstep, voffB); PG8_STAGE(PG8_SA(0, 0), a2, voffA);
;             PG8_WAIT_V(8); PG8_WAIT_L(0); PG8_BAR; PG8_MMA(1, 0, At, B0); PG8_MMA(1, 1, At, B1); PG8_BAR; PG8_SCHED;
;     __device__ __forceinline__ void operator()(const f32x4 (&acc)[2][2][4][2], const pg8::Unit& u, int wr, int wc, int fr, int fq) const {
;         const int row0 = u.pm * 256 + wr * 64 + fr, col = u.pn * 128 + wc * 32 + 8 * fq;
; #pragma unroll
;         for (int ai = 0; ai < 2; ++ai)
; #pragma unroll
;             for (int m = 0; m < 4; ++m) {
;                 const int row = row0 + ai * 128 + m * 16;
;                 const float rs = sumsq ? rsqrtf(sumsq[row] * (1.f / 1024.f) + EPS) : 1.f;
;                 float o[8];
; #pragma unroll
;                 for (int n = 0; n < 2; ++n)
; #pragma unroll
;                     for (int e = 0; e < 4; ++e) { const float g = acc[ai][0][m][n][e] * rs, up = acc[ai][1][m][n][e] * rs; o[4 * n + e] = silu_f(g) * up; }
;                 u32x4 w; w.x = pk2(o[0], o[1]); w.y = pk2(o[2], o[3]); w.z = pk2(o[4], o[5]); w.w = pk2(o[6], o[7]);
;                 *(u32x4*)(H + (size_t)row * DFF + col) = w;
	v_mul_f32_e32 v28, v31, v29
	v_add_f32_e32 v29, 1.0, v32
	v_rcp_f32_e32 v29, v29
	v_mul_f32_e32 v30, 0xbfb8aa3b, v25
	v_exp_f32_e32 v30, v30
	v_mul_f32_e32 v23, v28, v23
	v_mul_f32_e32 v24, v24, v29
	v_mul_f32_e32 v24, v24, v16
	v_add_f32_e32 v16, 1.0, v30
	v_mul_f32_e32 v28, 0xbfb8aa3b, v26
	v_rcp_f32_e32 v16, v16
	v_exp_f32_e32 v28, v28
	v_mul_f32_e32 v29, 0xbfb8aa3b, v27
	v_exp_f32_e32 v29, v29
	v_mul_f32_e32 v16, v25, v16
	v_add_f32_e32 v25, 1.0, v28
	v_rcp_f32_e32 v25, v25
	v_add_f32_e32 v28, 1.0, v29
	v_rcp_f32_e32 v28, v28
	v_mul_f32_e32 v29, v16, v17
	v_mul_f32_e32 v16, v26, v25
	v_mul_f32_e32 v25, v16, v18
	v_mul_f32_e32 v16, v27, v28
	v_mul_f32_e32 v19, v16, v19
	v_cvt_pk_bf16_f32 v16, v20, v21
	v_cvt_pk_bf16_f32 v17, v22, v23
	v_mul_f32_e32 v22, 0xbfb8aa3b, v12
	v_exp_f32_e32 v22, v22
	v_mul_f32_e32 v23, 0xbfb8aa3b, v13
	v_exp_f32_e32 v23, v23
	v_mad_i64_i32 v[20:21], s[100:101], v34, s48, v[112:113]
	v_lshl_add_u64 v[20:21], v[20:21], 0, v[114:115]
	v_cvt_pk_bf16_f32 v18, v24, v29
	v_cvt_pk_bf16_f32 v19, v25, v19
	global_store_dwordx4 v[20:21], v[16:19], off
	s_nop 1
	v_add_f32_e32 v16, 1.0, v22
	v_rcp_f32_e32 v16, v16
	v_add_f32_e32 v17, 1.0, v23
	v_rcp_f32_e32 v17, v17
	v_add_u32_e32 v18, 0xb0, v228
	v_mul_f32_e32 v12, v12, v16
	v_mul_f32_e32 v4, v12, v4
	v_mul_f32_e32 v12, v13, v17
	v_mul_f32_e32 v13, 0xbfb8aa3b, v14
	v_exp_f32_e32 v13, v13
	v_mul_f32_e32 v16, 0xbfb8aa3b, v15
	v_exp_f32_e32 v16, v16
	v_mul_f32_e32 v5, v12, v5
	v_add_f32_e32 v12, 1.0, v13
	v_rcp_f32_e32 v12, v12
	v_add_f32_e32 v13, 1.0, v16
	v_mul_f32_e32 v16, 0xbfb8aa3b, v8
	v_rcp_f32_e32 v13, v13
	v_exp_f32_e32 v16, v16
	v_mul_f32_e32 v12, v14, v12
	v_mul_f32_e32 v6, v12, v6
	v_mul_f32_e32 v12, v15, v13
	v_add_f32_e32 v13, 1.0, v16
	v_rcp_f32_e32 v13, v13
	v_mul_f32_e32 v14, 0xbfb8aa3b, v9
	v_exp_f32_e32 v14, v14
	v_mul_f32_e32 v7, v12, v7
	v_mul_f32_e32 v8, v8, v13
	v_mul_f32_e32 v8, v8, v0
	v_add_f32_e32 v0, 1.0, v14
	v_mul_f32_e32 v12, 0xbfb8aa3b, v10
	v_rcp_f32_e32 v0, v0
	v_exp_f32_e32 v12, v12
	v_mul_f32_e32 v13, 0xbfb8aa3b, v11
	v_exp_f32_e32 v13, v13
	v_mul_f32_e32 v0, v9, v0
	v_add_f32_e32 v9, 1.0, v12
	v_rcp_f32_e32 v9, v9
	v_add_f32_e32 v12, 1.0, v13
	v_rcp_f32_e32 v12, v12
	v_mul_f32_e32 v13, v0, v1
	v_mul_f32_e32 v0, v10, v9
	v_mul_f32_e32 v9, v0, v2
	v_mul_f32_e32 v0, v11, v12
	v_mul_f32_e32 v3, v0, v3
	v_cvt_pk_bf16_f32 v0, v4, v5
	v_mad_i64_i32 v[4:5], s[100:101], v18, s48, v[112:113]
	v_lshl_add_u64 v[4:5], v[4:5], 0, v[114:115]
	v_cvt_pk_bf16_f32 v1, v6, v7
	v_cvt_pk_bf16_f32 v2, v8, v13
	v_cvt_pk_bf16_f32 v3, v9, v3
	global_store_dwordx4 v[4:5], v[0:3], off
	s_waitcnt vmcnt(16)
	s_waitcnt lgkmcnt(0)
	s_setprio 1
	s_barrier
	v_mfma_f32_16x16x32_bf16 v[124:127], v[150:153], v[182:185], 0
	v_mfma_f32_16x16x32_bf16 v[120:123], v[158:161], v[182:185], 0
	v_mfma_f32_16x16x32_bf16 v[108:111], v[150:153], v[196:199], 0
	v_mfma_f32_16x16x32_bf16 v[104:107], v[158:161], v[196:199], 0
	v_mfma_f32_16x16x32_bf16 v[92:95], v[150:153], v[204:207], 0
	v_mfma_f32_16x16x32_bf16 v[88:91], v[158:161], v[204:207], 0
	v_mfma_f32_16x16x32_bf16 v[76:79], v[150:153], v[212:215], 0
	v_mfma_f32_16x16x32_bf16 v[72:75], v[158:161], v[212:215], 0
	v_mfma_f32_16x16x32_bf16 v[124:127], v[154:157], v[192:195], v[124:127]
	v_mfma_f32_16x16x32_bf16 v[120:123], v[162:165], v[192:195], v[120:123]
	v_mfma_f32_16x16x32_bf16 v[108:111], v[154:157], v[200:203], v[108:111]
	v_mfma_f32_16x16x32_bf16 v[104:107], v[162:165], v[200:203], v[104:107]
	v_mfma_f32_16x16x32_bf16 v[92:95], v[154:157], v[208:211], v[92:95]
	v_mfma_f32_16x16x32_bf16 v[88:91], v[162:165], v[208:211], v[88:91]
	v_mfma_f32_16x16x32_bf16 v[76:79], v[154:157], v[216:219], v[76:79]
	v_mfma_f32_16x16x32_bf16 v[72:75], v[162:165], v[216:219], v[72:75]
	v_mfma_f32_16x16x32_bf16 v[116:119], v[166:169], v[182:185], 0
	v_mfma_f32_16x16x32_bf16 v[112:115], v[174:177], v[182:185], 0
	v_mfma_f32_16x16x32_bf16 v[100:103], v[166:169], v[196:199], 0
	v_mfma_f32_16x16x32_bf16 v[96:99], v[174:177], v[196:199], 0
	v_mfma_f32_16x16x32_bf16 v[84:87], v[166:169], v[204:207], 0
	v_mfma_f32_16x16x32_bf16 v[80:83], v[174:177], v[204:207], 0
	v_mfma_f32_16x16x32_bf16 v[68:71], v[166:169], v[212:215], 0
	v_mfma_f32_16x16x32_bf16 v[64:67], v[174:177], v[212:215], 0
	v_mfma_f32_16x16x32_bf16 v[116:119], v[170:173], v[192:195], v[116:119]
	v_mfma_f32_16x16x32_bf16 v[112:115], v[178:181], v[192:195], v[112:115]
	v_mfma_f32_16x16x32_bf16 v[100:103], v[170:173], v[200:203], v[100:103]
	v_mfma_f32_16x16x32_bf16 v[96:99], v[178:181], v[200:203], v[96:99]
	v_mfma_f32_16x16x32_bf16 v[84:87], v[170:173], v[208:211], v[84:87]
	v_mfma_f32_16x16x32_bf16 v[80:83], v[178:181], v[208:211], v[80:83]
	v_mfma_f32_16x16x32_bf16 v[68:71], v[170:173], v[216:219], v[68:71]
	v_mfma_f32_16x16x32_bf16 v[64:67], v[178:181], v[216:219], v[64:67]
	s_barrier
	s_setprio 0
	s_add_i32 s55, s46, s35
	v_lshl_add_u64 v[186:187], s[24:25], 0, v[132:133]
	s_mov_b32 m0, s55
	ds_read_b128 v[182:185], v149 offset:16384
	ds_read_b128 v[192:195], v149 offset:17408
	ds_read_b128 v[196:199], v149 offset:18432
	ds_read_b128 v[200:203], v149 offset:19456
	ds_read_b128 v[204:207], v149 offset:20480
	ds_read_b128 v[208:211], v149 offset:21504
	ds_read_b128 v[212:215], v149 offset:22528
	ds_read_b128 v[216:219], v149 offset:23552
	global_load_lds_dwordx4 v[186:187], off
	s_add_i32 m0, s55, 0x2000
	s_add_u32 s56, s24, 0x40000
	v_lshl_add_u64 v[220:221], s[24:25], 0, v[128:129]
	s_addc_u32 s57, s25, 0
	s_add_i32 s55, s47, s35
	global_load_lds_dwordx4 v[220:221], off
	s_mov_b32 m0, s55
	v_lshl_add_u64 v[224:225], s[30:31], 0, v[130:131]
	global_load_lds_dwordx4 v132, s[56:57]
	s_add_i32 m0, s55, 0x2000
	s_nop 0
	global_load_lds_dwordx4 v128, s[56:57]
	v_lshl_add_u64 v[222:223], s[30:31], 0, v[134:135]
	s_mov_b32 m0, s21
	s_nop 0
	global_load_lds_dwordx4 v[222:223], off
	s_mov_b32 m0, s38
	s_nop 0
	global_load_lds_dwordx4 v[224:225], off
	s_waitcnt vmcnt(16)
	s_waitcnt lgkmcnt(0)
	s_setprio 1
	s_barrier
; #define PG8_STAGE(bufoff, gbase, voff) do { _Pragma("unroll") for (int _i = 0; _i < 2; ++_i) \
;         __builtin_amdgcn_global_load_lds((const unsigned*)((const char*)(gbase) + (voff)[_i]), (PG8_LAS unsigned*)(lds + (bufoff) + ldsw + _i * 8192), 16, 0, 0); } while (0)
; #define PG8_LDA(dst, b, h) do { _Pragma("unroll") for (int m = 0; m < 4; ++m) _Pragma("unroll") for (int k = 0; k < 2; ++k) dst[m][k] = *(const PG8_LAS bf16x8*)(lds + PG8_SA(b, h) + aoff + m * 2048 + k * 1024); } while (0)
; #define PG8_LDB(dst, b, h) do { _Pragma("unroll") for (int n = 0; n < 2; ++n) _Pragma("unroll") for (int k = 0; k < 2; ++k) dst[n][k] = *(const PG8_LAS bf16x8*)(lds + PG8_SB(b, h) + boff + n * 2048 + k * 1024); } while (0)
; #define PG8_MMA(ai, bj, At, Bt) do { __builtin_amdgcn_s_setprio(1); _Pragma("unroll") for (int m = 0; m < 4; ++m) _Pragma("unroll") for (int n = 0; n < 2; ++n) _Pragma("unroll") for (int k = 0; k < 2; ++k) \
;         acc[ai][bj][m][n] = __builtin_amdgcn_mfma_f32_16x16x32_bf16(Bt[n][k], At[m][k], acc[ai][bj][m][n], 0, 0, 0); __builtin_amdgcn_s_setprio(0); } while (0)
; #define PG8_WAIT_V(n) asm volatile("s_waitcnt vmcnt(" #n ")" ::: "memory")
; #define PG8_WAIT_L(n) asm volatile("s_waitcnt lgkmcnt(" #n ")" ::: "memory")
; #define PG8_BAR __builtin_amdgcn_s_barrier()
; #define PG8_SCHED __builtin_amdgcn_sched_barrier(0)
; template <class Epi, class Sched, bool ALIGN_EPI = false, bool SP2 = false>
; __device__ __forceinline__ void gemm_phase(PG8_LAS unsigned char* lds, const Gemm g, const Sched& S, const Epi& E) {
;     ...
;             PG8_LDA(At, 0, 1); PG8_STAGE(PG8_SB(0, 0), b2, voffB); PG8_STAGE(PG8_SB(0, 1), b2 + hstep, voffB); PG8_STAGE(PG8_SA(0, 0), a2, voffA);
;             PG8_WAIT_V(8); PG8_WAIT_L(0); PG8_BAR; PG8_MMA(1, 0, At, B0); PG8_MMA(1, 1, At, B1); PG8_BAR; PG8_SCHED;
;             PG8_LDB(B0, 1, 0); PG8_LDB(B1, 1, 1); PG8_SCHED; PG8_LDA(At, 1, 0); PG8_STAGE(PG8_SA(0, 1), a2 + hstep, voffA);
;             PG8_WAIT_V(8); PG8_WAIT_L(0); PG8_BAR; PG8_MMA(0, 0, At, B0); PG8_MMA(0, 1, At, B1); PG8_BAR; PG8_SCHED;
	v_mfma_f32_16x16x32_bf16 v[60:63], v[150:153], v[182:185], 0
	v_mfma_f32_16x16x32_bf16 v[56:59], v[158:161], v[182:185], 0
	v_mfma_f32_16x16x32_bf16 v[44:47], v[150:153], v[196:199], 0
	v_mfma_f32_16x16x32_bf16 v[40:43], v[158:161], v[196:199], 0
	v_mfma_f32_16x16x32_bf16 v[28:31], v[150:153], v[204:207], 0
	v_mfma_f32_16x16x32_bf16 v[24:27], v[158:161], v[204:207], 0
	v_mfma_f32_16x16x32_bf16 v[12:15], v[150:153], v[212:215], 0
	v_mfma_f32_16x16x32_bf16 v[8:11], v[158:161], v[212:215], 0
	v_mfma_f32_16x16x32_bf16 v[60:63], v[154:157], v[192:195], v[60:63]
	v_mfma_f32_16x16x32_bf16 v[56:59], v[162:165], v[192:195], v[56:59]
	v_mfma_f32_16x16x32_bf16 v[44:47], v[154:157], v[200:203], v[44:47]
	v_mfma_f32_16x16x32_bf16 v[40:43], v[162:165], v[200:203], v[40:43]
	v_mfma_f32_16x16x32_bf16 v[28:31], v[154:157], v[208:211], v[28:31]
	v_mfma_f32_16x16x32_bf16 v[24:27], v[162:165], v[208:211], v[24:27]
	v_mfma_f32_16x16x32_bf16 v[12:15], v[154:157], v[216:219], v[12:15]
	v_mfma_f32_16x16x32_bf16 v[8:11], v[162:165], v[216:219], v[8:11]
	v_mfma_f32_16x16x32_bf16 v[52:55], v[166:169], v[182:185], 0
	v_mfma_f32_16x16x32_bf16 v[48:51], v[174:177], v[182:185], 0
	v_mfma_f32_16x16x32_bf16 v[36:39], v[166:169], v[196:199], 0
	v_mfma_f32_16x16x32_bf16 v[32:35], v[174:177], v[196:199], 0
	v_mfma_f32_16x16x32_bf16 v[20:23], v[166:169], v[204:207], 0
	v_mfma_f32_16x16x32_bf16 v[16:19], v[174:177], v[204:207], 0
	v_mfma_f32_16x16x32_bf16 v[4:7], v[166:169], v[212:215], 0
	v_mfma_f32_16x16x32_bf16 v[0:3], v[174:177], v[212:215], 0
	v_mfma_f32_16x16x32_bf16 v[52:55], v[170:173], v[192:195], v[52:55]
	v_mfma_f32_16x16x32_bf16 v[48:51], v[178:181], v[192:195], v[48:51]
	v_mfma_f32_16x16x32_bf16 v[36:39], v[170:173], v[200:203], v[36:39]
	v_mfma_f32_16x16x32_bf16 v[32:35], v[178:181], v[200:203], v[32:35]
	v_mfma_f32_16x16x32_bf16 v[20:23], v[170:173], v[208:211], v[20:23]
	v_mfma_f32_16x16x32_bf16 v[16:19], v[178:181], v[208:211], v[16:19]
	v_mfma_f32_16x16x32_bf16 v[4:7], v[170:173], v[216:219], v[4:7]
	v_mfma_f32_16x16x32_bf16 v[0:3], v[178:181], v[216:219], v[0:3]
	s_barrier
	s_setprio 0
	s_add_i32 s55, 0, 0x18000
	s_add_i32 s56, 0, 0x1c000
	v_add_u32_e32 v162, s55, v145
	v_add_u32_e32 v178, s56, v145
	ds_read_b128 v[150:153], v162
	ds_read_b128 v[154:157], v162 offset:1024
	ds_read_b128 v[158:161], v162 offset:2048
	ds_read_b128 v[162:165], v162 offset:3072
	ds_read_b128 v[166:169], v178
	ds_read_b128 v[170:173], v178 offset:1024
	ds_read_b128 v[174:177], v178 offset:2048
	ds_read_b128 v[178:181], v178 offset:3072
	s_add_u32 s30, s30, 0x40000
	s_addc_u32 s31, s31, 0
	s_mov_b32 m0, s39
	ds_read_b128 v[182:185], v149 offset:32768
	ds_read_b128 v[192:195], v149 offset:33792
	ds_read_b128 v[196:199], v149 offset:34816
	ds_read_b128 v[200:203], v149 offset:35840
	ds_read_b128 v[204:207], v149 offset:36864
	ds_read_b128 v[208:211], v149 offset:37888
	ds_read_b128 v[212:215], v149 offset:38912
	ds_read_b128 v[216:219], v149 offset:39936
	global_load_lds_dwordx4 v134, s[30:31]
	v_lshl_add_u64 v[226:227], s[30:31], 0, v[130:131]
	s_mov_b32 m0, s40
	s_nop 0
	global_load_lds_dwordx4 v[226:227], off
	s_waitcnt vmcnt(12)
	s_waitcnt lgkmcnt(0)
	s_setprio 1
	s_barrier
	v_mfma_f32_16x16x32_bf16 v[124:127], v[150:153], v[182:185], v[124:127]
	v_mfma_f32_16x16x32_bf16 v[120:123], v[158:161], v[182:185], v[120:123]
	v_mfma_f32_16x16x32_bf16 v[108:111], v[150:153], v[196:199], v[108:111]
	v_mfma_f32_16x16x32_bf16 v[104:107], v[158:161], v[196:199], v[104:107]
	v_mfma_f32_16x16x32_bf16 v[92:95], v[150:153], v[204:207], v[92:95]
	v_mfma_f32_16x16x32_bf16 v[88:91], v[158:161], v[204:207], v[88:91]
	v_mfma_f32_16x16x32_bf16 v[76:79], v[150:153], v[212:215], v[76:79]
	v_mfma_f32_16x16x32_bf16 v[72:75], v[158:161], v[212:215], v[72:75]
	v_mfma_f32_16x16x32_bf16 v[124:127], v[154:157], v[192:195], v[124:127]
	v_mfma_f32_16x16x32_bf16 v[120:123], v[162:165], v[192:195], v[120:123]
	v_mfma_f32_16x16x32_bf16 v[108:111], v[154:157], v[200:203], v[108:111]
	v_mfma_f32_16x16x32_bf16 v[104:107], v[162:165], v[200:203], v[104:107]
	v_mfma_f32_16x16x32_bf16 v[92:95], v[154:157], v[208:211], v[92:95]
	v_mfma_f32_16x16x32_bf16 v[88:91], v[162:165], v[208:211], v[88:91]
	v_mfma_f32_16x16x32_bf16 v[76:79], v[154:157], v[216:219], v[76:79]
	v_mfma_f32_16x16x32_bf16 v[72:75], v[162:165], v[216:219], v[72:75]
	v_mfma_f32_16x16x32_bf16 v[116:119], v[166:169], v[182:185], v[116:119]
	v_mfma_f32_16x16x32_bf16 v[112:115], v[174:177], v[182:185], v[112:115]
	v_mfma_f32_16x16x32_bf16 v[100:103], v[166:169], v[196:199], v[100:103]
	v_mfma_f32_16x16x32_bf16 v[96:99], v[174:177], v[196:199], v[96:99]
	v_mfma_f32_16x16x32_bf16 v[84:87], v[166:169], v[204:207], v[84:87]
	v_mfma_f32_16x16x32_bf16 v[80:83], v[174:177], v[204:207], v[80:83]
	v_mfma_f32_16x16x32_bf16 v[68:71], v[166:169], v[212:215], v[68:71]
	v_mfma_f32_16x16x32_bf16 v[64:67], v[174:177], v[212:215], v[64:67]
	v_mfma_f32_16x16x32_bf16 v[116:119], v[170:173], v[192:195], v[116:119]
	v_mfma_f32_16x16x32_bf16 v[112:115], v[178:181], v[192:195], v[112:115]
	v_mfma_f32_16x16x32_bf16 v[100:103], v[170:173], v[200:203], v[100:103]
	v_mfma_f32_16x16x32_bf16 v[96:99], v[178:181], v[200:203], v[96:99]
	v_mfma_f32_16x16x32_bf16 v[84:87], v[170:173], v[208:211], v[84:87]
	v_mfma_f32_16x16x32_bf16 v[80:83], v[178:181], v[208:211], v[80:83]
	v_mfma_f32_16x16x32_bf16 v[68:71], v[170:173], v[216:219], v[68:71]
	v_mfma_f32_16x16x32_bf16 v[64:67], v[178:181], v[216:219], v[64:67]
	s_barrier
; #define PG8_STAGE(bufoff, gbase, voff) do { _Pragma("unroll") for (int _i = 0; _i < 2; ++_i) \
;         __builtin_amdgcn_global_load_lds((const unsigned*)((const char*)(gbase) + (voff)[_i]), (PG8_LAS unsigned*)(lds + (bufoff) + ldsw + _i * 8192), 16, 0, 0); } while (0)
; #define PG8_LDA(dst, b, h) do { _Pragma("unroll") for (int m = 0; m < 4; ++m) _Pragma("unroll") for (int k = 0; k < 2; ++k) dst[m][k] = *(const PG8_LAS bf16x8*)(lds + PG8_SA(b, h) + aoff + m * 2048 + k * 1024); } while (0)
; #define PG8_LDB(dst, b, h) do { _Pragma("unroll") for (int n = 0; n < 2; ++n) _Pragma("unroll") for (int k = 0; k < 2; ++k) dst[n][k] = *(const PG8_LAS bf16x8*)(lds + PG8_SB(b, h) + boff + n * 2048 + k * 1024); } while (0)
; #define PG8_MMA(ai, bj, At, Bt) do { __builtin_amdgcn_s_setprio(1); _Pragma("unroll") for (int m = 0; m < 4; ++m) _Pragma("unroll") for (int n = 0; n < 2; ++n) _Pragma("unroll") for (int k = 0; k < 2; ++k) \
;         acc[ai][bj][m][n] = __builtin_amdgcn_mfma_f32_16x16x32_bf16(Bt[n][k], At[m][k], acc[ai][bj][m][n], 0, 0, 0); __builtin_amdgcn_s_setprio(0); } while (0)
; #define PG8_WAIT_V(n) asm volatile("s_waitcnt vmcnt(" #n ")" ::: "memory")
; #define PG8_WAIT_L(n) asm volatile("s_waitcnt lgkmcnt(" #n ")" ::: "memory")
; #define PG8_BAR __builtin_amdgcn_s_barrier()
; #define PG8_SCHED __builtin_amdgcn_sched_barrier(0)
; template <class Epi, class Sched, bool ALIGN_EPI = false, bool SP2 = false>
; __device__ __forceinline__ void gemm_phase(PG8_LAS unsigned char* lds, const Gemm g, const Sched& S, const Epi& E) {
;     ...
;             PG8_LDB(B0, 0, 0); PG8_LDB(B1, 0, 1); PG8_SCHED; PG8_LDA(At, 0, 0); PG8_STAGE(PG8_SA(1, 1), a1 + hstep, voffA);
;             PG8_WAIT_V(8); PG8_WAIT_L(0); PG8_BAR; PG8_MMA(0, 0, At, B0); PG8_MMA(0, 1, At, B1); PG8_BAR; PG8_SCHED;
;     ...
;             PG8_LDA(At, 1, 1); PG8_STAGE(PG8_SB(1, 0), b3, voffB); PG8_STAGE(PG8_SB(1, 1), b3 + hstep, voffB); PG8_STAGE(PG8_SA(1, 0), a3, voffA);
;             PG8_WAIT_V(8); PG8_WAIT_L(0); PG8_BAR; PG8_MMA(1, 0, At, B0); PG8_MMA(1, 1, At, B1); PG8_BAR; PG8_SCHED;
	s_setprio 0
	s_add_i32 s30, s55, s35
	v_lshl_add_u64 v[186:187], v[186:187], 0, s[4:5]
	s_mov_b32 m0, s30
	ds_read_b128 v[182:185], v149 offset:49152
	ds_read_b128 v[192:195], v149 offset:50176
	ds_read_b128 v[196:199], v149 offset:51200
	ds_read_b128 v[200:203], v149 offset:52224
	ds_read_b128 v[204:207], v149 offset:53248
	ds_read_b128 v[208:211], v149 offset:54272
	ds_read_b128 v[212:215], v149 offset:55296
	ds_read_b128 v[216:219], v149 offset:56320
	global_load_lds_dwordx4 v[186:187], off
	s_add_i32 m0, s30, 0x2000
	s_add_u32 s24, s24, 0x40080
	v_lshl_add_u64 v[186:187], v[220:221], 0, s[4:5]
	s_addc_u32 s25, s25, 0
	s_add_i32 s30, s56, s35
	global_load_lds_dwordx4 v[186:187], off
	s_mov_b32 m0, s30
	s_nop 0
	global_load_lds_dwordx4 v132, s[24:25]
	s_add_i32 m0, s30, 0x2000
	s_nop 0
	global_load_lds_dwordx4 v128, s[24:25]
	v_lshl_add_u64 v[186:187], v[222:223], 0, s[4:5]
	s_mov_b32 m0, s42
	s_nop 0
	global_load_lds_dwordx4 v[186:187], off
	v_lshl_add_u64 v[186:187], v[224:225], 0, s[4:5]
	s_mov_b32 m0, s43
	s_nop 0
	global_load_lds_dwordx4 v[186:187], off
	s_waitcnt vmcnt(8)
	s_waitcnt lgkmcnt(0)
	s_setprio 1
	s_barrier
	v_mfma_f32_16x16x32_bf16 v[60:63], v[150:153], v[182:185], v[60:63]
	v_mfma_f32_16x16x32_bf16 v[56:59], v[158:161], v[182:185], v[56:59]
	v_mfma_f32_16x16x32_bf16 v[44:47], v[150:153], v[196:199], v[44:47]
	v_mfma_f32_16x16x32_bf16 v[40:43], v[158:161], v[196:199], v[40:43]
	v_mfma_f32_16x16x32_bf16 v[28:31], v[150:153], v[204:207], v[28:31]
	v_mfma_f32_16x16x32_bf16 v[24:27], v[158:161], v[204:207], v[24:27]
	v_mfma_f32_16x16x32_bf16 v[12:15], v[150:153], v[212:215], v[12:15]
	v_mfma_f32_16x16x32_bf16 v[8:11], v[158:161], v[212:215], v[8:11]
	v_mfma_f32_16x16x32_bf16 v[60:63], v[154:157], v[192:195], v[60:63]
	v_mfma_f32_16x16x32_bf16 v[56:59], v[162:165], v[192:195], v[56:59]
	v_mfma_f32_16x16x32_bf16 v[44:47], v[154:157], v[200:203], v[44:47]
	v_mfma_f32_16x16x32_bf16 v[40:43], v[162:165], v[200:203], v[40:43]
	v_mfma_f32_16x16x32_bf16 v[28:31], v[154:157], v[208:211], v[28:31]
	v_mfma_f32_16x16x32_bf16 v[24:27], v[162:165], v[208:211], v[24:27]
	v_mfma_f32_16x16x32_bf16 v[12:15], v[154:157], v[216:219], v[12:15]
	v_mfma_f32_16x16x32_bf16 v[8:11], v[162:165], v[216:219], v[8:11]
	v_mfma_f32_16x16x32_bf16 v[52:55], v[166:169], v[182:185], v[52:55]
	v_mfma_f32_16x16x32_bf16 v[48:51], v[174:177], v[182:185], v[48:51]
	v_mfma_f32_16x16x32_bf16 v[36:39], v[166:169], v[196:199], v[36:39]
	v_mfma_f32_16x16x32_bf16 v[32:35], v[174:177], v[196:199], v[32:35]
	v_mfma_f32_16x16x32_bf16 v[20:23], v[166:169], v[204:207], v[20:23]
	v_mfma_f32_16x16x32_bf16 v[16:19], v[174:177], v[204:207], v[16:19]
	v_mfma_f32_16x16x32_bf16 v[4:7], v[166:169], v[212:215], v[4:7]
	v_mfma_f32_16x16x32_bf16 v[0:3], v[174:177], v[212:215], v[0:3]
	v_mfma_f32_16x16x32_bf16 v[52:55], v[170:173], v[192:195], v[52:55]
	v_mfma_f32_16x16x32_bf16 v[48:51], v[178:181], v[192:195], v[48:51]
	v_mfma_f32_16x16x32_bf16 v[36:39], v[170:173], v[200:203], v[36:39]
	v_mfma_f32_16x16x32_bf16 v[32:35], v[178:181], v[200:203], v[32:35]
	v_mfma_f32_16x16x32_bf16 v[20:23], v[170:173], v[208:211], v[20:23]
	v_mfma_f32_16x16x32_bf16 v[16:19], v[178:181], v[208:211], v[16:19]
	v_mfma_f32_16x16x32_bf16 v[4:7], v[170:173], v[216:219], v[4:7]
	v_mfma_f32_16x16x32_bf16 v[0:3], v[178:181], v[216:219], v[0:3]
	s_barrier
	s_setprio 0
	s_add_i32 s54, s54, 2
	s_add_u32 s22, s22, 0x100
	s_addc_u32 s23, s23, 0
	s_add_u32 s52, s52, 0x100
	s_addc_u32 s53, s53, 0
	s_branch .LBB0_192
.Lp1_plain:
	ds_read_b128 v[150:153], v147
	ds_read_b128 v[154:157], v147 offset:1024
	ds_read_b128 v[158:161], v147 offset:2048
	ds_read_b128 v[162:165], v147 offset:3072
	ds_read_b128 v[166:169], v148
	ds_read_b128 v[170:173], v148 offset:1024
	ds_read_b128 v[174:177], v148 offset:2048
	ds_read_b128 v[178:181], v148 offset:3072
	s_add_u32 s24, s22, 0xfffc0080
	s_addc_u32 s25, s23, -1
	s_cmp_eq_u32 s54, 12
	s_cselect_b32 s31, s15, s25
	s_cselect_b32 s30, s50, s24
	s_cselect_b32 s25, s9, s53
	s_cselect_b32 s24, s51, s52
	s_add_i32 m0, s21, 0xc000
	ds_read_b128 v[182:185], v149
	ds_read_b128 v[192:195], v149 offset:1024
	ds_read_b128 v[196:199], v149 offset:2048
	ds_read_b128 v[200:203], v149 offset:3072
	ds_read_b128 v[204:207], v149 offset:4096
	ds_read_b128 v[208:211], v149 offset:5120
	ds_read_b128 v[212:215], v149 offset:6144
	ds_read_b128 v[216:219], v149 offset:7168
	global_load_lds_dwordx4 v136, s[22:23]
	s_add_i32 m0, s21, 0xe000
	s_nop 0
	global_load_lds_dwordx4 v138, s[22:23]
	s_waitcnt vmcnt(16)
	s_waitcnt lgkmcnt(0)
	s_setprio 1
	s_barrier
; #define PG8_STAGE(bufoff, gbase, voff) do { _Pragma("unroll") for (int _i = 0; _i < 2; ++_i) \
;         __builtin_amdgcn_global_load_lds((const unsigned*)((const char*)(gbase) + (voff)[_i]), (PG8_LAS unsigned*)(lds + (bufoff) + ldsw + _i * 8192), 16, 0, 0); } while (0)
; #define PG8_LDA(dst, b, h) do { _Pragma("unroll") for (int m = 0; m < 4; ++m) _Pragma("unroll") for (int k = 0; k < 2; ++k) dst[m][k] = *(const PG8_LAS bf16x8*)(lds + PG8_SA(b, h) + aoff + m * 2048 + k * 1024); } while (0)
; #define PG8_LDB(dst, b, h) do { _Pragma("unroll") for (int n = 0; n < 2; ++n) _Pragma("unroll") for (int k = 0; k < 2; ++k) dst[n][k] = *(const PG8_LAS bf16x8*)(lds + PG8_SB(b, h) + boff + n * 2048 + k * 1024); } while (0)
; #define PG8_MMA(ai, bj, At, Bt) do { __builtin_amdgcn_s_setprio(1); _Pragma("unroll") for (int m = 0; m < 4; ++m) _Pragma("unroll") for (int n = 0; n < 2; ++n) _Pragma("unroll") for (int k = 0; k < 2; ++k) \
;         acc[ai][bj][m][n] = __builtin_amdgcn_mfma_f32_16x16x32_bf16(Bt[n][k], At[m][k], acc[ai][bj][m][n], 0, 0, 0); __builtin_amdgcn_s_setprio(0); } while (0)
; #define PG8_WAIT_V(n) asm volatile("s_waitcnt vmcnt(" #n ")" ::: "memory")
; #define PG8_WAIT_L(n) asm volatile("s_waitcnt lgkmcnt(" #n ")" ::: "memory")
; #define PG8_BAR __builtin_amdgcn_s_barrier()
; #define PG8_SCHED __builtin_amdgcn_sched_barrier(0)
; template <class Epi, class Sched, bool ALIGN_EPI = false, bool SP2 = false>
; __device__ __forceinline__ void gemm_phase(PG8_LAS unsigned char* lds, const Gemm g, const Sched& S, const Epi& E) {
;     ...
;             PG8_LDB(B0, 0, 0); PG8_LDB(B1, 0, 1); PG8_SCHED; PG8_LDA(At, 0, 0); PG8_STAGE(PG8_SA(1, 1), a1 + hstep, voffA);
;             PG8_WAIT_V(8); PG8_WAIT_L(0); PG8_BAR; PG8_MMA(0, 0, At, B0); PG8_MMA(0, 1, At, B1); PG8_BAR; PG8_SCHED;
;             PG8_LDA(At, 0, 1); PG8_STAGE(PG8_SB(0, 0), b2, voffB); PG8_STAGE(PG8_SB(0, 1), b2 + hstep, voffB); PG8_STAGE(PG8_SA(0, 0), a2, voffA);
;             PG8_WAIT_V(8); PG8_WAIT_L(0); PG8_BAR; PG8_MMA(1, 0, At, B0); PG8_MMA(1, 1, At, B1); PG8_BAR; PG8_SCHED;
	v_mfma_f32_16x16x32_bf16 v[124:127], v[150:153], v[182:185], 0
	v_mfma_f32_16x16x32_bf16 v[120:123], v[158:161], v[182:185], 0
	v_mfma_f32_16x16x32_bf16 v[108:111], v[150:153], v[196:199], 0
	v_mfma_f32_16x16x32_bf16 v[104:107], v[158:161], v[196:199], 0
	v_mfma_f32_16x16x32_bf16 v[92:95], v[150:153], v[204:207], 0
	v_mfma_f32_16x16x32_bf16 v[88:91], v[158:161], v[204:207], 0
	v_mfma_f32_16x16x32_bf16 v[76:79], v[150:153], v[212:215], 0
	v_mfma_f32_16x16x32_bf16 v[72:75], v[158:161], v[212:215], 0
	v_mfma_f32_16x16x32_bf16 v[124:127], v[154:157], v[192:195], v[124:127]
	v_mfma_f32_16x16x32_bf16 v[120:123], v[162:165], v[192:195], v[120:123]
	v_mfma_f32_16x16x32_bf16 v[108:111], v[154:157], v[200:203], v[108:111]
	v_mfma_f32_16x16x32_bf16 v[104:107], v[162:165], v[200:203], v[104:107]
	v_mfma_f32_16x16x32_bf16 v[92:95], v[154:157], v[208:211], v[92:95]
	v_mfma_f32_16x16x32_bf16 v[88:91], v[162:165], v[208:211], v[88:91]
	v_mfma_f32_16x16x32_bf16 v[76:79], v[154:157], v[216:219], v[76:79]
	v_mfma_f32_16x16x32_bf16 v[72:75], v[162:165], v[216:219], v[72:75]
	v_mfma_f32_16x16x32_bf16 v[116:119], v[166:169], v[182:185], 0
	v_mfma_f32_16x16x32_bf16 v[112:115], v[174:177], v[182:185], 0
	v_mfma_f32_16x16x32_bf16 v[100:103], v[166:169], v[196:199], 0
	v_mfma_f32_16x16x32_bf16 v[96:99], v[174:177], v[196:199], 0
	v_mfma_f32_16x16x32_bf16 v[84:87], v[166:169], v[204:207], 0
	v_mfma_f32_16x16x32_bf16 v[80:83], v[174:177], v[204:207], 0
	v_mfma_f32_16x16x32_bf16 v[68:71], v[166:169], v[212:215], 0
	v_mfma_f32_16x16x32_bf16 v[64:67], v[174:177], v[212:215], 0
	v_mfma_f32_16x16x32_bf16 v[116:119], v[170:173], v[192:195], v[116:119]
	v_mfma_f32_16x16x32_bf16 v[112:115], v[178:181], v[192:195], v[112:115]
	v_mfma_f32_16x16x32_bf16 v[100:103], v[170:173], v[200:203], v[100:103]
	v_mfma_f32_16x16x32_bf16 v[96:99], v[178:181], v[200:203], v[96:99]
	v_mfma_f32_16x16x32_bf16 v[84:87], v[170:173], v[208:211], v[84:87]
	v_mfma_f32_16x16x32_bf16 v[80:83], v[178:181], v[208:211], v[80:83]
	v_mfma_f32_16x16x32_bf16 v[68:71], v[170:173], v[216:219], v[68:71]
	v_mfma_f32_16x16x32_bf16 v[64:67], v[178:181], v[216:219], v[64:67]
	s_barrier
	s_setprio 0
	s_add_i32 s55, s46, s35
	v_lshl_add_u64 v[186:187], s[24:25], 0, v[132:133]
	s_mov_b32 m0, s55
	ds_read_b128 v[182:185], v149 offset:16384
	ds_read_b128 v[192:195], v149 offset:17408
	ds_read_b128 v[196:199], v149 offset:18432
	ds_read_b128 v[200:203], v149 offset:19456
	ds_read_b128 v[204:207], v149 offset:20480
	ds_read_b128 v[208:211], v149 offset:21504
	ds_read_b128 v[212:215], v149 offset:22528
	ds_read_b128 v[216:219], v149 offset:23552
	global_load_lds_dwordx4 v[186:187], off
	s_add_i32 m0, s55, 0x2000
	s_add_u32 s56, s24, 0x40000
	v_lshl_add_u64 v[220:221], s[24:25], 0, v[128:129]
	s_addc_u32 s57, s25, 0
	s_add_i32 s55, s47, s35
	global_load_lds_dwordx4 v[220:221], off
	s_mov_b32 m0, s55
	v_lshl_add_u64 v[224:225], s[30:31], 0, v[130:131]
	global_load_lds_dwordx4 v132, s[56:57]
	s_add_i32 m0, s55, 0x2000
	s_nop 0
	global_load_lds_dwordx4 v128, s[56:57]
	v_lshl_add_u64 v[222:223], s[30:31], 0, v[134:135]
	s_mov_b32 m0, s21
	s_nop 0
	global_load_lds_dwordx4 v[222:223], off
	s_mov_b32 m0, s38
	s_nop 0
	global_load_lds_dwordx4 v[224:225], off
	s_waitcnt vmcnt(16)
	s_waitcnt lgkmcnt(0)
	s_setprio 1
	s_barrier
	v_mfma_f32_16x16x32_bf16 v[60:63], v[150:153], v[182:185], 0
	v_mfma_f32_16x16x32_bf16 v[56:59], v[158:161], v[182:185], 0
	v_mfma_f32_16x16x32_bf16 v[44:47], v[150:153], v[196:199], 0
	v_mfma_f32_16x16x32_bf16 v[40:43], v[158:161], v[196:199], 0
	v_mfma_f32_16x16x32_bf16 v[28:31], v[150:153], v[204:207], 0
	v_mfma_f32_16x16x32_bf16 v[24:27], v[158:161], v[204:207], 0
	v_mfma_f32_16x16x32_bf16 v[12:15], v[150:153], v[212:215], 0
	v_mfma_f32_16x16x32_bf16 v[8:11], v[158:161], v[212:215], 0
	v_mfma_f32_16x16x32_bf16 v[60:63], v[154:157], v[192:195], v[60:63]
	v_mfma_f32_16x16x32_bf16 v[56:59], v[162:165], v[192:195], v[56:59]
	v_mfma_f32_16x16x32_bf16 v[44:47], v[154:157], v[200:203], v[44:47]
	v_mfma_f32_16x16x32_bf16 v[40:43], v[162:165], v[200:203], v[40:43]
	v_mfma_f32_16x16x32_bf16 v[28:31], v[154:157], v[208:211], v[28:31]
	v_mfma_f32_16x16x32_bf16 v[24:27], v[162:165], v[208:211], v[24:27]
	v_mfma_f32_16x16x32_bf16 v[12:15], v[154:157], v[216:219], v[12:15]
	v_mfma_f32_16x16x32_bf16 v[8:11], v[162:165], v[216:219], v[8:11]
	v_mfma_f32_16x16x32_bf16 v[52:55], v[166:169], v[182:185], 0
	v_mfma_f32_16x16x32_bf16 v[48:51], v[174:177], v[182:185], 0
	v_mfma_f32_16x16x32_bf16 v[36:39], v[166:169], v[196:199], 0
	v_mfma_f32_16x16x32_bf16 v[32:35], v[174:177], v[196:199], 0
	v_mfma_f32_16x16x32_bf16 v[20:23], v[166:169], v[204:207], 0
	v_mfma_f32_16x16x32_bf16 v[16:19], v[174:177], v[204:207], 0
	v_mfma_f32_16x16x32_bf16 v[4:7], v[166:169], v[212:215], 0
	v_mfma_f32_16x16x32_bf16 v[0:3], v[174:177], v[212:215], 0
	v_mfma_f32_16x16x32_bf16 v[52:55], v[170:173], v[192:195], v[52:55]
	v_mfma_f32_16x16x32_bf16 v[48:51], v[178:181], v[192:195], v[48:51]
	v_mfma_f32_16x16x32_bf16 v[36:39], v[170:173], v[200:203], v[36:39]
	v_mfma_f32_16x16x32_bf16 v[32:35], v[178:181], v[200:203], v[32:35]
	v_mfma_f32_16x16x32_bf16 v[20:23], v[170:173], v[208:211], v[20:23]
	v_mfma_f32_16x16x32_bf16 v[16:19], v[178:181], v[208:211], v[16:19]
	v_mfma_f32_16x16x32_bf16 v[4:7], v[170:173], v[216:219], v[4:7]
	v_mfma_f32_16x16x32_bf16 v[0:3], v[178:181], v[216:219], v[0:3]
	s_barrier
; #define PG8_STAGE(bufoff, gbase, voff) do { _Pragma("unroll") for (int _i = 0; _i < 2; ++_i) \
;         __builtin_amdgcn_global_load_lds((const unsigned*)((const char*)(gbase) + (voff)[_i]), (PG8_LAS unsigned*)(lds + (bufoff) + ldsw + _i * 8192), 16, 0, 0); } while (0)
; #define PG8_LDA(dst, b, h) do { _Pragma("unroll") for (int m = 0; m < 4; ++m) _Pragma("unroll") for (int k = 0; k < 2; ++k) dst[m][k] = *(const PG8_LAS bf16x8*)(lds + PG8_SA(b, h) + aoff + m * 2048 + k * 1024); } while (0)
; #define PG8_LDB(dst, b, h) do { _Pragma("unroll") for (int n = 0; n < 2; ++n) _Pragma("unroll") for (int k = 0; k < 2; ++k) dst[n][k] = *(const PG8_LAS bf16x8*)(lds + PG8_SB(b, h) + boff + n * 2048 + k * 1024); } while (0)
; #define PG8_MMA(ai, bj, At, Bt) do { __builtin_amdgcn_s_setprio(1); _Pragma("unroll") for (int m = 0; m < 4; ++m) _Pragma("unroll") for (int n = 0; n < 2; ++n) _Pragma("unroll") for (int k = 0; k < 2; ++k) \
;         acc[ai][bj][m][n] = __builtin_amdgcn_mfma_f32_16x16x32_bf16(Bt[n][k], At[m][k], acc[ai][bj][m][n], 0, 0, 0); __builtin_amdgcn_s_setprio(0); } while (0)
; #define PG8_WAIT_V(n) asm volatile("s_waitcnt vmcnt(" #n ")" ::: "memory")
; #define PG8_WAIT_L(n) asm volatile("s_waitcnt lgkmcnt(" #n ")" ::: "memory")
; #define PG8_BAR __builtin_amdgcn_s_barrier()
; #define PG8_SCHED __builtin_amdgcn_sched_barrier(0)
; template <class Epi, class Sched, bool ALIGN_EPI = false, bool SP2 = false>
; __device__ __forceinline__ void gemm_phase(PG8_LAS unsigned char* lds, const Gemm g, const Sched& S, const Epi& E) {
;     ...
;             PG8_LDB(B0, 1, 0); PG8_LDB(B1, 1, 1); PG8_SCHED; PG8_LDA(At, 1, 0); PG8_STAGE(PG8_SA(0, 1), a2 + hstep, voffA);
;             PG8_WAIT_V(8); PG8_WAIT_L(0); PG8_BAR; PG8_MMA(0, 0, At, B0); PG8_MMA(0, 1, At, B1); PG8_BAR; PG8_SCHED;
;             PG8_LDA(At, 1, 1); PG8_STAGE(PG8_SB(1, 0), b3, voffB); PG8_STAGE(PG8_SB(1, 1), b3 + hstep, voffB); PG8_STAGE(PG8_SA(1, 0), a3, voffA);
;             PG8_WAIT_V(8); PG8_WAIT_L(0); PG8_BAR; PG8_MMA(1, 0, At, B0); PG8_MMA(1, 1, At, B1); PG8_BAR; PG8_SCHED;
	s_setprio 0
	s_add_i32 s55, 0, 0x18000
	s_add_i32 s56, 0, 0x1c000
	v_add_u32_e32 v162, s55, v145
	v_add_u32_e32 v178, s56, v145
	ds_read_b128 v[150:153], v162
	ds_read_b128 v[154:157], v162 offset:1024
	ds_read_b128 v[158:161], v162 offset:2048
	ds_read_b128 v[162:165], v162 offset:3072
	ds_read_b128 v[166:169], v178
	ds_read_b128 v[170:173], v178 offset:1024
	ds_read_b128 v[174:177], v178 offset:2048
	ds_read_b128 v[178:181], v178 offset:3072
	s_add_u32 s30, s30, 0x40000
	s_addc_u32 s31, s31, 0
	s_mov_b32 m0, s39
	ds_read_b128 v[182:185], v149 offset:32768
	ds_read_b128 v[192:195], v149 offset:33792
	ds_read_b128 v[196:199], v149 offset:34816
	ds_read_b128 v[200:203], v149 offset:35840
	ds_read_b128 v[204:207], v149 offset:36864
	ds_read_b128 v[208:211], v149 offset:37888
	ds_read_b128 v[212:215], v149 offset:38912
	ds_read_b128 v[216:219], v149 offset:39936
	global_load_lds_dwordx4 v134, s[30:31]
	v_lshl_add_u64 v[226:227], s[30:31], 0, v[130:131]
	s_mov_b32 m0, s40
	s_nop 0
	global_load_lds_dwordx4 v[226:227], off
	s_waitcnt vmcnt(8)
	s_waitcnt lgkmcnt(0)
	s_setprio 1
	s_barrier
	v_mfma_f32_16x16x32_bf16 v[124:127], v[150:153], v[182:185], v[124:127]
	v_mfma_f32_16x16x32_bf16 v[120:123], v[158:161], v[182:185], v[120:123]
	v_mfma_f32_16x16x32_bf16 v[108:111], v[150:153], v[196:199], v[108:111]
	v_mfma_f32_16x16x32_bf16 v[104:107], v[158:161], v[196:199], v[104:107]
	v_mfma_f32_16x16x32_bf16 v[92:95], v[150:153], v[204:207], v[92:95]
	v_mfma_f32_16x16x32_bf16 v[88:91], v[158:161], v[204:207], v[88:91]
	v_mfma_f32_16x16x32_bf16 v[76:79], v[150:153], v[212:215], v[76:79]
	v_mfma_f32_16x16x32_bf16 v[72:75], v[158:161], v[212:215], v[72:75]
	v_mfma_f32_16x16x32_bf16 v[124:127], v[154:157], v[192:195], v[124:127]
	v_mfma_f32_16x16x32_bf16 v[120:123], v[162:165], v[192:195], v[120:123]
	v_mfma_f32_16x16x32_bf16 v[108:111], v[154:157], v[200:203], v[108:111]
	v_mfma_f32_16x16x32_bf16 v[104:107], v[162:165], v[200:203], v[104:107]
	v_mfma_f32_16x16x32_bf16 v[92:95], v[154:157], v[208:211], v[92:95]
	v_mfma_f32_16x16x32_bf16 v[88:91], v[162:165], v[208:211], v[88:91]
	v_mfma_f32_16x16x32_bf16 v[76:79], v[154:157], v[216:219], v[76:79]
	v_mfma_f32_16x16x32_bf16 v[72:75], v[162:165], v[216:219], v[72:75]
	v_mfma_f32_16x16x32_bf16 v[116:119], v[166:169], v[182:185], v[116:119]
	v_mfma_f32_16x16x32_bf16 v[112:115], v[174:177], v[182:185], v[112:115]
	v_mfma_f32_16x16x32_bf16 v[100:103], v[166:169], v[196:199], v[100:103]
	v_mfma_f32_16x16x32_bf16 v[96:99], v[174:177], v[196:199], v[96:99]
	v_mfma_f32_16x16x32_bf16 v[84:87], v[166:169], v[204:207], v[84:87]
	v_mfma_f32_16x16x32_bf16 v[80:83], v[174:177], v[204:207], v[80:83]
	v_mfma_f32_16x16x32_bf16 v[68:71], v[166:169], v[212:215], v[68:71]
	v_mfma_f32_16x16x32_bf16 v[64:67], v[174:177], v[212:215], v[64:67]
	v_mfma_f32_16x16x32_bf16 v[116:119], v[170:173], v[192:195], v[116:119]
	v_mfma_f32_16x16x32_bf16 v[112:115], v[178:181], v[192:195], v[112:115]
	v_mfma_f32_16x16x32_bf16 v[100:103], v[170:173], v[200:203], v[100:103]
	v_mfma_f32_16x16x32_bf16 v[96:99], v[178:181], v[200:203], v[96:99]
	v_mfma_f32_16x16x32_bf16 v[84:87], v[170:173], v[208:211], v[84:87]
	v_mfma_f32_16x16x32_bf16 v[80:83], v[178:181], v[208:211], v[80:83]
	v_mfma_f32_16x16x32_bf16 v[68:71], v[170:173], v[216:219], v[68:71]
	v_mfma_f32_16x16x32_bf16 v[64:67], v[178:181], v[216:219], v[64:67]
	s_barrier
	s_setprio 0
	s_add_i32 s30, s55, s35
	v_lshl_add_u64 v[186:187], v[186:187], 0, s[4:5]
	s_mov_b32 m0, s30
	ds_read_b128 v[182:185], v149 offset:49152
	ds_read_b128 v[192:195], v149 offset:50176
	ds_read_b128 v[196:199], v149 offset:51200
	ds_read_b128 v[200:203], v149 offset:52224
	ds_read_b128 v[204:207], v149 offset:53248
	ds_read_b128 v[208:211], v149 offset:54272
	ds_read_b128 v[212:215], v149 offset:55296
	ds_read_b128 v[216:219], v149 offset:56320
	global_load_lds_dwordx4 v[186:187], off
	s_add_i32 m0, s30, 0x2000
	s_add_u32 s24, s24, 0x40080
	v_lshl_add_u64 v[186:187], v[220:221], 0, s[4:5]
	s_addc_u32 s25, s25, 0
	s_add_i32 s30, s56, s35
	global_load_lds_dwordx4 v[186:187], off
	s_mov_b32 m0, s30
	s_nop 0
	global_load_lds_dwordx4 v132, s[24:25]
	s_add_i32 m0, s30, 0x2000
	s_nop 0
	global_load_lds_dwordx4 v128, s[24:25]
	v_lshl_add_u64 v[186:187], v[222:223], 0, s[4:5]
	s_mov_b32 m0, s42
	s_nop 0
	global_load_lds_dwordx4 v[186:187], off
	v_lshl_add_u64 v[186:187], v[224:225], 0, s[4:5]
	s_mov_b32 m0, s43
	s_nop 0
	global_load_lds_dwordx4 v[186:187], off
	s_waitcnt vmcnt(8)
	s_waitcnt lgkmcnt(0)
	s_setprio 1
	s_barrier
	v_mfma_f32_16x16x32_bf16 v[60:63], v[150:153], v[182:185], v[60:63]
	v_mfma_f32_16x16x32_bf16 v[56:59], v[158:161], v[182:185], v[56:59]
	v_mfma_f32_16x16x32_bf16 v[44:47], v[150:153], v[196:199], v[44:47]
	v_mfma_f32_16x16x32_bf16 v[40:43], v[158:161], v[196:199], v[40:43]
	v_mfma_f32_16x16x32_bf16 v[28:31], v[150:153], v[204:207], v[28:31]
	v_mfma_f32_16x16x32_bf16 v[24:27], v[158:161], v[204:207], v[24:27]
	v_mfma_f32_16x16x32_bf16 v[12:15], v[150:153], v[212:215], v[12:15]
	v_mfma_f32_16x16x32_bf16 v[8:11], v[158:161], v[212:215], v[8:11]
	v_mfma_f32_16x16x32_bf16 v[60:63], v[154:157], v[192:195], v[60:63]
	v_mfma_f32_16x16x32_bf16 v[56:59], v[162:165], v[192:195], v[56:59]
	v_mfma_f32_16x16x32_bf16 v[44:47], v[154:157], v[200:203], v[44:47]
	v_mfma_f32_16x16x32_bf16 v[40:43], v[162:165], v[200:203], v[40:43]
	v_mfma_f32_16x16x32_bf16 v[28:31], v[154:157], v[208:211], v[28:31]
	v_mfma_f32_16x16x32_bf16 v[24:27], v[162:165], v[208:211], v[24:27]
	v_mfma_f32_16x16x32_bf16 v[12:15], v[154:157], v[216:219], v[12:15]
	v_mfma_f32_16x16x32_bf16 v[8:11], v[162:165], v[216:219], v[8:11]
	v_mfma_f32_16x16x32_bf16 v[52:55], v[166:169], v[182:185], v[52:55]
	v_mfma_f32_16x16x32_bf16 v[48:51], v[174:177], v[182:185], v[48:51]
	v_mfma_f32_16x16x32_bf16 v[36:39], v[166:169], v[196:199], v[36:39]
	v_mfma_f32_16x16x32_bf16 v[32:35], v[174:177], v[196:199], v[32:35]
	v_mfma_f32_16x16x32_bf16 v[20:23], v[166:169], v[204:207], v[20:23]
	v_mfma_f32_16x16x32_bf16 v[16:19], v[174:177], v[204:207], v[16:19]
	v_mfma_f32_16x16x32_bf16 v[4:7], v[166:169], v[212:215], v[4:7]
	v_mfma_f32_16x16x32_bf16 v[0:3], v[174:177], v[212:215], v[0:3]
	v_mfma_f32_16x16x32_bf16 v[52:55], v[170:173], v[192:195], v[52:55]
	v_mfma_f32_16x16x32_bf16 v[48:51], v[178:181], v[192:195], v[48:51]
	v_mfma_f32_16x16x32_bf16 v[36:39], v[170:173], v[200:203], v[36:39]
	v_mfma_f32_16x16x32_bf16 v[32:35], v[178:181], v[200:203], v[32:35]
	v_mfma_f32_16x16x32_bf16 v[20:23], v[170:173], v[208:211], v[20:23]
	v_mfma_f32_16x16x32_bf16 v[16:19], v[178:181], v[208:211], v[16:19]
	v_mfma_f32_16x16x32_bf16 v[4:7], v[170:173], v[216:219], v[4:7]
	v_mfma_f32_16x16x32_bf16 v[0:3], v[178:181], v[216:219], v[0:3]
	s_barrier
	s_setprio 0
	s_add_i32 s54, s54, 2
	s_add_u32 s22, s22, 0x100
	s_addc_u32 s23, s23, 0
	s_add_u32 s52, s52, 0x100
	s_addc_u32 s53, s53, 0
; #define PG8_STAGE(bufoff, gbase, voff) do { _Pragma("unroll") for (int _i = 0; _i < 2; ++_i) \
;         __builtin_amdgcn_global_load_lds((const unsigned*)((const char*)(gbase) + (voff)[_i]), (PG8_LAS unsigned*)(lds + (bufoff) + ldsw + _i * 8192), 16, 0, 0); } while (0)
; #define PG8_LDA(dst, b, h) do { _Pragma("unroll") for (int m = 0; m < 4; ++m) _Pragma("unroll") for (int k = 0; k < 2; ++k) dst[m][k] = *(const PG8_LAS bf16x8*)(lds + PG8_SA(b, h) + aoff + m * 2048 + k * 1024); } while (0)
; #define PG8_LDB(dst, b, h) do { _Pragma("unroll") for (int n = 0; n < 2; ++n) _Pragma("unroll") for (int k = 0; k < 2; ++k) dst[n][k] = *(const PG8_LAS bf16x8*)(lds + PG8_SB(b, h) + boff + n * 2048 + k * 1024); } while (0)
; #define PG8_MMA(ai, bj, At, Bt) do { __builtin_amdgcn_s_setprio(1); _Pragma("unroll") for (int m = 0; m < 4; ++m) _Pragma("unroll") for (int n = 0; n < 2; ++n) _Pragma("unroll") for (int k = 0; k < 2; ++k) \
;         acc[ai][bj][m][n] = __builtin_amdgcn_mfma_f32_16x16x32_bf16(Bt[n][k], At[m][k], acc[ai][bj][m][n], 0, 0, 0); __builtin_amdgcn_s_setprio(0); } while (0)
; #define PG8_WAIT_V(n) asm volatile("s_waitcnt vmcnt(" #n ")" ::: "memory")
; #define PG8_WAIT_L(n) asm volatile("s_waitcnt lgkmcnt(" #n ")" ::: "memory")
; #define PG8_BAR __builtin_amdgcn_s_barrier()
; #define PG8_SCHED __builtin_amdgcn_sched_barrier(0)
; template <class Epi, class Sched, bool ALIGN_EPI = false, bool SP2 = false>
; __device__ __forceinline__ void gemm_phase(PG8_LAS unsigned char* lds, const Gemm g, const Sched& S, const Epi& E) {
;     ...
;             PG8_LDB(B0, 0, 0); PG8_LDB(B1, 0, 1); PG8_SCHED; PG8_LDA(At, 0, 0); PG8_STAGE(PG8_SA(1, 1), a1 + hstep, voffA);
;             PG8_WAIT_V(8); PG8_WAIT_L(0); PG8_BAR; PG8_MMA(0, 0, At, B0); PG8_MMA(0, 1, At, B1); PG8_BAR; PG8_SCHED;
;             PG8_LDA(At, 0, 1); PG8_STAGE(PG8_SB(0, 0), b2, voffB); PG8_STAGE(PG8_SB(0, 1), b2 + hstep, voffB); PG8_STAGE(PG8_SA(0, 0), a2, voffA);
;             PG8_WAIT_V(8); PG8_WAIT_L(0); PG8_BAR; PG8_MMA(1, 0, At, B0); PG8_MMA(1, 1, At, B1); PG8_BAR; PG8_SCHED;
.LBB0_192:
	ds_read_b128 v[150:153], v147
	ds_read_b128 v[154:157], v147 offset:1024
	ds_read_b128 v[158:161], v147 offset:2048
	ds_read_b128 v[162:165], v147 offset:3072
	ds_read_b128 v[166:169], v148
	ds_read_b128 v[170:173], v148 offset:1024
	ds_read_b128 v[174:177], v148 offset:2048
	ds_read_b128 v[178:181], v148 offset:3072
	s_add_u32 s24, s22, 0xfffc0080
	s_addc_u32 s25, s23, -1
	s_cmp_eq_u32 s54, 12
	s_cselect_b32 s31, s15, s25
	s_cselect_b32 s30, s50, s24
	s_cselect_b32 s25, s9, s53
	s_cselect_b32 s24, s51, s52
	s_add_i32 m0, s21, 0xc000
	ds_read_b128 v[182:185], v149
	ds_read_b128 v[192:195], v149 offset:1024
	ds_read_b128 v[196:199], v149 offset:2048
	ds_read_b128 v[200:203], v149 offset:3072
	ds_read_b128 v[204:207], v149 offset:4096
	ds_read_b128 v[208:211], v149 offset:5120
	ds_read_b128 v[212:215], v149 offset:6144
	ds_read_b128 v[216:219], v149 offset:7168
	global_load_lds_dwordx4 v136, s[22:23]
	s_add_i32 m0, s21, 0xe000
	s_nop 0
	global_load_lds_dwordx4 v138, s[22:23]
	s_waitcnt vmcnt(8)
	s_waitcnt lgkmcnt(0)
	s_setprio 1
	s_barrier
	v_mfma_f32_16x16x32_bf16 v[124:127], v[150:153], v[182:185], v[124:127]
	v_mfma_f32_16x16x32_bf16 v[120:123], v[158:161], v[182:185], v[120:123]
	v_mfma_f32_16x16x32_bf16 v[108:111], v[150:153], v[196:199], v[108:111]
	v_mfma_f32_16x16x32_bf16 v[104:107], v[158:161], v[196:199], v[104:107]
	v_mfma_f32_16x16x32_bf16 v[92:95], v[150:153], v[204:207], v[92:95]
	v_mfma_f32_16x16x32_bf16 v[88:91], v[158:161], v[204:207], v[88:91]
	v_mfma_f32_16x16x32_bf16 v[76:79], v[150:153], v[212:215], v[76:79]
	v_mfma_f32_16x16x32_bf16 v[72:75], v[158:161], v[212:215], v[72:75]
	v_mfma_f32_16x16x32_bf16 v[124:127], v[154:157], v[192:195], v[124:127]
	v_mfma_f32_16x16x32_bf16 v[120:123], v[162:165], v[192:195], v[120:123]
	v_mfma_f32_16x16x32_bf16 v[108:111], v[154:157], v[200:203], v[108:111]
	v_mfma_f32_16x16x32_bf16 v[104:107], v[162:165], v[200:203], v[104:107]
	v_mfma_f32_16x16x32_bf16 v[92:95], v[154:157], v[208:211], v[92:95]
	v_mfma_f32_16x16x32_bf16 v[88:91], v[162:165], v[208:211], v[88:91]
	v_mfma_f32_16x16x32_bf16 v[76:79], v[154:157], v[216:219], v[76:79]
	v_mfma_f32_16x16x32_bf16 v[72:75], v[162:165], v[216:219], v[72:75]
	v_mfma_f32_16x16x32_bf16 v[116:119], v[166:169], v[182:185], v[116:119]
	v_mfma_f32_16x16x32_bf16 v[112:115], v[174:177], v[182:185], v[112:115]
	v_mfma_f32_16x16x32_bf16 v[100:103], v[166:169], v[196:199], v[100:103]
	v_mfma_f32_16x16x32_bf16 v[96:99], v[174:177], v[196:199], v[96:99]
	v_mfma_f32_16x16x32_bf16 v[84:87], v[166:169], v[204:207], v[84:87]
	v_mfma_f32_16x16x32_bf16 v[80:83], v[174:177], v[204:207], v[80:83]
	v_mfma_f32_16x16x32_bf16 v[68:71], v[166:169], v[212:215], v[68:71]
	v_mfma_f32_16x16x32_bf16 v[64:67], v[174:177], v[212:215], v[64:67]
	v_mfma_f32_16x16x32_bf16 v[116:119], v[170:173], v[192:195], v[116:119]
	v_mfma_f32_16x16x32_bf16 v[112:115], v[178:181], v[192:195], v[112:115]
	v_mfma_f32_16x16x32_bf16 v[100:103], v[170:173], v[200:203], v[100:103]
	v_mfma_f32_16x16x32_bf16 v[96:99], v[178:181], v[200:203], v[96:99]
	v_mfma_f32_16x16x32_bf16 v[84:87], v[170:173], v[208:211], v[84:87]
	v_mfma_f32_16x16x32_bf16 v[80:83], v[178:181], v[208:211], v[80:83]
	v_mfma_f32_16x16x32_bf16 v[68:71], v[170:173], v[216:219], v[68:71]
	v_mfma_f32_16x16x32_bf16 v[64:67], v[178:181], v[216:219], v[64:67]
	s_barrier
	s_setprio 0
	s_add_i32 s55, s46, s35
	v_lshl_add_u64 v[186:187], s[24:25], 0, v[132:133]
	s_mov_b32 m0, s55
	ds_read_b128 v[182:185], v149 offset:16384
	ds_read_b128 v[192:195], v149 offset:17408
	ds_read_b128 v[196:199], v149 offset:18432
	ds_read_b128 v[200:203], v149 offset:19456
	ds_read_b128 v[204:207], v149 offset:20480
	ds_read_b128 v[208:211], v149 offset:21504
	ds_read_b128 v[212:215], v149 offset:22528
	ds_read_b128 v[216:219], v149 offset:23552
	global_load_lds_dwordx4 v[186:187], off
	s_add_i32 m0, s55, 0x2000
	s_add_u32 s56, s24, 0x40000
	v_lshl_add_u64 v[220:221], s[24:25], 0, v[128:129]
	s_addc_u32 s57, s25, 0
	s_add_i32 s55, s47, s35
	global_load_lds_dwordx4 v[220:221], off
	s_mov_b32 m0, s55
	v_lshl_add_u64 v[224:225], s[30:31], 0, v[130:131]
	global_load_lds_dwordx4 v132, s[56:57]
	s_add_i32 m0, s55, 0x2000
	s_nop 0
	global_load_lds_dwordx4 v128, s[56:57]
	v_lshl_add_u64 v[222:223], s[30:31], 0, v[134:135]
	s_mov_b32 m0, s21
	s_nop 0
	global_load_lds_dwordx4 v[222:223], off
	s_mov_b32 m0, s38
	s_nop 0
	global_load_lds_dwordx4 v[224:225], off
	s_waitcnt vmcnt(8)
	s_waitcnt lgkmcnt(0)
	s_setprio 1
	s_barrier
	v_mfma_f32_16x16x32_bf16 v[60:63], v[150:153], v[182:185], v[60:63]
	v_mfma_f32_16x16x32_bf16 v[56:59], v[158:161], v[182:185], v[56:59]
	v_mfma_f32_16x16x32_bf16 v[44:47], v[150:153], v[196:199], v[44:47]
	v_mfma_f32_16x16x32_bf16 v[40:43], v[158:161], v[196:199], v[40:43]
	v_mfma_f32_16x16x32_bf16 v[28:31], v[150:153], v[204:207], v[28:31]
	v_mfma_f32_16x16x32_bf16 v[24:27], v[158:161], v[204:207], v[24:27]
	v_mfma_f32_16x16x32_bf16 v[12:15], v[150:153], v[212:215], v[12:15]
	v_mfma_f32_16x16x32_bf16 v[8:11], v[158:161], v[212:215], v[8:11]
	v_mfma_f32_16x16x32_bf16 v[60:63], v[154:157], v[192:195], v[60:63]
	v_mfma_f32_16x16x32_bf16 v[56:59], v[162:165], v[192:195], v[56:59]
	v_mfma_f32_16x16x32_bf16 v[44:47], v[154:157], v[200:203], v[44:47]
	v_mfma_f32_16x16x32_bf16 v[40:43], v[162:165], v[200:203], v[40:43]
	v_mfma_f32_16x16x32_bf16 v[28:31], v[154:157], v[208:211], v[28:31]
	v_mfma_f32_16x16x32_bf16 v[24:27], v[162:165], v[208:211], v[24:27]
	v_mfma_f32_16x16x32_bf16 v[12:15], v[154:157], v[216:219], v[12:15]
	v_mfma_f32_16x16x32_bf16 v[8:11], v[162:165], v[216:219], v[8:11]
	v_mfma_f32_16x16x32_bf16 v[52:55], v[166:169], v[182:185], v[52:55]
	v_mfma_f32_16x16x32_bf16 v[48:51], v[174:177], v[182:185], v[48:51]
	v_mfma_f32_16x16x32_bf16 v[36:39], v[166:169], v[196:199], v[36:39]
	v_mfma_f32_16x16x32_bf16 v[32:35], v[174:177], v[196:199], v[32:35]
	v_mfma_f32_16x16x32_bf16 v[20:23], v[166:169], v[204:207], v[20:23]
	v_mfma_f32_16x16x32_bf16 v[16:19], v[174:177], v[204:207], v[16:19]
	v_mfma_f32_16x16x32_bf16 v[4:7], v[166:169], v[212:215], v[4:7]
	v_mfma_f32_16x16x32_bf16 v[0:3], v[174:177], v[212:215], v[0:3]
	v_mfma_f32_16x16x32_bf16 v[52:55], v[170:173], v[192:195], v[52:55]
	v_mfma_f32_16x16x32_bf16 v[48:51], v[178:181], v[192:195], v[48:51]
	v_mfma_f32_16x16x32_bf16 v[36:39], v[170:173], v[200:203], v[36:39]
	v_mfma_f32_16x16x32_bf16 v[32:35], v[178:181], v[200:203], v[32:35]
	v_mfma_f32_16x16x32_bf16 v[20:23], v[170:173], v[208:211], v[20:23]
	v_mfma_f32_16x16x32_bf16 v[16:19], v[178:181], v[208:211], v[16:19]
	v_mfma_f32_16x16x32_bf16 v[4:7], v[170:173], v[216:219], v[4:7]
	v_mfma_f32_16x16x32_bf16 v[0:3], v[178:181], v[216:219], v[0:3]
	s_barrier
; #define PG8_STAGE(bufoff, gbase, voff) do { _Pragma("unroll") for (int _i = 0; _i < 2; ++_i) \
;         __builtin_amdgcn_global_load_lds((const unsigned*)((const char*)(gbase) + (voff)[_i]), (PG8_LAS unsigned*)(lds + (bufoff) + ldsw + _i * 8192), 16, 0, 0); } while (0)
; #define PG8_LDA(dst, b, h) do { _Pragma("unroll") for (int m = 0; m < 4; ++m) _Pragma("unroll") for (int k = 0; k < 2; ++k) dst[m][k] = *(const PG8_LAS bf16x8*)(lds + PG8_SA(b, h) + aoff + m * 2048 + k * 1024); } while (0)
; #define PG8_LDB(dst, b, h) do { _Pragma("unroll") for (int n = 0; n < 2; ++n) _Pragma("unroll") for (int k = 0; k < 2; ++k) dst[n][k] = *(const PG8_LAS bf16x8*)(lds + PG8_SB(b, h) + boff + n * 2048 + k * 1024); } while (0)
; #define PG8_MMA(ai, bj, At, Bt) do { __builtin_amdgcn_s_setprio(1); _Pragma("unroll") for (int m = 0; m < 4; ++m) _Pragma("unroll") for (int n = 0; n < 2; ++n) _Pragma("unroll") for (int k = 0; k < 2; ++k) \
;         acc[ai][bj][m][n] = __builtin_amdgcn_mfma_f32_16x16x32_bf16(Bt[n][k], At[m][k], acc[ai][bj][m][n], 0, 0, 0); __builtin_amdgcn_s_setprio(0); } while (0)
; #define PG8_WAIT_V(n) asm volatile("s_waitcnt vmcnt(" #n ")" ::: "memory")
; #define PG8_WAIT_L(n) asm volatile("s_waitcnt lgkmcnt(" #n ")" ::: "memory")
; #define PG8_BAR __builtin_amdgcn_s_barrier()
; #define PG8_SCHED __builtin_amdgcn_sched_barrier(0)
; template <class Epi, class Sched, bool ALIGN_EPI = false, bool SP2 = false>
; __device__ __forceinline__ void gemm_phase(PG8_LAS unsigned char* lds, const Gemm g, const Sched& S, const Epi& E) {
;     ...
;             PG8_LDB(B0, 1, 0); PG8_LDB(B1, 1, 1); PG8_SCHED; PG8_LDA(At, 1, 0); PG8_STAGE(PG8_SA(0, 1), a2 + hstep, voffA);
;             PG8_WAIT_V(8); PG8_WAIT_L(0); PG8_BAR; PG8_MMA(0, 0, At, B0); PG8_MMA(0, 1, At, B1); PG8_BAR; PG8_SCHED;
;             PG8_LDA(At, 1, 1); PG8_STAGE(PG8_SB(1, 0), b3, voffB); PG8_STAGE(PG8_SB(1, 1), b3 + hstep, voffB); PG8_STAGE(PG8_SA(1, 0), a3, voffA);
;             PG8_WAIT_V(8); PG8_WAIT_L(0); PG8_BAR; PG8_MMA(1, 0, At, B0); PG8_MMA(1, 1, At, B1); PG8_BAR; PG8_SCHED;
;     ...
;         if constexpr (ALIGN_EPI) { if (wr == 0) PG8_BAR; }
	s_setprio 0
	s_add_i32 s55, 0, 0x18000
	s_add_i32 s56, 0, 0x1c000
	v_add_u32_e32 v162, s55, v145
	v_add_u32_e32 v178, s56, v145
	ds_read_b128 v[150:153], v162
	ds_read_b128 v[154:157], v162 offset:1024
	ds_read_b128 v[158:161], v162 offset:2048
	ds_read_b128 v[162:165], v162 offset:3072
	ds_read_b128 v[166:169], v178
	ds_read_b128 v[170:173], v178 offset:1024
	ds_read_b128 v[174:177], v178 offset:2048
	ds_read_b128 v[178:181], v178 offset:3072
	s_add_u32 s30, s30, 0x40000
	s_addc_u32 s31, s31, 0
	s_mov_b32 m0, s39
	ds_read_b128 v[182:185], v149 offset:32768
	ds_read_b128 v[192:195], v149 offset:33792
	ds_read_b128 v[196:199], v149 offset:34816
	ds_read_b128 v[200:203], v149 offset:35840
	ds_read_b128 v[204:207], v149 offset:36864
	ds_read_b128 v[208:211], v149 offset:37888
	ds_read_b128 v[212:215], v149 offset:38912
	ds_read_b128 v[216:219], v149 offset:39936
	global_load_lds_dwordx4 v134, s[30:31]
	v_lshl_add_u64 v[226:227], s[30:31], 0, v[130:131]
	s_mov_b32 m0, s40
	s_nop 0
	global_load_lds_dwordx4 v[226:227], off
	s_waitcnt vmcnt(8)
	s_waitcnt lgkmcnt(0)
	s_setprio 1
	s_barrier
	v_mfma_f32_16x16x32_bf16 v[124:127], v[150:153], v[182:185], v[124:127]
	v_mfma_f32_16x16x32_bf16 v[120:123], v[158:161], v[182:185], v[120:123]
	v_mfma_f32_16x16x32_bf16 v[108:111], v[150:153], v[196:199], v[108:111]
	v_mfma_f32_16x16x32_bf16 v[104:107], v[158:161], v[196:199], v[104:107]
	v_mfma_f32_16x16x32_bf16 v[92:95], v[150:153], v[204:207], v[92:95]
	v_mfma_f32_16x16x32_bf16 v[88:91], v[158:161], v[204:207], v[88:91]
	v_mfma_f32_16x16x32_bf16 v[76:79], v[150:153], v[212:215], v[76:79]
	v_mfma_f32_16x16x32_bf16 v[72:75], v[158:161], v[212:215], v[72:75]
	v_mfma_f32_16x16x32_bf16 v[124:127], v[154:157], v[192:195], v[124:127]
	v_mfma_f32_16x16x32_bf16 v[120:123], v[162:165], v[192:195], v[120:123]
	v_mfma_f32_16x16x32_bf16 v[108:111], v[154:157], v[200:203], v[108:111]
	v_mfma_f32_16x16x32_bf16 v[104:107], v[162:165], v[200:203], v[104:107]
	v_mfma_f32_16x16x32_bf16 v[92:95], v[154:157], v[208:211], v[92:95]
	v_mfma_f32_16x16x32_bf16 v[88:91], v[162:165], v[208:211], v[88:91]
	v_mfma_f32_16x16x32_bf16 v[76:79], v[154:157], v[216:219], v[76:79]
	v_mfma_f32_16x16x32_bf16 v[72:75], v[162:165], v[216:219], v[72:75]
	v_mfma_f32_16x16x32_bf16 v[116:119], v[166:169], v[182:185], v[116:119]
	v_mfma_f32_16x16x32_bf16 v[112:115], v[174:177], v[182:185], v[112:115]
	v_mfma_f32_16x16x32_bf16 v[100:103], v[166:169], v[196:199], v[100:103]
	v_mfma_f32_16x16x32_bf16 v[96:99], v[174:177], v[196:199], v[96:99]
	v_mfma_f32_16x16x32_bf16 v[84:87], v[166:169], v[204:207], v[84:87]
	v_mfma_f32_16x16x32_bf16 v[80:83], v[174:177], v[204:207], v[80:83]
	v_mfma_f32_16x16x32_bf16 v[68:71], v[166:169], v[212:215], v[68:71]
	v_mfma_f32_16x16x32_bf16 v[64:67], v[174:177], v[212:215], v[64:67]
	v_mfma_f32_16x16x32_bf16 v[116:119], v[170:173], v[192:195], v[116:119]
	v_mfma_f32_16x16x32_bf16 v[112:115], v[178:181], v[192:195], v[112:115]
	v_mfma_f32_16x16x32_bf16 v[100:103], v[170:173], v[200:203], v[100:103]
	v_mfma_f32_16x16x32_bf16 v[96:99], v[178:181], v[200:203], v[96:99]
	v_mfma_f32_16x16x32_bf16 v[84:87], v[170:173], v[208:211], v[84:87]
	v_mfma_f32_16x16x32_bf16 v[80:83], v[178:181], v[208:211], v[80:83]
	v_mfma_f32_16x16x32_bf16 v[68:71], v[170:173], v[216:219], v[68:71]
	v_mfma_f32_16x16x32_bf16 v[64:67], v[178:181], v[216:219], v[64:67]
	s_barrier
	s_setprio 0
	s_add_i32 s30, s55, s35
	v_lshl_add_u64 v[186:187], v[186:187], 0, s[4:5]
	s_mov_b32 m0, s30
	ds_read_b128 v[182:185], v149 offset:49152
	ds_read_b128 v[192:195], v149 offset:50176
	ds_read_b128 v[196:199], v149 offset:51200
	ds_read_b128 v[200:203], v149 offset:52224
	ds_read_b128 v[204:207], v149 offset:53248
	ds_read_b128 v[208:211], v149 offset:54272
	ds_read_b128 v[212:215], v149 offset:55296
	ds_read_b128 v[216:219], v149 offset:56320
	global_load_lds_dwordx4 v[186:187], off
	s_add_i32 m0, s30, 0x2000
	s_add_u32 s24, s24, 0x40080
	v_lshl_add_u64 v[186:187], v[220:221], 0, s[4:5]
	s_addc_u32 s25, s25, 0
	s_add_i32 s30, s56, s35
	global_load_lds_dwordx4 v[186:187], off
	s_mov_b32 m0, s30
	s_nop 0
	global_load_lds_dwordx4 v132, s[24:25]
	s_add_i32 m0, s30, 0x2000
	s_nop 0
	global_load_lds_dwordx4 v128, s[24:25]
	v_lshl_add_u64 v[186:187], v[222:223], 0, s[4:5]
	s_mov_b32 m0, s42
	s_nop 0
	global_load_lds_dwordx4 v[186:187], off
	v_lshl_add_u64 v[186:187], v[224:225], 0, s[4:5]
	s_mov_b32 m0, s43
	s_nop 0
	global_load_lds_dwordx4 v[186:187], off
	s_waitcnt vmcnt(8)
	s_waitcnt lgkmcnt(0)
	s_setprio 1
	s_barrier
	v_mfma_f32_16x16x32_bf16 v[60:63], v[150:153], v[182:185], v[60:63]
	v_mfma_f32_16x16x32_bf16 v[56:59], v[158:161], v[182:185], v[56:59]
	v_mfma_f32_16x16x32_bf16 v[44:47], v[150:153], v[196:199], v[44:47]
	v_mfma_f32_16x16x32_bf16 v[40:43], v[158:161], v[196:199], v[40:43]
	v_mfma_f32_16x16x32_bf16 v[28:31], v[150:153], v[204:207], v[28:31]
	v_mfma_f32_16x16x32_bf16 v[24:27], v[158:161], v[204:207], v[24:27]
	v_mfma_f32_16x16x32_bf16 v[12:15], v[150:153], v[212:215], v[12:15]
	v_mfma_f32_16x16x32_bf16 v[8:11], v[158:161], v[212:215], v[8:11]
	v_mfma_f32_16x16x32_bf16 v[60:63], v[154:157], v[192:195], v[60:63]
	v_mfma_f32_16x16x32_bf16 v[56:59], v[162:165], v[192:195], v[56:59]
	v_mfma_f32_16x16x32_bf16 v[44:47], v[154:157], v[200:203], v[44:47]
	v_mfma_f32_16x16x32_bf16 v[40:43], v[162:165], v[200:203], v[40:43]
	v_mfma_f32_16x16x32_bf16 v[28:31], v[154:157], v[208:211], v[28:31]
	v_mfma_f32_16x16x32_bf16 v[24:27], v[162:165], v[208:211], v[24:27]
	v_mfma_f32_16x16x32_bf16 v[12:15], v[154:157], v[216:219], v[12:15]
	v_mfma_f32_16x16x32_bf16 v[8:11], v[162:165], v[216:219], v[8:11]
	v_mfma_f32_16x16x32_bf16 v[52:55], v[166:169], v[182:185], v[52:55]
	v_mfma_f32_16x16x32_bf16 v[48:51], v[174:177], v[182:185], v[48:51]
	v_mfma_f32_16x16x32_bf16 v[36:39], v[166:169], v[196:199], v[36:39]
	v_mfma_f32_16x16x32_bf16 v[32:35], v[174:177], v[196:199], v[32:35]
	v_mfma_f32_16x16x32_bf16 v[20:23], v[166:169], v[204:207], v[20:23]
	v_mfma_f32_16x16x32_bf16 v[16:19], v[174:177], v[204:207], v[16:19]
	v_mfma_f32_16x16x32_bf16 v[4:7], v[166:169], v[212:215], v[4:7]
	v_mfma_f32_16x16x32_bf16 v[0:3], v[174:177], v[212:215], v[0:3]
	v_mfma_f32_16x16x32_bf16 v[52:55], v[170:173], v[192:195], v[52:55]
	v_mfma_f32_16x16x32_bf16 v[48:51], v[178:181], v[192:195], v[48:51]
	v_mfma_f32_16x16x32_bf16 v[36:39], v[170:173], v[200:203], v[36:39]
	v_mfma_f32_16x16x32_bf16 v[32:35], v[178:181], v[200:203], v[32:35]
	v_mfma_f32_16x16x32_bf16 v[20:23], v[170:173], v[208:211], v[20:23]
	v_mfma_f32_16x16x32_bf16 v[16:19], v[178:181], v[208:211], v[16:19]
	v_mfma_f32_16x16x32_bf16 v[4:7], v[170:173], v[216:219], v[4:7]
	v_mfma_f32_16x16x32_bf16 v[0:3], v[178:181], v[216:219], v[0:3]
	s_barrier
	s_setprio 0
	s_add_i32 s54, s54, 2
	s_add_u32 s22, s22, 0x100
	s_addc_u32 s23, s23, 0
	s_add_u32 s52, s52, 0x100
	s_addc_u32 s53, s53, 0
	s_cmp_gt_u32 s54, 13
	s_cbranch_scc0 .LBB0_192
	s_and_b64 vcc, exec, s[6:7]
	s_cbranch_vccz .LBB0_195
	s_barrier

; #define PG8_STAGE(bufoff, gbase, voff) do { _Pragma("unroll") for (int _i = 0; _i < 2; ++_i) \
;         __builtin_amdgcn_global_load_lds((const unsigned*)((const char*)(gbase) + (voff)[_i]), (PG8_LAS unsigned*)(lds + (bufoff) + ldsw + _i * 8192), 16, 0, 0); } while (0)
; #define PG8_LDA(dst, b, h) do { _Pragma("unroll") for (int m = 0; m < 4; ++m) _Pragma("unroll") for (int k = 0; k < 2; ++k) dst[m][k] = *(const PG8_LAS bf16x8*)(lds + PG8_SA(b, h) + aoff + m * 2048 + k * 1024); } while (0)
; #define PG8_LDB(dst, b, h) do { _Pragma("unroll") for (int n = 0; n < 2; ++n) _Pragma("unroll") for (int k = 0; k < 2; ++k) dst[n][k] = *(const PG8_LAS bf16x8*)(lds + PG8_SB(b, h) + boff + n * 2048 + k * 1024); } while (0)
; #define PG8_WAIT_V(n) asm volatile("s_waitcnt vmcnt(" #n ")" ::: "memory")
; #define PG8_WAIT_L(n) asm volatile("s_waitcnt lgkmcnt(" #n ")" ::: "memory")
; #define PG8_BAR __builtin_amdgcn_s_barrier()
; #define PG8_SCHED __builtin_amdgcn_sched_barrier(0)
; template <class Epi, class Sched, bool ALIGN_EPI = false, bool SP2 = false>
; __device__ __forceinline__ void gemm_phase(PG8_LAS unsigned char* lds, const Gemm g, const Sched& S, const Epi& E) {
;     ...
;         const bool has_next = S.next(ui + 1, nxt);
;         const char* nA = has_next ? (const char*)g.A + (size_t)nxt.pm * tstep : cA; const char* nB = has_next ? (const char*)g.Bt + (size_t)nxt.pn * tstep : cB;
;         for (int t = 0; t < nt; t += 2) {
;             const bool last = (t == nt - 2);
;             const char* a1 = cA + (size_t)(t + 1) * kstep;
;             const char* a2 = last ? nA : cA + (size_t)(t + 2) * kstep; const char* b2 = last ? nB : cB + (size_t)(t + 2) * kstep;
;             const char* a3 = a2 + kstep; const char* b3 = b2 + kstep;
;             if (last && has_next) S.a_ready(nxt);
;             if constexpr (SP2) {
;             PG8_LDB(B0, 0, 0); PG8_LDB(B1, 0, 1); PG8_SCHED; PG8_LDA(At, 0, 0); PG8_STAGE(PG8_SA(1, 1), a1 + hstep, voffA);
;             PG8_WAIT_V(8); PG8_WAIT_L(0); PG8_BAR; PG8_MMA(0, 0, At, B0); PG8_MMA(0, 1, At, B1); PG8_BAR; PG8_SCHED;
;             PG8_LDA(At, 0, 1); PG8_STAGE(PG8_SB(0, 0), b2, voffB); PG8_STAGE(PG8_SB(0, 1), b2 + hstep, voffB); PG8_STAGE(PG8_SA(0, 0), a2, voffA);
;             PG8_WAIT_V(8); PG8_WAIT_L(0); PG8_BAR; PG8_MMA(1, 0, At, B0); PG8_MMA(1, 1, At, B1); PG8_BAR; PG8_SCHED;
.LBB0_373:
	s_ashr_i32 s31, s30, 31
	s_lshl_b64 s[34:35], s[30:31], 19
	v_readlane_b32 s36, v235, 31
	v_readlane_b32 s37, v235, 32
	s_add_u32 s34, s36, s34
	s_addc_u32 s35, s37, s35
	s_and_b64 s[36:37], s[6:7], exec
	s_cselect_b32 s1, s35, s3
	s_cselect_b32 s25, s34, s2
	s_ashr_i32 s29, s28, 31
	s_lshl_b64 s[36:37], s[28:29], 19
	s_add_u32 s36, s10, s36
	s_addc_u32 s37, s11, s37
	s_and_b64 s[40:41], s[6:7], exec
	s_cselect_b32 s29, s37, s39
	s_cselect_b32 s31, s36, s38
	s_add_u32 s2, s2, 0x40080
	s_addc_u32 s3, s3, 0
	s_add_u32 s58, s38, 0x100
	s_addc_u32 s59, s39, 0
	s_mov_b32 s60, -2
	ds_read_b128 v[128:131], v171
	ds_read_b128 v[132:135], v171 offset:1024
	ds_read_b128 v[136:139], v171 offset:2048
	ds_read_b128 v[140:143], v171 offset:3072
	ds_read_b128 v[164:167], v172
	ds_read_b128 v[178:181], v172 offset:1024
	ds_read_b128 v[182:185], v172 offset:2048
	ds_read_b128 v[192:195], v172 offset:3072
	s_add_u32 s38, s2, 0xfffc0080
	s_addc_u32 s39, s3, -1
	s_cmp_eq_u32 s60, 12
	s_cselect_b32 s41, s1, s39
	s_cselect_b32 s40, s25, s38
	s_cselect_b32 s39, s29, s59
	s_cselect_b32 s38, s31, s58
	s_add_i32 m0, s44, 0xc000
	ds_read_b128 v[196:199], v173
	ds_read_b128 v[200:203], v173 offset:1024
	ds_read_b128 v[204:207], v173 offset:2048
	ds_read_b128 v[208:211], v173 offset:3072
	ds_read_b128 v[212:215], v173 offset:4096
	ds_read_b128 v[216:219], v173 offset:5120
	ds_read_b128 v[220:223], v173 offset:6144
	ds_read_b128 v[224:227], v173 offset:7168
	global_load_lds_dwordx4 v156, s[2:3]
	s_add_i32 m0, s44, 0xe000
	s_nop 0
	global_load_lds_dwordx4 v158, s[2:3]
	s_waitcnt vmcnt(8)
	s_waitcnt lgkmcnt(0)
	s_setprio 1
	s_barrier
	v_mfma_f32_16x16x32_bf16 v[124:127], v[128:131], v[196:199], 0
	v_mfma_f32_16x16x32_bf16 v[120:123], v[136:139], v[196:199], 0
	v_mfma_f32_16x16x32_bf16 v[108:111], v[128:131], v[204:207], 0
	v_mfma_f32_16x16x32_bf16 v[104:107], v[136:139], v[204:207], 0
	v_mfma_f32_16x16x32_bf16 v[92:95], v[128:131], v[212:215], 0
	v_mfma_f32_16x16x32_bf16 v[88:91], v[136:139], v[212:215], 0
	v_mfma_f32_16x16x32_bf16 v[76:79], v[128:131], v[220:223], 0
	v_mfma_f32_16x16x32_bf16 v[72:75], v[136:139], v[220:223], 0
	v_mfma_f32_16x16x32_bf16 v[124:127], v[132:135], v[200:203], v[124:127]
	v_mfma_f32_16x16x32_bf16 v[120:123], v[140:143], v[200:203], v[120:123]
	v_mfma_f32_16x16x32_bf16 v[108:111], v[132:135], v[208:211], v[108:111]
	v_mfma_f32_16x16x32_bf16 v[104:107], v[140:143], v[208:211], v[104:107]
	v_mfma_f32_16x16x32_bf16 v[92:95], v[132:135], v[216:219], v[92:95]
	v_mfma_f32_16x16x32_bf16 v[88:91], v[140:143], v[216:219], v[88:91]
	v_mfma_f32_16x16x32_bf16 v[76:79], v[132:135], v[224:227], v[76:79]
	v_mfma_f32_16x16x32_bf16 v[72:75], v[140:143], v[224:227], v[72:75]
	v_mfma_f32_16x16x32_bf16 v[116:119], v[164:167], v[196:199], 0
	v_mfma_f32_16x16x32_bf16 v[112:115], v[182:185], v[196:199], 0
	v_mfma_f32_16x16x32_bf16 v[100:103], v[164:167], v[204:207], 0
	v_mfma_f32_16x16x32_bf16 v[96:99], v[182:185], v[204:207], 0
	v_mfma_f32_16x16x32_bf16 v[84:87], v[164:167], v[212:215], 0
	v_mfma_f32_16x16x32_bf16 v[80:83], v[182:185], v[212:215], 0
	v_mfma_f32_16x16x32_bf16 v[68:71], v[164:167], v[220:223], 0
	v_mfma_f32_16x16x32_bf16 v[64:67], v[182:185], v[220:223], 0
	v_mfma_f32_16x16x32_bf16 v[116:119], v[178:181], v[200:203], v[116:119]
	v_mfma_f32_16x16x32_bf16 v[112:115], v[192:195], v[200:203], v[112:115]
	v_mfma_f32_16x16x32_bf16 v[100:103], v[178:181], v[208:211], v[100:103]
	v_mfma_f32_16x16x32_bf16 v[96:99], v[192:195], v[208:211], v[96:99]
	v_mfma_f32_16x16x32_bf16 v[84:87], v[178:181], v[216:219], v[84:87]
	v_mfma_f32_16x16x32_bf16 v[80:83], v[192:195], v[216:219], v[80:83]
	v_mfma_f32_16x16x32_bf16 v[68:71], v[178:181], v[224:227], v[68:71]
	v_mfma_f32_16x16x32_bf16 v[64:67], v[192:195], v[224:227], v[64:67]
	s_barrier
	s_setprio 0
	s_add_i32 s61, s52, s33
	v_lshl_add_u64 v[168:169], s[38:39], 0, v[148:149]
	s_mov_b32 m0, s61
	ds_read_b128 v[196:199], v173 offset:16384
	ds_read_b128 v[200:203], v173 offset:17408
	ds_read_b128 v[204:207], v173 offset:18432
	ds_read_b128 v[208:211], v173 offset:19456
	ds_read_b128 v[212:215], v173 offset:20480
	ds_read_b128 v[216:219], v173 offset:21504
	ds_read_b128 v[220:223], v173 offset:22528
	ds_read_b128 v[224:227], v173 offset:23552
	global_load_lds_dwordx4 v[168:169], off
	s_add_i32 m0, s61, 0x2000
	s_add_u32 s62, s38, 0x40000
	v_lshl_add_u64 v[186:187], s[38:39], 0, v[144:145]
	s_addc_u32 s63, s39, 0
	s_add_i32 s61, s53, s33
	global_load_lds_dwordx4 v[186:187], off
	s_mov_b32 m0, s61
	v_lshl_add_u64 v[230:231], s[40:41], 0, v[146:147]
	global_load_lds_dwordx4 v148, s[62:63]
	s_add_i32 m0, s61, 0x2000
	s_nop 0
	global_load_lds_dwordx4 v144, s[62:63]
	v_lshl_add_u64 v[228:229], s[40:41], 0, v[150:151]
	s_mov_b32 m0, s44
	s_nop 0
	global_load_lds_dwordx4 v[228:229], off
	s_mov_b32 m0, s45
	s_nop 0
	global_load_lds_dwordx4 v[230:231], off
	s_waitcnt vmcnt(8)
	s_waitcnt lgkmcnt(0)
	s_setprio 1
	s_barrier
; #define PG8_STAGE(bufoff, gbase, voff) do { _Pragma("unroll") for (int _i = 0; _i < 2; ++_i) \
;         __builtin_amdgcn_global_load_lds((const unsigned*)((const char*)(gbase) + (voff)[_i]), (PG8_LAS unsigned*)(lds + (bufoff) + ldsw + _i * 8192), 16, 0, 0); } while (0)
; #define PG8_LDA(dst, b, h) do { _Pragma("unroll") for (int m = 0; m < 4; ++m) _Pragma("unroll") for (int k = 0; k < 2; ++k) dst[m][k] = *(const PG8_LAS bf16x8*)(lds + PG8_SA(b, h) + aoff + m * 2048 + k * 1024); } while (0)
; #define PG8_LDB(dst, b, h) do { _Pragma("unroll") for (int n = 0; n < 2; ++n) _Pragma("unroll") for (int k = 0; k < 2; ++k) dst[n][k] = *(const PG8_LAS bf16x8*)(lds + PG8_SB(b, h) + boff + n * 2048 + k * 1024); } while (0)
; #define PG8_MMA(ai, bj, At, Bt) do { __builtin_amdgcn_s_setprio(1); _Pragma("unroll") for (int m = 0; m < 4; ++m) _Pragma("unroll") for (int n = 0; n < 2; ++n) _Pragma("unroll") for (int k = 0; k < 2; ++k) \
;         acc[ai][bj][m][n] = __builtin_amdgcn_mfma_f32_16x16x32_bf16(Bt[n][k], At[m][k], acc[ai][bj][m][n], 0, 0, 0); __builtin_amdgcn_s_setprio(0); } while (0)
; #define PG8_WAIT_V(n) asm volatile("s_waitcnt vmcnt(" #n ")" ::: "memory")
; #define PG8_WAIT_L(n) asm volatile("s_waitcnt lgkmcnt(" #n ")" ::: "memory")
; #define PG8_BAR __builtin_amdgcn_s_barrier()
; #define PG8_SCHED __builtin_amdgcn_sched_barrier(0)
; template <class Epi, class Sched, bool ALIGN_EPI = false, bool SP2 = false>
; __device__ __forceinline__ void gemm_phase(PG8_LAS unsigned char* lds, const Gemm g, const Sched& S, const Epi& E) {
;     ...
;             PG8_WAIT_V(8); PG8_WAIT_L(0); PG8_BAR; PG8_MMA(1, 0, At, B0); PG8_MMA(1, 1, At, B1); PG8_BAR; PG8_SCHED;
;             PG8_LDB(B0, 1, 0); PG8_LDB(B1, 1, 1); PG8_SCHED; PG8_LDA(At, 1, 0); PG8_STAGE(PG8_SA(0, 1), a2 + hstep, voffA);
;             PG8_WAIT_V(8); PG8_WAIT_L(0); PG8_BAR; PG8_MMA(0, 0, At, B0); PG8_MMA(0, 1, At, B1); PG8_BAR; PG8_SCHED;
	v_mfma_f32_16x16x32_bf16 v[60:63], v[128:131], v[196:199], 0
	v_mfma_f32_16x16x32_bf16 v[56:59], v[136:139], v[196:199], 0
	v_mfma_f32_16x16x32_bf16 v[44:47], v[128:131], v[204:207], 0
	v_mfma_f32_16x16x32_bf16 v[40:43], v[136:139], v[204:207], 0
	v_mfma_f32_16x16x32_bf16 v[28:31], v[128:131], v[212:215], 0
	v_mfma_f32_16x16x32_bf16 v[24:27], v[136:139], v[212:215], 0
	v_mfma_f32_16x16x32_bf16 v[12:15], v[128:131], v[220:223], 0
	v_mfma_f32_16x16x32_bf16 v[8:11], v[136:139], v[220:223], 0
	v_mfma_f32_16x16x32_bf16 v[60:63], v[132:135], v[200:203], v[60:63]
	v_mfma_f32_16x16x32_bf16 v[56:59], v[140:143], v[200:203], v[56:59]
	v_mfma_f32_16x16x32_bf16 v[44:47], v[132:135], v[208:211], v[44:47]
	v_mfma_f32_16x16x32_bf16 v[40:43], v[140:143], v[208:211], v[40:43]
	v_mfma_f32_16x16x32_bf16 v[28:31], v[132:135], v[216:219], v[28:31]
	v_mfma_f32_16x16x32_bf16 v[24:27], v[140:143], v[216:219], v[24:27]
	v_mfma_f32_16x16x32_bf16 v[12:15], v[132:135], v[224:227], v[12:15]
	v_mfma_f32_16x16x32_bf16 v[8:11], v[140:143], v[224:227], v[8:11]
	v_mfma_f32_16x16x32_bf16 v[52:55], v[164:167], v[196:199], 0
	v_mfma_f32_16x16x32_bf16 v[48:51], v[182:185], v[196:199], 0
	v_mfma_f32_16x16x32_bf16 v[36:39], v[164:167], v[204:207], 0
	v_mfma_f32_16x16x32_bf16 v[32:35], v[182:185], v[204:207], 0
	v_mfma_f32_16x16x32_bf16 v[20:23], v[164:167], v[212:215], 0
	v_mfma_f32_16x16x32_bf16 v[16:19], v[182:185], v[212:215], 0
	v_mfma_f32_16x16x32_bf16 v[4:7], v[164:167], v[220:223], 0
	v_mfma_f32_16x16x32_bf16 v[0:3], v[182:185], v[220:223], 0
	v_mfma_f32_16x16x32_bf16 v[52:55], v[178:181], v[200:203], v[52:55]
	v_mfma_f32_16x16x32_bf16 v[48:51], v[192:195], v[200:203], v[48:51]
	v_mfma_f32_16x16x32_bf16 v[36:39], v[178:181], v[208:211], v[36:39]
	v_mfma_f32_16x16x32_bf16 v[32:35], v[192:195], v[208:211], v[32:35]
	v_mfma_f32_16x16x32_bf16 v[20:23], v[178:181], v[216:219], v[20:23]
	v_mfma_f32_16x16x32_bf16 v[16:19], v[192:195], v[216:219], v[16:19]
	v_mfma_f32_16x16x32_bf16 v[4:7], v[178:181], v[224:227], v[4:7]
	v_mfma_f32_16x16x32_bf16 v[0:3], v[192:195], v[224:227], v[0:3]
	s_barrier
	s_setprio 0
	s_add_i32 s61, 0, 0x18000
	s_add_i32 s62, 0, 0x1c000
	v_add_u32_e32 v140, s61, v170
	v_add_u32_e32 v152, s62, v170
	ds_read_b128 v[128:131], v140
	ds_read_b128 v[132:135], v140 offset:1024
	ds_read_b128 v[136:139], v140 offset:2048
	ds_read_b128 v[140:143], v140 offset:3072
	ds_read_b128 v[164:167], v152
	ds_read_b128 v[178:181], v152 offset:1024
	ds_read_b128 v[182:185], v152 offset:2048
	ds_read_b128 v[192:195], v152 offset:3072
	s_add_u32 s40, s40, 0x40000
	s_addc_u32 s41, s41, 0
	s_mov_b32 m0, s46
	ds_read_b128 v[196:199], v173 offset:32768
	ds_read_b128 v[200:203], v173 offset:33792
	ds_read_b128 v[204:207], v173 offset:34816
	ds_read_b128 v[208:211], v173 offset:35840
	ds_read_b128 v[212:215], v173 offset:36864
	ds_read_b128 v[216:219], v173 offset:37888
	ds_read_b128 v[220:223], v173 offset:38912
	ds_read_b128 v[224:227], v173 offset:39936
	global_load_lds_dwordx4 v150, s[40:41]
	v_lshl_add_u64 v[232:233], s[40:41], 0, v[146:147]
	s_mov_b32 m0, s47
	s_nop 0
	global_load_lds_dwordx4 v[232:233], off
	s_waitcnt vmcnt(8)
	s_waitcnt lgkmcnt(0)
	s_setprio 1
	s_barrier
	v_mfma_f32_16x16x32_bf16 v[124:127], v[128:131], v[196:199], v[124:127]
	v_mfma_f32_16x16x32_bf16 v[120:123], v[136:139], v[196:199], v[120:123]
	v_mfma_f32_16x16x32_bf16 v[108:111], v[128:131], v[204:207], v[108:111]
	v_mfma_f32_16x16x32_bf16 v[104:107], v[136:139], v[204:207], v[104:107]
	v_mfma_f32_16x16x32_bf16 v[92:95], v[128:131], v[212:215], v[92:95]
	v_mfma_f32_16x16x32_bf16 v[88:91], v[136:139], v[212:215], v[88:91]
	v_mfma_f32_16x16x32_bf16 v[76:79], v[128:131], v[220:223], v[76:79]
	v_mfma_f32_16x16x32_bf16 v[72:75], v[136:139], v[220:223], v[72:75]
	v_mfma_f32_16x16x32_bf16 v[124:127], v[132:135], v[200:203], v[124:127]
	v_mfma_f32_16x16x32_bf16 v[120:123], v[140:143], v[200:203], v[120:123]
	v_mfma_f32_16x16x32_bf16 v[108:111], v[132:135], v[208:211], v[108:111]
	v_mfma_f32_16x16x32_bf16 v[104:107], v[140:143], v[208:211], v[104:107]
	v_mfma_f32_16x16x32_bf16 v[92:95], v[132:135], v[216:219], v[92:95]
	v_mfma_f32_16x16x32_bf16 v[88:91], v[140:143], v[216:219], v[88:91]
	v_mfma_f32_16x16x32_bf16 v[76:79], v[132:135], v[224:227], v[76:79]
	v_mfma_f32_16x16x32_bf16 v[72:75], v[140:143], v[224:227], v[72:75]
	v_mfma_f32_16x16x32_bf16 v[116:119], v[164:167], v[196:199], v[116:119]
	v_mfma_f32_16x16x32_bf16 v[112:115], v[182:185], v[196:199], v[112:115]
	v_mfma_f32_16x16x32_bf16 v[100:103], v[164:167], v[204:207], v[100:103]
	v_mfma_f32_16x16x32_bf16 v[96:99], v[182:185], v[204:207], v[96:99]
	v_mfma_f32_16x16x32_bf16 v[84:87], v[164:167], v[212:215], v[84:87]
	v_mfma_f32_16x16x32_bf16 v[80:83], v[182:185], v[212:215], v[80:83]
	v_mfma_f32_16x16x32_bf16 v[68:71], v[164:167], v[220:223], v[68:71]
	v_mfma_f32_16x16x32_bf16 v[64:67], v[182:185], v[220:223], v[64:67]
	v_mfma_f32_16x16x32_bf16 v[116:119], v[178:181], v[200:203], v[116:119]
	v_mfma_f32_16x16x32_bf16 v[112:115], v[192:195], v[200:203], v[112:115]
	v_mfma_f32_16x16x32_bf16 v[100:103], v[178:181], v[208:211], v[100:103]
	v_mfma_f32_16x16x32_bf16 v[96:99], v[192:195], v[208:211], v[96:99]
	v_mfma_f32_16x16x32_bf16 v[84:87], v[178:181], v[216:219], v[84:87]
	v_mfma_f32_16x16x32_bf16 v[80:83], v[192:195], v[216:219], v[80:83]
	v_mfma_f32_16x16x32_bf16 v[68:71], v[178:181], v[224:227], v[68:71]
	v_mfma_f32_16x16x32_bf16 v[64:67], v[192:195], v[224:227], v[64:67]
	s_barrier
; #define PG8_STAGE(bufoff, gbase, voff) do { _Pragma("unroll") for (int _i = 0; _i < 2; ++_i) \
;         __builtin_amdgcn_global_load_lds((const unsigned*)((const char*)(gbase) + (voff)[_i]), (PG8_LAS unsigned*)(lds + (bufoff) + ldsw + _i * 8192), 16, 0, 0); } while (0)
; #define PG8_LDA(dst, b, h) do { _Pragma("unroll") for (int m = 0; m < 4; ++m) _Pragma("unroll") for (int k = 0; k < 2; ++k) dst[m][k] = *(const PG8_LAS bf16x8*)(lds + PG8_SA(b, h) + aoff + m * 2048 + k * 1024); } while (0)
; #define PG8_LDB(dst, b, h) do { _Pragma("unroll") for (int n = 0; n < 2; ++n) _Pragma("unroll") for (int k = 0; k < 2; ++k) dst[n][k] = *(const PG8_LAS bf16x8*)(lds + PG8_SB(b, h) + boff + n * 2048 + k * 1024); } while (0)
; #define PG8_MMA(ai, bj, At, Bt) do { __builtin_amdgcn_s_setprio(1); _Pragma("unroll") for (int m = 0; m < 4; ++m) _Pragma("unroll") for (int n = 0; n < 2; ++n) _Pragma("unroll") for (int k = 0; k < 2; ++k) \
;         acc[ai][bj][m][n] = __builtin_amdgcn_mfma_f32_16x16x32_bf16(Bt[n][k], At[m][k], acc[ai][bj][m][n], 0, 0, 0); __builtin_amdgcn_s_setprio(0); } while (0)
; #define PG8_WAIT_V(n) asm volatile("s_waitcnt vmcnt(" #n ")" ::: "memory")
; #define PG8_WAIT_L(n) asm volatile("s_waitcnt lgkmcnt(" #n ")" ::: "memory")
; #define PG8_BAR __builtin_amdgcn_s_barrier()
; #define PG8_SCHED __builtin_amdgcn_sched_barrier(0)
; template <class Epi, class Sched, bool ALIGN_EPI = false, bool SP2 = false>
; __device__ __forceinline__ void gemm_phase(PG8_LAS unsigned char* lds, const Gemm g, const Sched& S, const Epi& E) {
;     ...
;             PG8_LDB(B0, 0, 0); PG8_LDB(B1, 0, 1); PG8_SCHED; PG8_LDA(At, 0, 0); PG8_STAGE(PG8_SA(1, 1), a1 + hstep, voffA);
;             PG8_WAIT_V(8); PG8_WAIT_L(0); PG8_BAR; PG8_MMA(0, 0, At, B0); PG8_MMA(0, 1, At, B1); PG8_BAR; PG8_SCHED;
;     ...
;             PG8_LDA(At, 1, 1); PG8_STAGE(PG8_SB(1, 0), b3, voffB); PG8_STAGE(PG8_SB(1, 1), b3 + hstep, voffB); PG8_STAGE(PG8_SA(1, 0), a3, voffA);
;             PG8_WAIT_V(8); PG8_WAIT_L(0); PG8_BAR; PG8_MMA(1, 0, At, B0); PG8_MMA(1, 1, At, B1); PG8_BAR; PG8_SCHED;
	s_setprio 0
	s_add_i32 s40, s61, s33
	v_lshl_add_u64 v[168:169], v[168:169], 0, s[16:17]
	s_mov_b32 m0, s40
	ds_read_b128 v[196:199], v173 offset:49152
	ds_read_b128 v[200:203], v173 offset:50176
	ds_read_b128 v[204:207], v173 offset:51200
	ds_read_b128 v[208:211], v173 offset:52224
	ds_read_b128 v[212:215], v173 offset:53248
	ds_read_b128 v[216:219], v173 offset:54272
	ds_read_b128 v[220:223], v173 offset:55296
	ds_read_b128 v[224:227], v173 offset:56320
	global_load_lds_dwordx4 v[168:169], off
	s_add_i32 m0, s40, 0x2000
	s_add_u32 s38, s38, 0x40080
	v_lshl_add_u64 v[168:169], v[186:187], 0, s[16:17]
	s_addc_u32 s39, s39, 0
	s_add_i32 s40, s62, s33
	global_load_lds_dwordx4 v[168:169], off
	s_mov_b32 m0, s40
	s_nop 0
	global_load_lds_dwordx4 v148, s[38:39]
	s_add_i32 m0, s40, 0x2000
	s_nop 0
	global_load_lds_dwordx4 v144, s[38:39]
	v_lshl_add_u64 v[168:169], v[228:229], 0, s[16:17]
	s_mov_b32 m0, s48
	s_nop 0
	global_load_lds_dwordx4 v[168:169], off
	v_lshl_add_u64 v[168:169], v[230:231], 0, s[16:17]
	s_mov_b32 m0, s49
	s_nop 0
	global_load_lds_dwordx4 v[168:169], off
	s_waitcnt vmcnt(8)
	s_waitcnt lgkmcnt(0)
	s_setprio 1
	s_barrier
	v_mfma_f32_16x16x32_bf16 v[60:63], v[128:131], v[196:199], v[60:63]
	v_mfma_f32_16x16x32_bf16 v[56:59], v[136:139], v[196:199], v[56:59]
	v_mfma_f32_16x16x32_bf16 v[44:47], v[128:131], v[204:207], v[44:47]
	v_mfma_f32_16x16x32_bf16 v[40:43], v[136:139], v[204:207], v[40:43]
	v_mfma_f32_16x16x32_bf16 v[28:31], v[128:131], v[212:215], v[28:31]
	v_mfma_f32_16x16x32_bf16 v[24:27], v[136:139], v[212:215], v[24:27]
	v_mfma_f32_16x16x32_bf16 v[12:15], v[128:131], v[220:223], v[12:15]
	v_mfma_f32_16x16x32_bf16 v[8:11], v[136:139], v[220:223], v[8:11]
	v_mfma_f32_16x16x32_bf16 v[60:63], v[132:135], v[200:203], v[60:63]
	v_mfma_f32_16x16x32_bf16 v[56:59], v[140:143], v[200:203], v[56:59]
	v_mfma_f32_16x16x32_bf16 v[44:47], v[132:135], v[208:211], v[44:47]
	v_mfma_f32_16x16x32_bf16 v[40:43], v[140:143], v[208:211], v[40:43]
	v_mfma_f32_16x16x32_bf16 v[28:31], v[132:135], v[216:219], v[28:31]
	v_mfma_f32_16x16x32_bf16 v[24:27], v[140:143], v[216:219], v[24:27]
	v_mfma_f32_16x16x32_bf16 v[12:15], v[132:135], v[224:227], v[12:15]
	v_mfma_f32_16x16x32_bf16 v[8:11], v[140:143], v[224:227], v[8:11]
	v_mfma_f32_16x16x32_bf16 v[52:55], v[164:167], v[196:199], v[52:55]
	v_mfma_f32_16x16x32_bf16 v[48:51], v[182:185], v[196:199], v[48:51]
	v_mfma_f32_16x16x32_bf16 v[36:39], v[164:167], v[204:207], v[36:39]
	v_mfma_f32_16x16x32_bf16 v[32:35], v[182:185], v[204:207], v[32:35]
	v_mfma_f32_16x16x32_bf16 v[20:23], v[164:167], v[212:215], v[20:23]
	v_mfma_f32_16x16x32_bf16 v[16:19], v[182:185], v[212:215], v[16:19]
	v_mfma_f32_16x16x32_bf16 v[4:7], v[164:167], v[220:223], v[4:7]
	v_mfma_f32_16x16x32_bf16 v[0:3], v[182:185], v[220:223], v[0:3]
	v_mfma_f32_16x16x32_bf16 v[52:55], v[178:181], v[200:203], v[52:55]
	v_mfma_f32_16x16x32_bf16 v[48:51], v[192:195], v[200:203], v[48:51]
	v_mfma_f32_16x16x32_bf16 v[36:39], v[178:181], v[208:211], v[36:39]
	v_mfma_f32_16x16x32_bf16 v[32:35], v[192:195], v[208:211], v[32:35]
	v_mfma_f32_16x16x32_bf16 v[20:23], v[178:181], v[216:219], v[20:23]
	v_mfma_f32_16x16x32_bf16 v[16:19], v[192:195], v[216:219], v[16:19]
	v_mfma_f32_16x16x32_bf16 v[4:7], v[178:181], v[224:227], v[4:7]
	v_mfma_f32_16x16x32_bf16 v[0:3], v[192:195], v[224:227], v[0:3]
	s_barrier
	s_setprio 0
	s_add_i32 s60, s60, 2
	s_add_u32 s2, s2, 0x100
	s_addc_u32 s3, s3, 0
	s_add_u32 s58, s58, 0x100
	s_addc_u32 s59, s59, 0
.LBB0_374:
	ds_read_b128 v[128:131], v171
	ds_read_b128 v[132:135], v171 offset:1024
	ds_read_b128 v[136:139], v171 offset:2048
	ds_read_b128 v[140:143], v171 offset:3072
	ds_read_b128 v[164:167], v172
	ds_read_b128 v[178:181], v172 offset:1024
	ds_read_b128 v[182:185], v172 offset:2048
	ds_read_b128 v[192:195], v172 offset:3072
	s_add_u32 s38, s2, 0xfffc0080
	s_addc_u32 s39, s3, -1
	s_cmp_eq_u32 s60, 12
	s_cselect_b32 s41, s1, s39
	s_cselect_b32 s40, s25, s38
	s_cselect_b32 s39, s29, s59
	s_cselect_b32 s38, s31, s58
	s_add_i32 m0, s44, 0xc000
	ds_read_b128 v[196:199], v173
	ds_read_b128 v[200:203], v173 offset:1024
	ds_read_b128 v[204:207], v173 offset:2048
	ds_read_b128 v[208:211], v173 offset:3072
	ds_read_b128 v[212:215], v173 offset:4096
	ds_read_b128 v[216:219], v173 offset:5120
	ds_read_b128 v[220:223], v173 offset:6144
	ds_read_b128 v[224:227], v173 offset:7168
	global_load_lds_dwordx4 v156, s[2:3]
	s_add_i32 m0, s44, 0xe000
	s_nop 0
	global_load_lds_dwordx4 v158, s[2:3]
	s_waitcnt vmcnt(8)
	s_waitcnt lgkmcnt(0)
	s_setprio 1
	s_barrier
; #define PG8_STAGE(bufoff, gbase, voff) do { _Pragma("unroll") for (int _i = 0; _i < 2; ++_i) \
;         __builtin_amdgcn_global_load_lds((const unsigned*)((const char*)(gbase) + (voff)[_i]), (PG8_LAS unsigned*)(lds + (bufoff) + ldsw + _i * 8192), 16, 0, 0); } while (0)
; #define PG8_LDA(dst, b, h) do { _Pragma("unroll") for (int m = 0; m < 4; ++m) _Pragma("unroll") for (int k = 0; k < 2; ++k) dst[m][k] = *(const PG8_LAS bf16x8*)(lds + PG8_SA(b, h) + aoff + m * 2048 + k * 1024); } while (0)
; #define PG8_MMA(ai, bj, At, Bt) do { __builtin_amdgcn_s_setprio(1); _Pragma("unroll") for (int m = 0; m < 4; ++m) _Pragma("unroll") for (int n = 0; n < 2; ++n) _Pragma("unroll") for (int k = 0; k < 2; ++k) \
;         acc[ai][bj][m][n] = __builtin_amdgcn_mfma_f32_16x16x32_bf16(Bt[n][k], At[m][k], acc[ai][bj][m][n], 0, 0, 0); __builtin_amdgcn_s_setprio(0); } while (0)
; #define PG8_WAIT_V(n) asm volatile("s_waitcnt vmcnt(" #n ")" ::: "memory")
; #define PG8_WAIT_L(n) asm volatile("s_waitcnt lgkmcnt(" #n ")" ::: "memory")
; #define PG8_BAR __builtin_amdgcn_s_barrier()
; #define PG8_SCHED __builtin_amdgcn_sched_barrier(0)
; template <class Epi, class Sched, bool ALIGN_EPI = false, bool SP2 = false>
; __device__ __forceinline__ void gemm_phase(PG8_LAS unsigned char* lds, const Gemm g, const Sched& S, const Epi& E) {
;     ...
;             PG8_WAIT_V(8); PG8_WAIT_L(0); PG8_BAR; PG8_MMA(0, 0, At, B0); PG8_MMA(0, 1, At, B1); PG8_BAR; PG8_SCHED;
;             PG8_LDA(At, 0, 1); PG8_STAGE(PG8_SB(0, 0), b2, voffB); PG8_STAGE(PG8_SB(0, 1), b2 + hstep, voffB); PG8_STAGE(PG8_SA(0, 0), a2, voffA);
;             PG8_WAIT_V(8); PG8_WAIT_L(0); PG8_BAR; PG8_MMA(1, 0, At, B0); PG8_MMA(1, 1, At, B1); PG8_BAR; PG8_SCHED;
	v_mfma_f32_16x16x32_bf16 v[124:127], v[128:131], v[196:199], v[124:127]
	v_mfma_f32_16x16x32_bf16 v[120:123], v[136:139], v[196:199], v[120:123]
	v_mfma_f32_16x16x32_bf16 v[108:111], v[128:131], v[204:207], v[108:111]
	v_mfma_f32_16x16x32_bf16 v[104:107], v[136:139], v[204:207], v[104:107]
	v_mfma_f32_16x16x32_bf16 v[92:95], v[128:131], v[212:215], v[92:95]
	v_mfma_f32_16x16x32_bf16 v[88:91], v[136:139], v[212:215], v[88:91]
	v_mfma_f32_16x16x32_bf16 v[76:79], v[128:131], v[220:223], v[76:79]
	v_mfma_f32_16x16x32_bf16 v[72:75], v[136:139], v[220:223], v[72:75]
	v_mfma_f32_16x16x32_bf16 v[124:127], v[132:135], v[200:203], v[124:127]
	v_mfma_f32_16x16x32_bf16 v[120:123], v[140:143], v[200:203], v[120:123]
	v_mfma_f32_16x16x32_bf16 v[108:111], v[132:135], v[208:211], v[108:111]
	v_mfma_f32_16x16x32_bf16 v[104:107], v[140:143], v[208:211], v[104:107]
	v_mfma_f32_16x16x32_bf16 v[92:95], v[132:135], v[216:219], v[92:95]
	v_mfma_f32_16x16x32_bf16 v[88:91], v[140:143], v[216:219], v[88:91]
	v_mfma_f32_16x16x32_bf16 v[76:79], v[132:135], v[224:227], v[76:79]
	v_mfma_f32_16x16x32_bf16 v[72:75], v[140:143], v[224:227], v[72:75]
	v_mfma_f32_16x16x32_bf16 v[116:119], v[164:167], v[196:199], v[116:119]
	v_mfma_f32_16x16x32_bf16 v[112:115], v[182:185], v[196:199], v[112:115]
	v_mfma_f32_16x16x32_bf16 v[100:103], v[164:167], v[204:207], v[100:103]
	v_mfma_f32_16x16x32_bf16 v[96:99], v[182:185], v[204:207], v[96:99]
	v_mfma_f32_16x16x32_bf16 v[84:87], v[164:167], v[212:215], v[84:87]
	v_mfma_f32_16x16x32_bf16 v[80:83], v[182:185], v[212:215], v[80:83]
	v_mfma_f32_16x16x32_bf16 v[68:71], v[164:167], v[220:223], v[68:71]
	v_mfma_f32_16x16x32_bf16 v[64:67], v[182:185], v[220:223], v[64:67]
	v_mfma_f32_16x16x32_bf16 v[116:119], v[178:181], v[200:203], v[116:119]
	v_mfma_f32_16x16x32_bf16 v[112:115], v[192:195], v[200:203], v[112:115]
	v_mfma_f32_16x16x32_bf16 v[100:103], v[178:181], v[208:211], v[100:103]
	v_mfma_f32_16x16x32_bf16 v[96:99], v[192:195], v[208:211], v[96:99]
	v_mfma_f32_16x16x32_bf16 v[84:87], v[178:181], v[216:219], v[84:87]
	v_mfma_f32_16x16x32_bf16 v[80:83], v[192:195], v[216:219], v[80:83]
	v_mfma_f32_16x16x32_bf16 v[68:71], v[178:181], v[224:227], v[68:71]
	v_mfma_f32_16x16x32_bf16 v[64:67], v[192:195], v[224:227], v[64:67]
	s_barrier
	s_setprio 0
	s_add_i32 s61, s52, s33
	v_lshl_add_u64 v[168:169], s[38:39], 0, v[148:149]
	s_mov_b32 m0, s61
	ds_read_b128 v[196:199], v173 offset:16384
	ds_read_b128 v[200:203], v173 offset:17408
	ds_read_b128 v[204:207], v173 offset:18432
	ds_read_b128 v[208:211], v173 offset:19456
	ds_read_b128 v[212:215], v173 offset:20480
	ds_read_b128 v[216:219], v173 offset:21504
	ds_read_b128 v[220:223], v173 offset:22528
	ds_read_b128 v[224:227], v173 offset:23552
	global_load_lds_dwordx4 v[168:169], off
	s_add_i32 m0, s61, 0x2000
	s_add_u32 s62, s38, 0x40000
	v_lshl_add_u64 v[186:187], s[38:39], 0, v[144:145]
	s_addc_u32 s63, s39, 0
	s_add_i32 s61, s53, s33
	global_load_lds_dwordx4 v[186:187], off
	s_mov_b32 m0, s61
	v_lshl_add_u64 v[230:231], s[40:41], 0, v[146:147]
	global_load_lds_dwordx4 v148, s[62:63]
	s_add_i32 m0, s61, 0x2000
	s_nop 0
	global_load_lds_dwordx4 v144, s[62:63]
	v_lshl_add_u64 v[228:229], s[40:41], 0, v[150:151]
	s_mov_b32 m0, s44
	s_nop 0
	global_load_lds_dwordx4 v[228:229], off
	s_mov_b32 m0, s45
	s_nop 0
	global_load_lds_dwordx4 v[230:231], off
	s_waitcnt vmcnt(8)
	s_waitcnt lgkmcnt(0)
	s_setprio 1
	s_barrier
	v_mfma_f32_16x16x32_bf16 v[60:63], v[128:131], v[196:199], v[60:63]
	v_mfma_f32_16x16x32_bf16 v[56:59], v[136:139], v[196:199], v[56:59]
	v_mfma_f32_16x16x32_bf16 v[44:47], v[128:131], v[204:207], v[44:47]
	v_mfma_f32_16x16x32_bf16 v[40:43], v[136:139], v[204:207], v[40:43]
	v_mfma_f32_16x16x32_bf16 v[28:31], v[128:131], v[212:215], v[28:31]
	v_mfma_f32_16x16x32_bf16 v[24:27], v[136:139], v[212:215], v[24:27]
	v_mfma_f32_16x16x32_bf16 v[12:15], v[128:131], v[220:223], v[12:15]
	v_mfma_f32_16x16x32_bf16 v[8:11], v[136:139], v[220:223], v[8:11]
	v_mfma_f32_16x16x32_bf16 v[60:63], v[132:135], v[200:203], v[60:63]
	v_mfma_f32_16x16x32_bf16 v[56:59], v[140:143], v[200:203], v[56:59]
	v_mfma_f32_16x16x32_bf16 v[44:47], v[132:135], v[208:211], v[44:47]
	v_mfma_f32_16x16x32_bf16 v[40:43], v[140:143], v[208:211], v[40:43]
	v_mfma_f32_16x16x32_bf16 v[28:31], v[132:135], v[216:219], v[28:31]
	v_mfma_f32_16x16x32_bf16 v[24:27], v[140:143], v[216:219], v[24:27]
	v_mfma_f32_16x16x32_bf16 v[12:15], v[132:135], v[224:227], v[12:15]
	v_mfma_f32_16x16x32_bf16 v[8:11], v[140:143], v[224:227], v[8:11]
	v_mfma_f32_16x16x32_bf16 v[52:55], v[164:167], v[196:199], v[52:55]
	v_mfma_f32_16x16x32_bf16 v[48:51], v[182:185], v[196:199], v[48:51]
	v_mfma_f32_16x16x32_bf16 v[36:39], v[164:167], v[204:207], v[36:39]
	v_mfma_f32_16x16x32_bf16 v[32:35], v[182:185], v[204:207], v[32:35]
	v_mfma_f32_16x16x32_bf16 v[20:23], v[164:167], v[212:215], v[20:23]
	v_mfma_f32_16x16x32_bf16 v[16:19], v[182:185], v[212:215], v[16:19]
	v_mfma_f32_16x16x32_bf16 v[4:7], v[164:167], v[220:223], v[4:7]
	v_mfma_f32_16x16x32_bf16 v[0:3], v[182:185], v[220:223], v[0:3]
	v_mfma_f32_16x16x32_bf16 v[52:55], v[178:181], v[200:203], v[52:55]
	v_mfma_f32_16x16x32_bf16 v[48:51], v[192:195], v[200:203], v[48:51]
	v_mfma_f32_16x16x32_bf16 v[36:39], v[178:181], v[208:211], v[36:39]
	v_mfma_f32_16x16x32_bf16 v[32:35], v[192:195], v[208:211], v[32:35]
	v_mfma_f32_16x16x32_bf16 v[20:23], v[178:181], v[216:219], v[20:23]
	v_mfma_f32_16x16x32_bf16 v[16:19], v[192:195], v[216:219], v[16:19]
	v_mfma_f32_16x16x32_bf16 v[4:7], v[178:181], v[224:227], v[4:7]
	v_mfma_f32_16x16x32_bf16 v[0:3], v[192:195], v[224:227], v[0:3]
	s_barrier
; #define PG8_STAGE(bufoff, gbase, voff) do { _Pragma("unroll") for (int _i = 0; _i < 2; ++_i) \
;         __builtin_amdgcn_global_load_lds((const unsigned*)((const char*)(gbase) + (voff)[_i]), (PG8_LAS unsigned*)(lds + (bufoff) + ldsw + _i * 8192), 16, 0, 0); } while (0)
; #define PG8_LDA(dst, b, h) do { _Pragma("unroll") for (int m = 0; m < 4; ++m) _Pragma("unroll") for (int k = 0; k < 2; ++k) dst[m][k] = *(const PG8_LAS bf16x8*)(lds + PG8_SA(b, h) + aoff + m * 2048 + k * 1024); } while (0)
; #define PG8_LDB(dst, b, h) do { _Pragma("unroll") for (int n = 0; n < 2; ++n) _Pragma("unroll") for (int k = 0; k < 2; ++k) dst[n][k] = *(const PG8_LAS bf16x8*)(lds + PG8_SB(b, h) + boff + n * 2048 + k * 1024); } while (0)
; #define PG8_MMA(ai, bj, At, Bt) do { __builtin_amdgcn_s_setprio(1); _Pragma("unroll") for (int m = 0; m < 4; ++m) _Pragma("unroll") for (int n = 0; n < 2; ++n) _Pragma("unroll") for (int k = 0; k < 2; ++k) \
;         acc[ai][bj][m][n] = __builtin_amdgcn_mfma_f32_16x16x32_bf16(Bt[n][k], At[m][k], acc[ai][bj][m][n], 0, 0, 0); __builtin_amdgcn_s_setprio(0); } while (0)
; #define PG8_WAIT_V(n) asm volatile("s_waitcnt vmcnt(" #n ")" ::: "memory")
; #define PG8_WAIT_L(n) asm volatile("s_waitcnt lgkmcnt(" #n ")" ::: "memory")
; #define PG8_BAR __builtin_amdgcn_s_barrier()
; #define PG8_SCHED __builtin_amdgcn_sched_barrier(0)
; template <class Epi, class Sched, bool ALIGN_EPI = false, bool SP2 = false>
; __device__ __forceinline__ void gemm_phase(PG8_LAS unsigned char* lds, const Gemm g, const Sched& S, const Epi& E) {
;     ...
;             PG8_LDB(B0, 1, 0); PG8_LDB(B1, 1, 1); PG8_SCHED; PG8_LDA(At, 1, 0); PG8_STAGE(PG8_SA(0, 1), a2 + hstep, voffA);
;             PG8_WAIT_V(8); PG8_WAIT_L(0); PG8_BAR; PG8_MMA(0, 0, At, B0); PG8_MMA(0, 1, At, B1); PG8_BAR; PG8_SCHED;
	s_setprio 0
	s_add_i32 s61, 0, 0x18000
	s_add_i32 s62, 0, 0x1c000
	v_add_u32_e32 v140, s61, v170
	v_add_u32_e32 v152, s62, v170
	ds_read_b128 v[128:131], v140
	ds_read_b128 v[132:135], v140 offset:1024
	ds_read_b128 v[136:139], v140 offset:2048
	ds_read_b128 v[140:143], v140 offset:3072
	ds_read_b128 v[164:167], v152
	ds_read_b128 v[178:181], v152 offset:1024
	ds_read_b128 v[182:185], v152 offset:2048
	ds_read_b128 v[192:195], v152 offset:3072
	s_add_u32 s40, s40, 0x40000
	s_addc_u32 s41, s41, 0
	s_mov_b32 m0, s46
	ds_read_b128 v[196:199], v173 offset:32768
	ds_read_b128 v[200:203], v173 offset:33792
	ds_read_b128 v[204:207], v173 offset:34816
	ds_read_b128 v[208:211], v173 offset:35840
	ds_read_b128 v[212:215], v173 offset:36864
	ds_read_b128 v[216:219], v173 offset:37888
	ds_read_b128 v[220:223], v173 offset:38912
	ds_read_b128 v[224:227], v173 offset:39936
	global_load_lds_dwordx4 v150, s[40:41]
	v_lshl_add_u64 v[232:233], s[40:41], 0, v[146:147]
	s_mov_b32 m0, s47
	s_nop 0
	global_load_lds_dwordx4 v[232:233], off
	s_waitcnt vmcnt(8)
	s_waitcnt lgkmcnt(0)
	s_setprio 1
	s_barrier
	v_mfma_f32_16x16x32_bf16 v[124:127], v[128:131], v[196:199], v[124:127]
	v_mfma_f32_16x16x32_bf16 v[120:123], v[136:139], v[196:199], v[120:123]
	v_mfma_f32_16x16x32_bf16 v[108:111], v[128:131], v[204:207], v[108:111]
	v_mfma_f32_16x16x32_bf16 v[104:107], v[136:139], v[204:207], v[104:107]
	v_mfma_f32_16x16x32_bf16 v[92:95], v[128:131], v[212:215], v[92:95]
	v_mfma_f32_16x16x32_bf16 v[88:91], v[136:139], v[212:215], v[88:91]
	v_mfma_f32_16x16x32_bf16 v[76:79], v[128:131], v[220:223], v[76:79]
	v_mfma_f32_16x16x32_bf16 v[72:75], v[136:139], v[220:223], v[72:75]
	v_mfma_f32_16x16x32_bf16 v[124:127], v[132:135], v[200:203], v[124:127]
	v_mfma_f32_16x16x32_bf16 v[120:123], v[140:143], v[200:203], v[120:123]
	v_mfma_f32_16x16x32_bf16 v[108:111], v[132:135], v[208:211], v[108:111]
	v_mfma_f32_16x16x32_bf16 v[104:107], v[140:143], v[208:211], v[104:107]
	v_mfma_f32_16x16x32_bf16 v[92:95], v[132:135], v[216:219], v[92:95]
	v_mfma_f32_16x16x32_bf16 v[88:91], v[140:143], v[216:219], v[88:91]
	v_mfma_f32_16x16x32_bf16 v[76:79], v[132:135], v[224:227], v[76:79]
	v_mfma_f32_16x16x32_bf16 v[72:75], v[140:143], v[224:227], v[72:75]
	v_mfma_f32_16x16x32_bf16 v[116:119], v[164:167], v[196:199], v[116:119]
	v_mfma_f32_16x16x32_bf16 v[112:115], v[182:185], v[196:199], v[112:115]
	v_mfma_f32_16x16x32_bf16 v[100:103], v[164:167], v[204:207], v[100:103]
	v_mfma_f32_16x16x32_bf16 v[96:99], v[182:185], v[204:207], v[96:99]
	v_mfma_f32_16x16x32_bf16 v[84:87], v[164:167], v[212:215], v[84:87]
	v_mfma_f32_16x16x32_bf16 v[80:83], v[182:185], v[212:215], v[80:83]
	v_mfma_f32_16x16x32_bf16 v[68:71], v[164:167], v[220:223], v[68:71]
	v_mfma_f32_16x16x32_bf16 v[64:67], v[182:185], v[220:223], v[64:67]
	v_mfma_f32_16x16x32_bf16 v[116:119], v[178:181], v[200:203], v[116:119]
	v_mfma_f32_16x16x32_bf16 v[112:115], v[192:195], v[200:203], v[112:115]
	v_mfma_f32_16x16x32_bf16 v[100:103], v[178:181], v[208:211], v[100:103]
	v_mfma_f32_16x16x32_bf16 v[96:99], v[192:195], v[208:211], v[96:99]
	v_mfma_f32_16x16x32_bf16 v[84:87], v[178:181], v[216:219], v[84:87]
	v_mfma_f32_16x16x32_bf16 v[80:83], v[192:195], v[216:219], v[80:83]
	v_mfma_f32_16x16x32_bf16 v[68:71], v[178:181], v[224:227], v[68:71]
	v_mfma_f32_16x16x32_bf16 v[64:67], v[192:195], v[224:227], v[64:67]
	s_barrier
; #define PG8_STAGE(bufoff, gbase, voff) do { _Pragma("unroll") for (int _i = 0; _i < 2; ++_i) \
;         __builtin_amdgcn_global_load_lds((const unsigned*)((const char*)(gbase) + (voff)[_i]), (PG8_LAS unsigned*)(lds + (bufoff) + ldsw + _i * 8192), 16, 0, 0); } while (0)
; #define PG8_LDA(dst, b, h) do { _Pragma("unroll") for (int m = 0; m < 4; ++m) _Pragma("unroll") for (int k = 0; k < 2; ++k) dst[m][k] = *(const PG8_LAS bf16x8*)(lds + PG8_SA(b, h) + aoff + m * 2048 + k * 1024); } while (0)
; #define PG8_MMA(ai, bj, At, Bt) do { __builtin_amdgcn_s_setprio(1); _Pragma("unroll") for (int m = 0; m < 4; ++m) _Pragma("unroll") for (int n = 0; n < 2; ++n) _Pragma("unroll") for (int k = 0; k < 2; ++k) \
;         acc[ai][bj][m][n] = __builtin_amdgcn_mfma_f32_16x16x32_bf16(Bt[n][k], At[m][k], acc[ai][bj][m][n], 0, 0, 0); __builtin_amdgcn_s_setprio(0); } while (0)
; #define PG8_WAIT_V(n) asm volatile("s_waitcnt vmcnt(" #n ")" ::: "memory")
; #define PG8_WAIT_L(n) asm volatile("s_waitcnt lgkmcnt(" #n ")" ::: "memory")
; #define PG8_BAR __builtin_amdgcn_s_barrier()
; #define PG8_SCHED __builtin_amdgcn_sched_barrier(0)
; template <class Epi, class Sched, bool ALIGN_EPI = false, bool SP2 = false>
; __device__ __forceinline__ void gemm_phase(PG8_LAS unsigned char* lds, const Gemm g, const Sched& S, const Epi& E) {
;     ...
;             PG8_LDA(At, 1, 1); PG8_STAGE(PG8_SB(1, 0), b3, voffB); PG8_STAGE(PG8_SB(1, 1), b3 + hstep, voffB); PG8_STAGE(PG8_SA(1, 0), a3, voffA);
;             PG8_WAIT_V(8); PG8_WAIT_L(0); PG8_BAR; PG8_MMA(1, 0, At, B0); PG8_MMA(1, 1, At, B1); PG8_BAR; PG8_SCHED;
;     __device__ __forceinline__ void operator()(const f32x4 (&acc)[2][2][4][2], const pg8::Unit& u, int wr, int wc, int fr, int fq) const {
;     ...
;         if (u.pn < 4) {
	s_setprio 0
	s_add_i32 s40, s61, s33
	v_lshl_add_u64 v[168:169], v[168:169], 0, s[16:17]
	s_mov_b32 m0, s40
	ds_read_b128 v[196:199], v173 offset:49152
	ds_read_b128 v[200:203], v173 offset:50176
	ds_read_b128 v[204:207], v173 offset:51200
	ds_read_b128 v[208:211], v173 offset:52224
	ds_read_b128 v[212:215], v173 offset:53248
	ds_read_b128 v[216:219], v173 offset:54272
	ds_read_b128 v[220:223], v173 offset:55296
	ds_read_b128 v[224:227], v173 offset:56320
	global_load_lds_dwordx4 v[168:169], off
	s_add_i32 m0, s40, 0x2000
	s_add_u32 s38, s38, 0x40080
	v_lshl_add_u64 v[168:169], v[186:187], 0, s[16:17]
	s_addc_u32 s39, s39, 0
	s_add_i32 s40, s62, s33
	global_load_lds_dwordx4 v[168:169], off
	s_mov_b32 m0, s40
	s_nop 0
	global_load_lds_dwordx4 v148, s[38:39]
	s_add_i32 m0, s40, 0x2000
	s_nop 0
	global_load_lds_dwordx4 v144, s[38:39]
	v_lshl_add_u64 v[168:169], v[228:229], 0, s[16:17]
	s_mov_b32 m0, s48
	s_nop 0
	global_load_lds_dwordx4 v[168:169], off
	v_lshl_add_u64 v[168:169], v[230:231], 0, s[16:17]
	s_mov_b32 m0, s49
	s_nop 0
	global_load_lds_dwordx4 v[168:169], off
	s_waitcnt vmcnt(8)
	s_waitcnt lgkmcnt(0)
	s_setprio 1
	s_barrier
	v_mfma_f32_16x16x32_bf16 v[60:63], v[128:131], v[196:199], v[60:63]
	v_mfma_f32_16x16x32_bf16 v[56:59], v[136:139], v[196:199], v[56:59]
	v_mfma_f32_16x16x32_bf16 v[44:47], v[128:131], v[204:207], v[44:47]
	v_mfma_f32_16x16x32_bf16 v[40:43], v[136:139], v[204:207], v[40:43]
	v_mfma_f32_16x16x32_bf16 v[28:31], v[128:131], v[212:215], v[28:31]
	v_mfma_f32_16x16x32_bf16 v[24:27], v[136:139], v[212:215], v[24:27]
	v_mfma_f32_16x16x32_bf16 v[12:15], v[128:131], v[220:223], v[12:15]
	v_mfma_f32_16x16x32_bf16 v[8:11], v[136:139], v[220:223], v[8:11]
	v_mfma_f32_16x16x32_bf16 v[60:63], v[132:135], v[200:203], v[60:63]
	v_mfma_f32_16x16x32_bf16 v[56:59], v[140:143], v[200:203], v[56:59]
	v_mfma_f32_16x16x32_bf16 v[44:47], v[132:135], v[208:211], v[44:47]
	v_mfma_f32_16x16x32_bf16 v[40:43], v[140:143], v[208:211], v[40:43]
	v_mfma_f32_16x16x32_bf16 v[28:31], v[132:135], v[216:219], v[28:31]
	v_mfma_f32_16x16x32_bf16 v[24:27], v[140:143], v[216:219], v[24:27]
	v_mfma_f32_16x16x32_bf16 v[12:15], v[132:135], v[224:227], v[12:15]
	v_mfma_f32_16x16x32_bf16 v[8:11], v[140:143], v[224:227], v[8:11]
	v_mfma_f32_16x16x32_bf16 v[52:55], v[164:167], v[196:199], v[52:55]
	v_mfma_f32_16x16x32_bf16 v[48:51], v[182:185], v[196:199], v[48:51]
	v_mfma_f32_16x16x32_bf16 v[36:39], v[164:167], v[204:207], v[36:39]
	v_mfma_f32_16x16x32_bf16 v[32:35], v[182:185], v[204:207], v[32:35]
	v_mfma_f32_16x16x32_bf16 v[20:23], v[164:167], v[212:215], v[20:23]
	v_mfma_f32_16x16x32_bf16 v[16:19], v[182:185], v[212:215], v[16:19]
	v_mfma_f32_16x16x32_bf16 v[4:7], v[164:167], v[220:223], v[4:7]
	v_mfma_f32_16x16x32_bf16 v[0:3], v[182:185], v[220:223], v[0:3]
	v_mfma_f32_16x16x32_bf16 v[52:55], v[178:181], v[200:203], v[52:55]
	v_mfma_f32_16x16x32_bf16 v[48:51], v[192:195], v[200:203], v[48:51]
	v_mfma_f32_16x16x32_bf16 v[36:39], v[178:181], v[208:211], v[36:39]
	v_mfma_f32_16x16x32_bf16 v[32:35], v[192:195], v[208:211], v[32:35]
	v_mfma_f32_16x16x32_bf16 v[20:23], v[178:181], v[216:219], v[20:23]
	v_mfma_f32_16x16x32_bf16 v[16:19], v[192:195], v[216:219], v[16:19]
	v_mfma_f32_16x16x32_bf16 v[4:7], v[178:181], v[224:227], v[4:7]
	v_mfma_f32_16x16x32_bf16 v[0:3], v[192:195], v[224:227], v[0:3]
	s_barrier
	s_setprio 0
	s_add_i32 s60, s60, 2
	s_add_u32 s2, s2, 0x100
	s_addc_u32 s3, s3, 0
	s_add_u32 s58, s58, 0x100
	s_addc_u32 s59, s59, 0
	s_cmp_gt_u32 s60, 13
	s_cbranch_scc0 .LBB0_374
	s_and_b64 vcc, exec, s[18:19]
	s_cbranch_vccnz .LBB0_379
	v_lshl_add_u32 v164, s0, 8, v155
	s_cmp_gt_i32 s57, 3
	s_mov_b64 s[0:1], -1
	s_cbranch_scc1 .LBB0_380

; #define PG8_STAGE(bufoff, gbase, voff) do { _Pragma("unroll") for (int _i = 0; _i < 2; ++_i) \
;         __builtin_amdgcn_global_load_lds((const unsigned*)((const char*)(gbase) + (voff)[_i]), (PG8_LAS unsigned*)(lds + (bufoff) + ldsw + _i * 8192), 16, 0, 0); } while (0)
; #define PG8_LDA(dst, b, h) do { _Pragma("unroll") for (int m = 0; m < 4; ++m) _Pragma("unroll") for (int k = 0; k < 2; ++k) dst[m][k] = *(const PG8_LAS bf16x8*)(lds + PG8_SA(b, h) + aoff + m * 2048 + k * 1024); } while (0)
; #define PG8_LDB(dst, b, h) do { _Pragma("unroll") for (int n = 0; n < 2; ++n) _Pragma("unroll") for (int k = 0; k < 2; ++k) dst[n][k] = *(const PG8_LAS bf16x8*)(lds + PG8_SB(b, h) + boff + n * 2048 + k * 1024); } while (0)
; #define PG8_WAIT_V(n) asm volatile("s_waitcnt vmcnt(" #n ")" ::: "memory")
; #define PG8_WAIT_L(n) asm volatile("s_waitcnt lgkmcnt(" #n ")" ::: "memory")
; #define PG8_BAR __builtin_amdgcn_s_barrier()
; #define PG8_SCHED __builtin_amdgcn_sched_barrier(0)
; template <class Epi, class Sched, bool ALIGN_EPI = false, bool SP2 = false>
; __device__ __forceinline__ void gemm_phase(PG8_LAS unsigned char* lds, const Gemm g, const Sched& S, const Epi& E) {
;     ...
;         const bool has_next = S.next(ui + 1, nxt);
;         const char* nA = has_next ? (const char*)g.A + (size_t)nxt.pm * tstep : cA; const char* nB = has_next ? (const char*)g.Bt + (size_t)nxt.pn * tstep : cB;
;         for (int t = 0; t < nt; t += 2) {
;             const bool last = (t == nt - 2);
;             const char* a1 = cA + (size_t)(t + 1) * kstep;
;             const char* a2 = last ? nA : cA + (size_t)(t + 2) * kstep; const char* b2 = last ? nB : cB + (size_t)(t + 2) * kstep;
;             const char* a3 = a2 + kstep; const char* b3 = b2 + kstep;
;             if (last && has_next) S.a_ready(nxt);
;             if constexpr (SP2) {
;             PG8_LDB(B0, 0, 0); PG8_LDB(B1, 0, 1); PG8_SCHED; PG8_LDA(At, 0, 0); PG8_STAGE(PG8_SA(1, 1), a1 + hstep, voffA);
;             PG8_WAIT_V(8); PG8_WAIT_L(0); PG8_BAR; PG8_MMA(0, 0, At, B0); PG8_MMA(0, 1, At, B1); PG8_BAR; PG8_SCHED;
;             PG8_LDA(At, 0, 1); PG8_STAGE(PG8_SB(0, 0), b2, voffB); PG8_STAGE(PG8_SB(0, 1), b2 + hstep, voffB); PG8_STAGE(PG8_SA(0, 0), a2, voffA);
;             PG8_WAIT_V(8); PG8_WAIT_L(0); PG8_BAR; PG8_MMA(1, 0, At, B0); PG8_MMA(1, 1, At, B1); PG8_BAR; PG8_SCHED;
.LBB0_697:
	s_ashr_i32 s17, s16, 31
	s_lshl_b64 s[18:19], s[16:17], 19
	v_readlane_b32 s48, v235, 2
	v_readlane_b32 s49, v235, 3
	s_add_u32 s18, s48, s18
	s_addc_u32 s19, s49, s19
	s_and_b64 s[20:21], s[6:7], exec
	s_cselect_b32 s17, s19, s27
	s_cselect_b32 s23, s18, s26
	s_ashr_i32 s15, s14, 31
	s_lshl_b64 s[20:21], s[14:15], 19
	s_add_u32 s20, s33, s20
	s_addc_u32 s21, s34, s21
	s_and_b64 s[30:31], s[6:7], exec
	s_cselect_b32 s15, s21, s29
	s_cselect_b32 s47, s20, s28
	s_add_u32 s26, s26, 0x40080
	s_addc_u32 s27, s27, 0
	v_readlane_b32 s50, v235, 4
	s_add_u32 s48, s28, 0x100
	s_addc_u32 s49, s29, 0
	s_mov_b32 s50, -2
	s_waitcnt lgkmcnt(0)
	v_readlane_b32 s51, v235, 5
	ds_read_b128 v[144:147], v151
	ds_read_b128 v[156:159], v151 offset:1024
	ds_read_b128 v[160:163], v151 offset:2048
	ds_read_b128 v[164:167], v151 offset:3072
	ds_read_b128 v[168:171], v152
	ds_read_b128 v[172:175], v152 offset:1024
	ds_read_b128 v[176:179], v152 offset:2048
	ds_read_b128 v[180:183], v152 offset:3072
	s_add_u32 s28, s26, 0xfffc0080
	s_addc_u32 s29, s27, -1
	s_cmp_eq_u32 s50, 12
	s_cselect_b32 s31, s17, s29
	s_cselect_b32 s30, s23, s28
	s_cselect_b32 s29, s15, s49
	s_cselect_b32 s28, s47, s48
	s_add_i32 m0, s25, 0xc000
	ds_read_b128 v[184:187], v153
	ds_read_b128 v[190:193], v153 offset:1024
	ds_read_b128 v[194:197], v153 offset:2048
	ds_read_b128 v[198:201], v153 offset:3072
	ds_read_b128 v[202:205], v153 offset:4096
	ds_read_b128 v[206:209], v153 offset:5120
	ds_read_b128 v[210:213], v153 offset:6144
	ds_read_b128 v[214:217], v153 offset:7168
	global_load_lds_dwordx4 v136, s[26:27]
	s_add_i32 m0, s25, 0xe000
	s_nop 0
	global_load_lds_dwordx4 v138, s[26:27]
	s_waitcnt vmcnt(8)
	s_waitcnt lgkmcnt(0)
	s_setprio 1
	s_barrier
	v_mfma_f32_16x16x32_bf16 v[124:127], v[144:147], v[184:187], 0
	v_mfma_f32_16x16x32_bf16 v[120:123], v[160:163], v[184:187], 0
	v_mfma_f32_16x16x32_bf16 v[108:111], v[144:147], v[194:197], 0
	v_mfma_f32_16x16x32_bf16 v[104:107], v[160:163], v[194:197], 0
	v_mfma_f32_16x16x32_bf16 v[92:95], v[144:147], v[202:205], 0
	v_mfma_f32_16x16x32_bf16 v[88:91], v[160:163], v[202:205], 0
	v_mfma_f32_16x16x32_bf16 v[76:79], v[144:147], v[210:213], 0
	v_mfma_f32_16x16x32_bf16 v[72:75], v[160:163], v[210:213], 0
	v_mfma_f32_16x16x32_bf16 v[124:127], v[156:159], v[190:193], v[124:127]
	v_mfma_f32_16x16x32_bf16 v[120:123], v[164:167], v[190:193], v[120:123]
	v_mfma_f32_16x16x32_bf16 v[108:111], v[156:159], v[198:201], v[108:111]
	v_mfma_f32_16x16x32_bf16 v[104:107], v[164:167], v[198:201], v[104:107]
	v_mfma_f32_16x16x32_bf16 v[92:95], v[156:159], v[206:209], v[92:95]
	v_mfma_f32_16x16x32_bf16 v[88:91], v[164:167], v[206:209], v[88:91]
	v_mfma_f32_16x16x32_bf16 v[76:79], v[156:159], v[214:217], v[76:79]
	v_mfma_f32_16x16x32_bf16 v[72:75], v[164:167], v[214:217], v[72:75]
	v_mfma_f32_16x16x32_bf16 v[116:119], v[168:171], v[184:187], 0
	v_mfma_f32_16x16x32_bf16 v[112:115], v[176:179], v[184:187], 0
	v_mfma_f32_16x16x32_bf16 v[100:103], v[168:171], v[194:197], 0
	v_mfma_f32_16x16x32_bf16 v[96:99], v[176:179], v[194:197], 0
	v_mfma_f32_16x16x32_bf16 v[84:87], v[168:171], v[202:205], 0
	v_mfma_f32_16x16x32_bf16 v[80:83], v[176:179], v[202:205], 0
	v_mfma_f32_16x16x32_bf16 v[68:71], v[168:171], v[210:213], 0
	v_mfma_f32_16x16x32_bf16 v[64:67], v[176:179], v[210:213], 0
	v_mfma_f32_16x16x32_bf16 v[116:119], v[172:175], v[190:193], v[116:119]
	v_mfma_f32_16x16x32_bf16 v[112:115], v[180:183], v[190:193], v[112:115]
	v_mfma_f32_16x16x32_bf16 v[100:103], v[172:175], v[198:201], v[100:103]
	v_mfma_f32_16x16x32_bf16 v[96:99], v[180:183], v[198:201], v[96:99]
	v_mfma_f32_16x16x32_bf16 v[84:87], v[172:175], v[206:209], v[84:87]
	v_mfma_f32_16x16x32_bf16 v[80:83], v[180:183], v[206:209], v[80:83]
	v_mfma_f32_16x16x32_bf16 v[68:71], v[172:175], v[214:217], v[68:71]
	v_mfma_f32_16x16x32_bf16 v[64:67], v[180:183], v[214:217], v[64:67]
	s_barrier
	s_setprio 0
	s_add_i32 s51, s45, s35
	v_lshl_add_u64 v[218:219], s[28:29], 0, v[130:131]
	s_mov_b32 m0, s51
	ds_read_b128 v[184:187], v153 offset:16384
	ds_read_b128 v[190:193], v153 offset:17408
	ds_read_b128 v[194:197], v153 offset:18432
	ds_read_b128 v[198:201], v153 offset:19456
	ds_read_b128 v[202:205], v153 offset:20480
	ds_read_b128 v[206:209], v153 offset:21504
	ds_read_b128 v[210:213], v153 offset:22528
	ds_read_b128 v[214:217], v153 offset:23552
	global_load_lds_dwordx4 v[218:219], off
	s_add_i32 m0, s51, 0x2000
	s_add_u32 s52, s28, 0x40000
	v_lshl_add_u64 v[220:221], s[28:29], 0, v[134:135]
	s_addc_u32 s53, s29, 0
	s_add_i32 s51, s46, s35
	global_load_lds_dwordx4 v[220:221], off
	s_mov_b32 m0, s51
	v_lshl_add_u64 v[224:225], s[30:31], 0, v[132:133]
	global_load_lds_dwordx4 v130, s[52:53]
	s_add_i32 m0, s51, 0x2000
	s_nop 0
	global_load_lds_dwordx4 v134, s[52:53]
	v_lshl_add_u64 v[222:223], s[30:31], 0, v[128:129]
	s_mov_b32 m0, s25
	s_nop 0
	global_load_lds_dwordx4 v[222:223], off
	s_mov_b32 m0, s36
	s_nop 0
	global_load_lds_dwordx4 v[224:225], off
	s_waitcnt vmcnt(8)
	s_waitcnt lgkmcnt(0)
	s_setprio 1
	s_barrier
; #define PG8_STAGE(bufoff, gbase, voff) do { _Pragma("unroll") for (int _i = 0; _i < 2; ++_i) \
;         __builtin_amdgcn_global_load_lds((const unsigned*)((const char*)(gbase) + (voff)[_i]), (PG8_LAS unsigned*)(lds + (bufoff) + ldsw + _i * 8192), 16, 0, 0); } while (0)
; #define PG8_LDA(dst, b, h) do { _Pragma("unroll") for (int m = 0; m < 4; ++m) _Pragma("unroll") for (int k = 0; k < 2; ++k) dst[m][k] = *(const PG8_LAS bf16x8*)(lds + PG8_SA(b, h) + aoff + m * 2048 + k * 1024); } while (0)
; #define PG8_LDB(dst, b, h) do { _Pragma("unroll") for (int n = 0; n < 2; ++n) _Pragma("unroll") for (int k = 0; k < 2; ++k) dst[n][k] = *(const PG8_LAS bf16x8*)(lds + PG8_SB(b, h) + boff + n * 2048 + k * 1024); } while (0)
; #define PG8_MMA(ai, bj, At, Bt) do { __builtin_amdgcn_s_setprio(1); _Pragma("unroll") for (int m = 0; m < 4; ++m) _Pragma("unroll") for (int n = 0; n < 2; ++n) _Pragma("unroll") for (int k = 0; k < 2; ++k) \
;         acc[ai][bj][m][n] = __builtin_amdgcn_mfma_f32_16x16x32_bf16(Bt[n][k], At[m][k], acc[ai][bj][m][n], 0, 0, 0); __builtin_amdgcn_s_setprio(0); } while (0)
; #define PG8_WAIT_V(n) asm volatile("s_waitcnt vmcnt(" #n ")" ::: "memory")
; #define PG8_WAIT_L(n) asm volatile("s_waitcnt lgkmcnt(" #n ")" ::: "memory")
; #define PG8_BAR __builtin_amdgcn_s_barrier()
; #define PG8_SCHED __builtin_amdgcn_sched_barrier(0)
; template <class Epi, class Sched, bool ALIGN_EPI = false, bool SP2 = false>
; __device__ __forceinline__ void gemm_phase(PG8_LAS unsigned char* lds, const Gemm g, const Sched& S, const Epi& E) {
;     ...
;             PG8_WAIT_V(8); PG8_WAIT_L(0); PG8_BAR; PG8_MMA(1, 0, At, B0); PG8_MMA(1, 1, At, B1); PG8_BAR; PG8_SCHED;
;             PG8_LDB(B0, 1, 0); PG8_LDB(B1, 1, 1); PG8_SCHED; PG8_LDA(At, 1, 0); PG8_STAGE(PG8_SA(0, 1), a2 + hstep, voffA);
;             PG8_WAIT_V(8); PG8_WAIT_L(0); PG8_BAR; PG8_MMA(0, 0, At, B0); PG8_MMA(0, 1, At, B1); PG8_BAR; PG8_SCHED;
	v_mfma_f32_16x16x32_bf16 v[60:63], v[144:147], v[184:187], 0
	v_mfma_f32_16x16x32_bf16 v[56:59], v[160:163], v[184:187], 0
	v_mfma_f32_16x16x32_bf16 v[44:47], v[144:147], v[194:197], 0
	v_mfma_f32_16x16x32_bf16 v[40:43], v[160:163], v[194:197], 0
	v_mfma_f32_16x16x32_bf16 v[28:31], v[144:147], v[202:205], 0
	v_mfma_f32_16x16x32_bf16 v[24:27], v[160:163], v[202:205], 0
	v_mfma_f32_16x16x32_bf16 v[12:15], v[144:147], v[210:213], 0
	v_mfma_f32_16x16x32_bf16 v[8:11], v[160:163], v[210:213], 0
	v_mfma_f32_16x16x32_bf16 v[60:63], v[156:159], v[190:193], v[60:63]
	v_mfma_f32_16x16x32_bf16 v[56:59], v[164:167], v[190:193], v[56:59]
	v_mfma_f32_16x16x32_bf16 v[44:47], v[156:159], v[198:201], v[44:47]
	v_mfma_f32_16x16x32_bf16 v[40:43], v[164:167], v[198:201], v[40:43]
	v_mfma_f32_16x16x32_bf16 v[28:31], v[156:159], v[206:209], v[28:31]
	v_mfma_f32_16x16x32_bf16 v[24:27], v[164:167], v[206:209], v[24:27]
	v_mfma_f32_16x16x32_bf16 v[12:15], v[156:159], v[214:217], v[12:15]
	v_mfma_f32_16x16x32_bf16 v[8:11], v[164:167], v[214:217], v[8:11]
	v_mfma_f32_16x16x32_bf16 v[52:55], v[168:171], v[184:187], 0
	v_mfma_f32_16x16x32_bf16 v[48:51], v[176:179], v[184:187], 0
	v_mfma_f32_16x16x32_bf16 v[36:39], v[168:171], v[194:197], 0
	v_mfma_f32_16x16x32_bf16 v[32:35], v[176:179], v[194:197], 0
	v_mfma_f32_16x16x32_bf16 v[20:23], v[168:171], v[202:205], 0
	v_mfma_f32_16x16x32_bf16 v[16:19], v[176:179], v[202:205], 0
	v_mfma_f32_16x16x32_bf16 v[4:7], v[168:171], v[210:213], 0
	v_mfma_f32_16x16x32_bf16 v[0:3], v[176:179], v[210:213], 0
	v_mfma_f32_16x16x32_bf16 v[52:55], v[172:175], v[190:193], v[52:55]
	v_mfma_f32_16x16x32_bf16 v[48:51], v[180:183], v[190:193], v[48:51]
	v_mfma_f32_16x16x32_bf16 v[36:39], v[172:175], v[198:201], v[36:39]
	v_mfma_f32_16x16x32_bf16 v[32:35], v[180:183], v[198:201], v[32:35]
	v_mfma_f32_16x16x32_bf16 v[20:23], v[172:175], v[206:209], v[20:23]
	v_mfma_f32_16x16x32_bf16 v[16:19], v[180:183], v[206:209], v[16:19]
	v_mfma_f32_16x16x32_bf16 v[4:7], v[172:175], v[214:217], v[4:7]
	v_mfma_f32_16x16x32_bf16 v[0:3], v[180:183], v[214:217], v[0:3]
	s_barrier
	s_setprio 0
	s_add_i32 s51, 0, 0x18000
	v_add_u32_e32 v155, s51, v149
	s_add_i32 s52, 0, 0x1c000
	ds_read_b128 v[144:147], v155
	ds_read_b128 v[156:159], v155 offset:1024
	ds_read_b128 v[160:163], v155 offset:2048
	ds_read_b128 v[164:167], v155 offset:3072
	v_add_u32_e32 v155, s52, v149
	ds_read_b128 v[168:171], v155
	ds_read_b128 v[172:175], v155 offset:1024
	ds_read_b128 v[176:179], v155 offset:2048
	ds_read_b128 v[180:183], v155 offset:3072
	s_add_u32 s30, s30, 0x40000
	s_addc_u32 s31, s31, 0
	s_mov_b32 m0, s37
	ds_read_b128 v[184:187], v153 offset:32768
	ds_read_b128 v[190:193], v153 offset:33792
	ds_read_b128 v[194:197], v153 offset:34816
	ds_read_b128 v[198:201], v153 offset:35840
	ds_read_b128 v[202:205], v153 offset:36864
	ds_read_b128 v[206:209], v153 offset:37888
	ds_read_b128 v[210:213], v153 offset:38912
	ds_read_b128 v[214:217], v153 offset:39936
	global_load_lds_dwordx4 v128, s[30:31]
	v_lshl_add_u64 v[226:227], s[30:31], 0, v[132:133]
	s_mov_b32 m0, s38
	s_nop 0
	global_load_lds_dwordx4 v[226:227], off
	s_waitcnt vmcnt(8)
	s_waitcnt lgkmcnt(0)
	s_setprio 1
	s_barrier
	v_mfma_f32_16x16x32_bf16 v[124:127], v[144:147], v[184:187], v[124:127]
	v_mfma_f32_16x16x32_bf16 v[120:123], v[160:163], v[184:187], v[120:123]
	v_mfma_f32_16x16x32_bf16 v[108:111], v[144:147], v[194:197], v[108:111]
	v_mfma_f32_16x16x32_bf16 v[104:107], v[160:163], v[194:197], v[104:107]
	v_mfma_f32_16x16x32_bf16 v[92:95], v[144:147], v[202:205], v[92:95]
	v_mfma_f32_16x16x32_bf16 v[88:91], v[160:163], v[202:205], v[88:91]
	v_mfma_f32_16x16x32_bf16 v[76:79], v[144:147], v[210:213], v[76:79]
	v_mfma_f32_16x16x32_bf16 v[72:75], v[160:163], v[210:213], v[72:75]
	v_mfma_f32_16x16x32_bf16 v[124:127], v[156:159], v[190:193], v[124:127]
	v_mfma_f32_16x16x32_bf16 v[120:123], v[164:167], v[190:193], v[120:123]
	v_mfma_f32_16x16x32_bf16 v[108:111], v[156:159], v[198:201], v[108:111]
	v_mfma_f32_16x16x32_bf16 v[104:107], v[164:167], v[198:201], v[104:107]
	v_mfma_f32_16x16x32_bf16 v[92:95], v[156:159], v[206:209], v[92:95]
	v_mfma_f32_16x16x32_bf16 v[88:91], v[164:167], v[206:209], v[88:91]
	v_mfma_f32_16x16x32_bf16 v[76:79], v[156:159], v[214:217], v[76:79]
	v_mfma_f32_16x16x32_bf16 v[72:75], v[164:167], v[214:217], v[72:75]
	v_mfma_f32_16x16x32_bf16 v[116:119], v[168:171], v[184:187], v[116:119]
	v_mfma_f32_16x16x32_bf16 v[112:115], v[176:179], v[184:187], v[112:115]
	v_mfma_f32_16x16x32_bf16 v[100:103], v[168:171], v[194:197], v[100:103]
	v_mfma_f32_16x16x32_bf16 v[96:99], v[176:179], v[194:197], v[96:99]
	v_mfma_f32_16x16x32_bf16 v[84:87], v[168:171], v[202:205], v[84:87]
	v_mfma_f32_16x16x32_bf16 v[80:83], v[176:179], v[202:205], v[80:83]
	v_mfma_f32_16x16x32_bf16 v[68:71], v[168:171], v[210:213], v[68:71]
	v_mfma_f32_16x16x32_bf16 v[64:67], v[176:179], v[210:213], v[64:67]
	v_mfma_f32_16x16x32_bf16 v[116:119], v[172:175], v[190:193], v[116:119]
	v_mfma_f32_16x16x32_bf16 v[112:115], v[180:183], v[190:193], v[112:115]
	v_mfma_f32_16x16x32_bf16 v[100:103], v[172:175], v[198:201], v[100:103]
	v_mfma_f32_16x16x32_bf16 v[96:99], v[180:183], v[198:201], v[96:99]
	v_mfma_f32_16x16x32_bf16 v[84:87], v[172:175], v[206:209], v[84:87]
	v_mfma_f32_16x16x32_bf16 v[80:83], v[180:183], v[206:209], v[80:83]
	v_mfma_f32_16x16x32_bf16 v[68:71], v[172:175], v[214:217], v[68:71]
	v_mfma_f32_16x16x32_bf16 v[64:67], v[180:183], v[214:217], v[64:67]
	s_barrier
; #define PG8_STAGE(bufoff, gbase, voff) do { _Pragma("unroll") for (int _i = 0; _i < 2; ++_i) \
;         __builtin_amdgcn_global_load_lds((const unsigned*)((const char*)(gbase) + (voff)[_i]), (PG8_LAS unsigned*)(lds + (bufoff) + ldsw + _i * 8192), 16, 0, 0); } while (0)
; #define PG8_LDA(dst, b, h) do { _Pragma("unroll") for (int m = 0; m < 4; ++m) _Pragma("unroll") for (int k = 0; k < 2; ++k) dst[m][k] = *(const PG8_LAS bf16x8*)(lds + PG8_SA(b, h) + aoff + m * 2048 + k * 1024); } while (0)
; #define PG8_LDB(dst, b, h) do { _Pragma("unroll") for (int n = 0; n < 2; ++n) _Pragma("unroll") for (int k = 0; k < 2; ++k) dst[n][k] = *(const PG8_LAS bf16x8*)(lds + PG8_SB(b, h) + boff + n * 2048 + k * 1024); } while (0)
; #define PG8_MMA(ai, bj, At, Bt) do { __builtin_amdgcn_s_setprio(1); _Pragma("unroll") for (int m = 0; m < 4; ++m) _Pragma("unroll") for (int n = 0; n < 2; ++n) _Pragma("unroll") for (int k = 0; k < 2; ++k) \
;         acc[ai][bj][m][n] = __builtin_amdgcn_mfma_f32_16x16x32_bf16(Bt[n][k], At[m][k], acc[ai][bj][m][n], 0, 0, 0); __builtin_amdgcn_s_setprio(0); } while (0)
; #define PG8_WAIT_V(n) asm volatile("s_waitcnt vmcnt(" #n ")" ::: "memory")
; #define PG8_WAIT_L(n) asm volatile("s_waitcnt lgkmcnt(" #n ")" ::: "memory")
; #define PG8_BAR __builtin_amdgcn_s_barrier()
; #define PG8_SCHED __builtin_amdgcn_sched_barrier(0)
; template <class Epi, class Sched, bool ALIGN_EPI = false, bool SP2 = false>
; __device__ __forceinline__ void gemm_phase(PG8_LAS unsigned char* lds, const Gemm g, const Sched& S, const Epi& E) {
;     ...
;             PG8_LDB(B0, 0, 0); PG8_LDB(B1, 0, 1); PG8_SCHED; PG8_LDA(At, 0, 0); PG8_STAGE(PG8_SA(1, 1), a1 + hstep, voffA);
;             PG8_WAIT_V(8); PG8_WAIT_L(0); PG8_BAR; PG8_MMA(0, 0, At, B0); PG8_MMA(0, 1, At, B1); PG8_BAR; PG8_SCHED;
;     ...
;             PG8_LDA(At, 1, 1); PG8_STAGE(PG8_SB(1, 0), b3, voffB); PG8_STAGE(PG8_SB(1, 1), b3 + hstep, voffB); PG8_STAGE(PG8_SA(1, 0), a3, voffA);
;             PG8_WAIT_V(8); PG8_WAIT_L(0); PG8_BAR; PG8_MMA(1, 0, At, B0); PG8_MMA(1, 1, At, B1); PG8_BAR; PG8_SCHED;
	s_setprio 0
	s_add_i32 s30, s51, s35
	v_lshl_add_u64 v[218:219], v[218:219], 0, s[2:3]
	s_mov_b32 m0, s30
	ds_read_b128 v[184:187], v153 offset:49152
	ds_read_b128 v[190:193], v153 offset:50176
	ds_read_b128 v[194:197], v153 offset:51200
	ds_read_b128 v[198:201], v153 offset:52224
	ds_read_b128 v[202:205], v153 offset:53248
	ds_read_b128 v[206:209], v153 offset:54272
	ds_read_b128 v[210:213], v153 offset:55296
	ds_read_b128 v[214:217], v153 offset:56320
	global_load_lds_dwordx4 v[218:219], off
	s_add_i32 m0, s30, 0x2000
	s_add_u32 s28, s28, 0x40080
	v_lshl_add_u64 v[218:219], v[220:221], 0, s[2:3]
	s_addc_u32 s29, s29, 0
	s_add_i32 s30, s52, s35
	global_load_lds_dwordx4 v[218:219], off
	s_mov_b32 m0, s30
	s_nop 0
	global_load_lds_dwordx4 v130, s[28:29]
	s_add_i32 m0, s30, 0x2000
	s_nop 0
	global_load_lds_dwordx4 v134, s[28:29]
	v_lshl_add_u64 v[218:219], v[222:223], 0, s[2:3]
	s_mov_b32 m0, s40
	s_nop 0
	global_load_lds_dwordx4 v[218:219], off
	v_lshl_add_u64 v[218:219], v[224:225], 0, s[2:3]
	s_mov_b32 m0, s41
	s_nop 0
	global_load_lds_dwordx4 v[218:219], off
	s_waitcnt vmcnt(8)
	s_waitcnt lgkmcnt(0)
	s_setprio 1
	s_barrier
	v_mfma_f32_16x16x32_bf16 v[60:63], v[144:147], v[184:187], v[60:63]
	v_mfma_f32_16x16x32_bf16 v[56:59], v[160:163], v[184:187], v[56:59]
	v_mfma_f32_16x16x32_bf16 v[44:47], v[144:147], v[194:197], v[44:47]
	v_mfma_f32_16x16x32_bf16 v[40:43], v[160:163], v[194:197], v[40:43]
	v_mfma_f32_16x16x32_bf16 v[28:31], v[144:147], v[202:205], v[28:31]
	v_mfma_f32_16x16x32_bf16 v[24:27], v[160:163], v[202:205], v[24:27]
	v_mfma_f32_16x16x32_bf16 v[12:15], v[144:147], v[210:213], v[12:15]
	v_mfma_f32_16x16x32_bf16 v[8:11], v[160:163], v[210:213], v[8:11]
	v_mfma_f32_16x16x32_bf16 v[60:63], v[156:159], v[190:193], v[60:63]
	v_mfma_f32_16x16x32_bf16 v[56:59], v[164:167], v[190:193], v[56:59]
	v_mfma_f32_16x16x32_bf16 v[44:47], v[156:159], v[198:201], v[44:47]
	v_mfma_f32_16x16x32_bf16 v[40:43], v[164:167], v[198:201], v[40:43]
	v_mfma_f32_16x16x32_bf16 v[28:31], v[156:159], v[206:209], v[28:31]
	v_mfma_f32_16x16x32_bf16 v[24:27], v[164:167], v[206:209], v[24:27]
	v_mfma_f32_16x16x32_bf16 v[12:15], v[156:159], v[214:217], v[12:15]
	v_mfma_f32_16x16x32_bf16 v[8:11], v[164:167], v[214:217], v[8:11]
	v_mfma_f32_16x16x32_bf16 v[52:55], v[168:171], v[184:187], v[52:55]
	v_mfma_f32_16x16x32_bf16 v[48:51], v[176:179], v[184:187], v[48:51]
	v_mfma_f32_16x16x32_bf16 v[36:39], v[168:171], v[194:197], v[36:39]
	v_mfma_f32_16x16x32_bf16 v[32:35], v[176:179], v[194:197], v[32:35]
	v_mfma_f32_16x16x32_bf16 v[20:23], v[168:171], v[202:205], v[20:23]
	v_mfma_f32_16x16x32_bf16 v[16:19], v[176:179], v[202:205], v[16:19]
	v_mfma_f32_16x16x32_bf16 v[4:7], v[168:171], v[210:213], v[4:7]
	v_mfma_f32_16x16x32_bf16 v[0:3], v[176:179], v[210:213], v[0:3]
	v_mfma_f32_16x16x32_bf16 v[52:55], v[172:175], v[190:193], v[52:55]
	v_mfma_f32_16x16x32_bf16 v[48:51], v[180:183], v[190:193], v[48:51]
	v_mfma_f32_16x16x32_bf16 v[36:39], v[172:175], v[198:201], v[36:39]
	v_mfma_f32_16x16x32_bf16 v[32:35], v[180:183], v[198:201], v[32:35]
	v_mfma_f32_16x16x32_bf16 v[20:23], v[172:175], v[206:209], v[20:23]
	v_mfma_f32_16x16x32_bf16 v[16:19], v[180:183], v[206:209], v[16:19]
	v_mfma_f32_16x16x32_bf16 v[4:7], v[172:175], v[214:217], v[4:7]
	v_mfma_f32_16x16x32_bf16 v[0:3], v[180:183], v[214:217], v[0:3]
	s_barrier
	s_setprio 0
	s_add_i32 s50, s50, 2
	s_add_u32 s26, s26, 0x100
	s_addc_u32 s27, s27, 0
	s_add_u32 s48, s48, 0x100
	s_addc_u32 s49, s49, 0
.LBB0_698:
	ds_read_b128 v[144:147], v151
	ds_read_b128 v[156:159], v151 offset:1024
	ds_read_b128 v[160:163], v151 offset:2048
	ds_read_b128 v[164:167], v151 offset:3072
	ds_read_b128 v[168:171], v152
	ds_read_b128 v[172:175], v152 offset:1024
	ds_read_b128 v[176:179], v152 offset:2048
	ds_read_b128 v[180:183], v152 offset:3072
	s_add_u32 s28, s26, 0xfffc0080
	s_addc_u32 s29, s27, -1
	s_cmp_eq_u32 s50, 12
	s_cselect_b32 s31, s17, s29
	s_cselect_b32 s30, s23, s28
	s_cselect_b32 s29, s15, s49
	s_cselect_b32 s28, s47, s48
	s_add_i32 m0, s25, 0xc000
	ds_read_b128 v[184:187], v153
	ds_read_b128 v[190:193], v153 offset:1024
	ds_read_b128 v[194:197], v153 offset:2048
	ds_read_b128 v[198:201], v153 offset:3072
	ds_read_b128 v[202:205], v153 offset:4096
	ds_read_b128 v[206:209], v153 offset:5120
	ds_read_b128 v[210:213], v153 offset:6144
	ds_read_b128 v[214:217], v153 offset:7168
	global_load_lds_dwordx4 v136, s[26:27]
	s_add_i32 m0, s25, 0xe000
	s_nop 0
	global_load_lds_dwordx4 v138, s[26:27]
	s_waitcnt vmcnt(8)
	s_waitcnt lgkmcnt(0)
	s_setprio 1
	s_barrier
; #define PG8_STAGE(bufoff, gbase, voff) do { _Pragma("unroll") for (int _i = 0; _i < 2; ++_i) \
;         __builtin_amdgcn_global_load_lds((const unsigned*)((const char*)(gbase) + (voff)[_i]), (PG8_LAS unsigned*)(lds + (bufoff) + ldsw + _i * 8192), 16, 0, 0); } while (0)
; #define PG8_LDA(dst, b, h) do { _Pragma("unroll") for (int m = 0; m < 4; ++m) _Pragma("unroll") for (int k = 0; k < 2; ++k) dst[m][k] = *(const PG8_LAS bf16x8*)(lds + PG8_SA(b, h) + aoff + m * 2048 + k * 1024); } while (0)
; #define PG8_LDB(dst, b, h) do { _Pragma("unroll") for (int n = 0; n < 2; ++n) _Pragma("unroll") for (int k = 0; k < 2; ++k) dst[n][k] = *(const PG8_LAS bf16x8*)(lds + PG8_SB(b, h) + boff + n * 2048 + k * 1024); } while (0)
; #define PG8_MMA(ai, bj, At, Bt) do { __builtin_amdgcn_s_setprio(1); _Pragma("unroll") for (int m = 0; m < 4; ++m) _Pragma("unroll") for (int n = 0; n < 2; ++n) _Pragma("unroll") for (int k = 0; k < 2; ++k) \
;         acc[ai][bj][m][n] = __builtin_amdgcn_mfma_f32_16x16x32_bf16(Bt[n][k], At[m][k], acc[ai][bj][m][n], 0, 0, 0); __builtin_amdgcn_s_setprio(0); } while (0)
; #define PG8_WAIT_V(n) asm volatile("s_waitcnt vmcnt(" #n ")" ::: "memory")
; #define PG8_WAIT_L(n) asm volatile("s_waitcnt lgkmcnt(" #n ")" ::: "memory")
; #define PG8_BAR __builtin_amdgcn_s_barrier()
; #define PG8_SCHED __builtin_amdgcn_sched_barrier(0)
; template <class Epi, class Sched, bool ALIGN_EPI = false, bool SP2 = false>
; __device__ __forceinline__ void gemm_phase(PG8_LAS unsigned char* lds, const Gemm g, const Sched& S, const Epi& E) {
;     ...
;             PG8_LDB(B0, 0, 0); PG8_LDB(B1, 0, 1); PG8_SCHED; PG8_LDA(At, 0, 0); PG8_STAGE(PG8_SA(1, 1), a1 + hstep, voffA);
;             PG8_WAIT_V(8); PG8_WAIT_L(0); PG8_BAR; PG8_MMA(0, 0, At, B0); PG8_MMA(0, 1, At, B1); PG8_BAR; PG8_SCHED;
;             PG8_LDA(At, 0, 1); PG8_STAGE(PG8_SB(0, 0), b2, voffB); PG8_STAGE(PG8_SB(0, 1), b2 + hstep, voffB); PG8_STAGE(PG8_SA(0, 0), a2, voffA);
;             PG8_WAIT_V(8); PG8_WAIT_L(0); PG8_BAR; PG8_MMA(1, 0, At, B0); PG8_MMA(1, 1, At, B1); PG8_BAR; PG8_SCHED;
	v_mfma_f32_16x16x32_bf16 v[124:127], v[144:147], v[184:187], v[124:127]
	v_mfma_f32_16x16x32_bf16 v[120:123], v[160:163], v[184:187], v[120:123]
	v_mfma_f32_16x16x32_bf16 v[108:111], v[144:147], v[194:197], v[108:111]
	v_mfma_f32_16x16x32_bf16 v[104:107], v[160:163], v[194:197], v[104:107]
	v_mfma_f32_16x16x32_bf16 v[92:95], v[144:147], v[202:205], v[92:95]
	v_mfma_f32_16x16x32_bf16 v[88:91], v[160:163], v[202:205], v[88:91]
	v_mfma_f32_16x16x32_bf16 v[76:79], v[144:147], v[210:213], v[76:79]
	v_mfma_f32_16x16x32_bf16 v[72:75], v[160:163], v[210:213], v[72:75]
	v_mfma_f32_16x16x32_bf16 v[124:127], v[156:159], v[190:193], v[124:127]
	v_mfma_f32_16x16x32_bf16 v[120:123], v[164:167], v[190:193], v[120:123]
	v_mfma_f32_16x16x32_bf16 v[108:111], v[156:159], v[198:201], v[108:111]
	v_mfma_f32_16x16x32_bf16 v[104:107], v[164:167], v[198:201], v[104:107]
	v_mfma_f32_16x16x32_bf16 v[92:95], v[156:159], v[206:209], v[92:95]
	v_mfma_f32_16x16x32_bf16 v[88:91], v[164:167], v[206:209], v[88:91]
	v_mfma_f32_16x16x32_bf16 v[76:79], v[156:159], v[214:217], v[76:79]
	v_mfma_f32_16x16x32_bf16 v[72:75], v[164:167], v[214:217], v[72:75]
	v_mfma_f32_16x16x32_bf16 v[116:119], v[168:171], v[184:187], v[116:119]
	v_mfma_f32_16x16x32_bf16 v[112:115], v[176:179], v[184:187], v[112:115]
	v_mfma_f32_16x16x32_bf16 v[100:103], v[168:171], v[194:197], v[100:103]
	v_mfma_f32_16x16x32_bf16 v[96:99], v[176:179], v[194:197], v[96:99]
	v_mfma_f32_16x16x32_bf16 v[84:87], v[168:171], v[202:205], v[84:87]
	v_mfma_f32_16x16x32_bf16 v[80:83], v[176:179], v[202:205], v[80:83]
	v_mfma_f32_16x16x32_bf16 v[68:71], v[168:171], v[210:213], v[68:71]
	v_mfma_f32_16x16x32_bf16 v[64:67], v[176:179], v[210:213], v[64:67]
	v_mfma_f32_16x16x32_bf16 v[116:119], v[172:175], v[190:193], v[116:119]
	v_mfma_f32_16x16x32_bf16 v[112:115], v[180:183], v[190:193], v[112:115]
	v_mfma_f32_16x16x32_bf16 v[100:103], v[172:175], v[198:201], v[100:103]
	v_mfma_f32_16x16x32_bf16 v[96:99], v[180:183], v[198:201], v[96:99]
	v_mfma_f32_16x16x32_bf16 v[84:87], v[172:175], v[206:209], v[84:87]
	v_mfma_f32_16x16x32_bf16 v[80:83], v[180:183], v[206:209], v[80:83]
	v_mfma_f32_16x16x32_bf16 v[68:71], v[172:175], v[214:217], v[68:71]
	v_mfma_f32_16x16x32_bf16 v[64:67], v[180:183], v[214:217], v[64:67]
	s_barrier
	s_setprio 0
	s_add_i32 s51, s45, s35
	v_lshl_add_u64 v[218:219], s[28:29], 0, v[130:131]
	s_mov_b32 m0, s51
	ds_read_b128 v[184:187], v153 offset:16384
	ds_read_b128 v[190:193], v153 offset:17408
	ds_read_b128 v[194:197], v153 offset:18432
	ds_read_b128 v[198:201], v153 offset:19456
	ds_read_b128 v[202:205], v153 offset:20480
	ds_read_b128 v[206:209], v153 offset:21504
	ds_read_b128 v[210:213], v153 offset:22528
	ds_read_b128 v[214:217], v153 offset:23552
	global_load_lds_dwordx4 v[218:219], off
	s_add_i32 m0, s51, 0x2000
	s_add_u32 s52, s28, 0x40000
	v_lshl_add_u64 v[220:221], s[28:29], 0, v[134:135]
	s_addc_u32 s53, s29, 0
	s_add_i32 s51, s46, s35
	global_load_lds_dwordx4 v[220:221], off
	s_mov_b32 m0, s51
	v_lshl_add_u64 v[224:225], s[30:31], 0, v[132:133]
	global_load_lds_dwordx4 v130, s[52:53]
	s_add_i32 m0, s51, 0x2000
	s_nop 0
	global_load_lds_dwordx4 v134, s[52:53]
	v_lshl_add_u64 v[222:223], s[30:31], 0, v[128:129]
	s_mov_b32 m0, s25
	s_nop 0
	global_load_lds_dwordx4 v[222:223], off
	s_mov_b32 m0, s36
	s_nop 0
	global_load_lds_dwordx4 v[224:225], off
	s_waitcnt vmcnt(8)
	s_waitcnt lgkmcnt(0)
	s_setprio 1
	s_barrier
	v_mfma_f32_16x16x32_bf16 v[60:63], v[144:147], v[184:187], v[60:63]
	v_mfma_f32_16x16x32_bf16 v[56:59], v[160:163], v[184:187], v[56:59]
	v_mfma_f32_16x16x32_bf16 v[44:47], v[144:147], v[194:197], v[44:47]
	v_mfma_f32_16x16x32_bf16 v[40:43], v[160:163], v[194:197], v[40:43]
	v_mfma_f32_16x16x32_bf16 v[28:31], v[144:147], v[202:205], v[28:31]
	v_mfma_f32_16x16x32_bf16 v[24:27], v[160:163], v[202:205], v[24:27]
	v_mfma_f32_16x16x32_bf16 v[12:15], v[144:147], v[210:213], v[12:15]
	v_mfma_f32_16x16x32_bf16 v[8:11], v[160:163], v[210:213], v[8:11]
	v_mfma_f32_16x16x32_bf16 v[60:63], v[156:159], v[190:193], v[60:63]
	v_mfma_f32_16x16x32_bf16 v[56:59], v[164:167], v[190:193], v[56:59]
	v_mfma_f32_16x16x32_bf16 v[44:47], v[156:159], v[198:201], v[44:47]
	v_mfma_f32_16x16x32_bf16 v[40:43], v[164:167], v[198:201], v[40:43]
	v_mfma_f32_16x16x32_bf16 v[28:31], v[156:159], v[206:209], v[28:31]
	v_mfma_f32_16x16x32_bf16 v[24:27], v[164:167], v[206:209], v[24:27]
	v_mfma_f32_16x16x32_bf16 v[12:15], v[156:159], v[214:217], v[12:15]
	v_mfma_f32_16x16x32_bf16 v[8:11], v[164:167], v[214:217], v[8:11]
	v_mfma_f32_16x16x32_bf16 v[52:55], v[168:171], v[184:187], v[52:55]
	v_mfma_f32_16x16x32_bf16 v[48:51], v[176:179], v[184:187], v[48:51]
	v_mfma_f32_16x16x32_bf16 v[36:39], v[168:171], v[194:197], v[36:39]
	v_mfma_f32_16x16x32_bf16 v[32:35], v[176:179], v[194:197], v[32:35]
	v_mfma_f32_16x16x32_bf16 v[20:23], v[168:171], v[202:205], v[20:23]
	v_mfma_f32_16x16x32_bf16 v[16:19], v[176:179], v[202:205], v[16:19]
	v_mfma_f32_16x16x32_bf16 v[4:7], v[168:171], v[210:213], v[4:7]
	v_mfma_f32_16x16x32_bf16 v[0:3], v[176:179], v[210:213], v[0:3]
	v_mfma_f32_16x16x32_bf16 v[52:55], v[172:175], v[190:193], v[52:55]
	v_mfma_f32_16x16x32_bf16 v[48:51], v[180:183], v[190:193], v[48:51]
	v_mfma_f32_16x16x32_bf16 v[36:39], v[172:175], v[198:201], v[36:39]
	v_mfma_f32_16x16x32_bf16 v[32:35], v[180:183], v[198:201], v[32:35]
	v_mfma_f32_16x16x32_bf16 v[20:23], v[172:175], v[206:209], v[20:23]
	v_mfma_f32_16x16x32_bf16 v[16:19], v[180:183], v[206:209], v[16:19]
	v_mfma_f32_16x16x32_bf16 v[4:7], v[172:175], v[214:217], v[4:7]
	v_mfma_f32_16x16x32_bf16 v[0:3], v[180:183], v[214:217], v[0:3]
	s_barrier
; #define PG8_STAGE(bufoff, gbase, voff) do { _Pragma("unroll") for (int _i = 0; _i < 2; ++_i) \
;         __builtin_amdgcn_global_load_lds((const unsigned*)((const char*)(gbase) + (voff)[_i]), (PG8_LAS unsigned*)(lds + (bufoff) + ldsw + _i * 8192), 16, 0, 0); } while (0)
; #define PG8_LDA(dst, b, h) do { _Pragma("unroll") for (int m = 0; m < 4; ++m) _Pragma("unroll") for (int k = 0; k < 2; ++k) dst[m][k] = *(const PG8_LAS bf16x8*)(lds + PG8_SA(b, h) + aoff + m * 2048 + k * 1024); } while (0)
; #define PG8_LDB(dst, b, h) do { _Pragma("unroll") for (int n = 0; n < 2; ++n) _Pragma("unroll") for (int k = 0; k < 2; ++k) dst[n][k] = *(const PG8_LAS bf16x8*)(lds + PG8_SB(b, h) + boff + n * 2048 + k * 1024); } while (0)
; #define PG8_MMA(ai, bj, At, Bt) do { __builtin_amdgcn_s_setprio(1); _Pragma("unroll") for (int m = 0; m < 4; ++m) _Pragma("unroll") for (int n = 0; n < 2; ++n) _Pragma("unroll") for (int k = 0; k < 2; ++k) \
;         acc[ai][bj][m][n] = __builtin_amdgcn_mfma_f32_16x16x32_bf16(Bt[n][k], At[m][k], acc[ai][bj][m][n], 0, 0, 0); __builtin_amdgcn_s_setprio(0); } while (0)
; #define PG8_WAIT_V(n) asm volatile("s_waitcnt vmcnt(" #n ")" ::: "memory")
; #define PG8_WAIT_L(n) asm volatile("s_waitcnt lgkmcnt(" #n ")" ::: "memory")
; #define PG8_BAR __builtin_amdgcn_s_barrier()
; #define PG8_SCHED __builtin_amdgcn_sched_barrier(0)
; template <class Epi, class Sched, bool ALIGN_EPI = false, bool SP2 = false>
; __device__ __forceinline__ void gemm_phase(PG8_LAS unsigned char* lds, const Gemm g, const Sched& S, const Epi& E) {
;     ...
;         for (int t = 0; t < nt; t += 2) {
;     ...
;             PG8_LDB(B0, 1, 0); PG8_LDB(B1, 1, 1); PG8_SCHED; PG8_LDA(At, 1, 0); PG8_STAGE(PG8_SA(0, 1), a2 + hstep, voffA);
;             PG8_WAIT_V(8); PG8_WAIT_L(0); PG8_BAR; PG8_MMA(0, 0, At, B0); PG8_MMA(0, 1, At, B1); PG8_BAR; PG8_SCHED;
;             PG8_LDA(At, 1, 1); PG8_STAGE(PG8_SB(1, 0), b3, voffB); PG8_STAGE(PG8_SB(1, 1), b3 + hstep, voffB); PG8_STAGE(PG8_SA(1, 0), a3, voffA);
;             PG8_WAIT_V(8); PG8_WAIT_L(0); PG8_BAR; PG8_MMA(1, 0, At, B0); PG8_MMA(1, 1, At, B1); PG8_BAR; PG8_SCHED;
	s_setprio 0
	s_add_i32 s51, 0, 0x18000
	v_add_u32_e32 v155, s51, v149
	s_add_i32 s52, 0, 0x1c000
	ds_read_b128 v[144:147], v155
	ds_read_b128 v[156:159], v155 offset:1024
	ds_read_b128 v[160:163], v155 offset:2048
	ds_read_b128 v[164:167], v155 offset:3072
	v_add_u32_e32 v155, s52, v149
	ds_read_b128 v[168:171], v155
	ds_read_b128 v[172:175], v155 offset:1024
	ds_read_b128 v[176:179], v155 offset:2048
	ds_read_b128 v[180:183], v155 offset:3072
	s_add_u32 s30, s30, 0x40000
	s_addc_u32 s31, s31, 0
	s_mov_b32 m0, s37
	ds_read_b128 v[184:187], v153 offset:32768
	ds_read_b128 v[190:193], v153 offset:33792
	ds_read_b128 v[194:197], v153 offset:34816
	ds_read_b128 v[198:201], v153 offset:35840
	ds_read_b128 v[202:205], v153 offset:36864
	ds_read_b128 v[206:209], v153 offset:37888
	ds_read_b128 v[210:213], v153 offset:38912
	ds_read_b128 v[214:217], v153 offset:39936
	global_load_lds_dwordx4 v128, s[30:31]
	v_lshl_add_u64 v[226:227], s[30:31], 0, v[132:133]
	s_mov_b32 m0, s38
	s_nop 0
	global_load_lds_dwordx4 v[226:227], off
	s_waitcnt vmcnt(8)
	s_waitcnt lgkmcnt(0)
	s_setprio 1
	s_barrier
	v_mfma_f32_16x16x32_bf16 v[124:127], v[144:147], v[184:187], v[124:127]
	v_mfma_f32_16x16x32_bf16 v[120:123], v[160:163], v[184:187], v[120:123]
	v_mfma_f32_16x16x32_bf16 v[108:111], v[144:147], v[194:197], v[108:111]
	v_mfma_f32_16x16x32_bf16 v[104:107], v[160:163], v[194:197], v[104:107]
	v_mfma_f32_16x16x32_bf16 v[92:95], v[144:147], v[202:205], v[92:95]
	v_mfma_f32_16x16x32_bf16 v[88:91], v[160:163], v[202:205], v[88:91]
	v_mfma_f32_16x16x32_bf16 v[76:79], v[144:147], v[210:213], v[76:79]
	v_mfma_f32_16x16x32_bf16 v[72:75], v[160:163], v[210:213], v[72:75]
	v_mfma_f32_16x16x32_bf16 v[124:127], v[156:159], v[190:193], v[124:127]
	v_mfma_f32_16x16x32_bf16 v[120:123], v[164:167], v[190:193], v[120:123]
	v_mfma_f32_16x16x32_bf16 v[108:111], v[156:159], v[198:201], v[108:111]
	v_mfma_f32_16x16x32_bf16 v[104:107], v[164:167], v[198:201], v[104:107]
	v_mfma_f32_16x16x32_bf16 v[92:95], v[156:159], v[206:209], v[92:95]
	v_mfma_f32_16x16x32_bf16 v[88:91], v[164:167], v[206:209], v[88:91]
	v_mfma_f32_16x16x32_bf16 v[76:79], v[156:159], v[214:217], v[76:79]
	v_mfma_f32_16x16x32_bf16 v[72:75], v[164:167], v[214:217], v[72:75]
	v_mfma_f32_16x16x32_bf16 v[116:119], v[168:171], v[184:187], v[116:119]
	v_mfma_f32_16x16x32_bf16 v[112:115], v[176:179], v[184:187], v[112:115]
	v_mfma_f32_16x16x32_bf16 v[100:103], v[168:171], v[194:197], v[100:103]
	v_mfma_f32_16x16x32_bf16 v[96:99], v[176:179], v[194:197], v[96:99]
	v_mfma_f32_16x16x32_bf16 v[84:87], v[168:171], v[202:205], v[84:87]
	v_mfma_f32_16x16x32_bf16 v[80:83], v[176:179], v[202:205], v[80:83]
	v_mfma_f32_16x16x32_bf16 v[68:71], v[168:171], v[210:213], v[68:71]
	v_mfma_f32_16x16x32_bf16 v[64:67], v[176:179], v[210:213], v[64:67]
	v_mfma_f32_16x16x32_bf16 v[116:119], v[172:175], v[190:193], v[116:119]
	v_mfma_f32_16x16x32_bf16 v[112:115], v[180:183], v[190:193], v[112:115]
	v_mfma_f32_16x16x32_bf16 v[100:103], v[172:175], v[198:201], v[100:103]
	v_mfma_f32_16x16x32_bf16 v[96:99], v[180:183], v[198:201], v[96:99]
	v_mfma_f32_16x16x32_bf16 v[84:87], v[172:175], v[206:209], v[84:87]
	v_mfma_f32_16x16x32_bf16 v[80:83], v[180:183], v[206:209], v[80:83]
	v_mfma_f32_16x16x32_bf16 v[68:71], v[172:175], v[214:217], v[68:71]
	v_mfma_f32_16x16x32_bf16 v[64:67], v[180:183], v[214:217], v[64:67]
	s_barrier
	s_setprio 0
	s_add_i32 s30, s51, s35
	v_lshl_add_u64 v[218:219], v[218:219], 0, s[2:3]
	s_mov_b32 m0, s30
	ds_read_b128 v[184:187], v153 offset:49152
	ds_read_b128 v[190:193], v153 offset:50176
	ds_read_b128 v[194:197], v153 offset:51200
	ds_read_b128 v[198:201], v153 offset:52224
	ds_read_b128 v[202:205], v153 offset:53248
	ds_read_b128 v[206:209], v153 offset:54272
	ds_read_b128 v[210:213], v153 offset:55296
	ds_read_b128 v[214:217], v153 offset:56320
	global_load_lds_dwordx4 v[218:219], off
	s_add_i32 m0, s30, 0x2000
	s_add_u32 s28, s28, 0x40080
	v_lshl_add_u64 v[218:219], v[220:221], 0, s[2:3]
	s_addc_u32 s29, s29, 0
	s_add_i32 s30, s52, s35
	global_load_lds_dwordx4 v[218:219], off
	s_mov_b32 m0, s30
	s_nop 0
	global_load_lds_dwordx4 v130, s[28:29]
	s_add_i32 m0, s30, 0x2000
	s_nop 0
	global_load_lds_dwordx4 v134, s[28:29]
	v_lshl_add_u64 v[218:219], v[222:223], 0, s[2:3]
	s_mov_b32 m0, s40
	s_nop 0
	global_load_lds_dwordx4 v[218:219], off
	v_lshl_add_u64 v[218:219], v[224:225], 0, s[2:3]
	s_mov_b32 m0, s41
	s_nop 0
	global_load_lds_dwordx4 v[218:219], off
	s_waitcnt vmcnt(8)
	s_waitcnt lgkmcnt(0)
	s_setprio 1
	s_barrier
	v_mfma_f32_16x16x32_bf16 v[60:63], v[144:147], v[184:187], v[60:63]
	v_mfma_f32_16x16x32_bf16 v[56:59], v[160:163], v[184:187], v[56:59]
	v_mfma_f32_16x16x32_bf16 v[44:47], v[144:147], v[194:197], v[44:47]
	v_mfma_f32_16x16x32_bf16 v[40:43], v[160:163], v[194:197], v[40:43]
	v_mfma_f32_16x16x32_bf16 v[28:31], v[144:147], v[202:205], v[28:31]
	v_mfma_f32_16x16x32_bf16 v[24:27], v[160:163], v[202:205], v[24:27]
	v_mfma_f32_16x16x32_bf16 v[12:15], v[144:147], v[210:213], v[12:15]
	v_mfma_f32_16x16x32_bf16 v[8:11], v[160:163], v[210:213], v[8:11]
	v_mfma_f32_16x16x32_bf16 v[60:63], v[156:159], v[190:193], v[60:63]
	v_mfma_f32_16x16x32_bf16 v[56:59], v[164:167], v[190:193], v[56:59]
	v_mfma_f32_16x16x32_bf16 v[44:47], v[156:159], v[198:201], v[44:47]
	v_mfma_f32_16x16x32_bf16 v[40:43], v[164:167], v[198:201], v[40:43]
	v_mfma_f32_16x16x32_bf16 v[28:31], v[156:159], v[206:209], v[28:31]
	v_mfma_f32_16x16x32_bf16 v[24:27], v[164:167], v[206:209], v[24:27]
	v_mfma_f32_16x16x32_bf16 v[12:15], v[156:159], v[214:217], v[12:15]
	v_mfma_f32_16x16x32_bf16 v[8:11], v[164:167], v[214:217], v[8:11]
	v_mfma_f32_16x16x32_bf16 v[52:55], v[168:171], v[184:187], v[52:55]
	v_mfma_f32_16x16x32_bf16 v[48:51], v[176:179], v[184:187], v[48:51]
	v_mfma_f32_16x16x32_bf16 v[36:39], v[168:171], v[194:197], v[36:39]
	v_mfma_f32_16x16x32_bf16 v[32:35], v[176:179], v[194:197], v[32:35]
	v_mfma_f32_16x16x32_bf16 v[20:23], v[168:171], v[202:205], v[20:23]
	v_mfma_f32_16x16x32_bf16 v[16:19], v[176:179], v[202:205], v[16:19]
	v_mfma_f32_16x16x32_bf16 v[4:7], v[168:171], v[210:213], v[4:7]
	v_mfma_f32_16x16x32_bf16 v[0:3], v[176:179], v[210:213], v[0:3]
	v_mfma_f32_16x16x32_bf16 v[52:55], v[172:175], v[190:193], v[52:55]
	v_mfma_f32_16x16x32_bf16 v[48:51], v[180:183], v[190:193], v[48:51]
	v_mfma_f32_16x16x32_bf16 v[36:39], v[172:175], v[198:201], v[36:39]
	v_mfma_f32_16x16x32_bf16 v[32:35], v[180:183], v[198:201], v[32:35]
	v_mfma_f32_16x16x32_bf16 v[20:23], v[172:175], v[206:209], v[20:23]
	v_mfma_f32_16x16x32_bf16 v[16:19], v[180:183], v[206:209], v[16:19]
	v_mfma_f32_16x16x32_bf16 v[4:7], v[172:175], v[214:217], v[4:7]
	v_mfma_f32_16x16x32_bf16 v[0:3], v[180:183], v[214:217], v[0:3]
	s_barrier
	s_setprio 0
	s_add_i32 s50, s50, 2
	s_add_u32 s26, s26, 0x100
	s_addc_u32 s27, s27, 0
	s_add_u32 s48, s48, 0x100
	s_addc_u32 s49, s49, 0
	s_cmp_gt_u32 s50, 13
	s_cbranch_scc0 .LBB0_698
	s_and_b64 vcc, exec, s[12:13]
	s_cbranch_vccz .LBB0_701
	s_barrier

; #define PG8_STAGE(bufoff, gbase, voff) do { _Pragma("unroll") for (int _i = 0; _i < 2; ++_i) \
;         __builtin_amdgcn_global_load_lds((const unsigned*)((const char*)(gbase) + (voff)[_i]), (PG8_LAS unsigned*)(lds + (bufoff) + ldsw + _i * 8192), 16, 0, 0); } while (0)
; #define PG8_LDA(dst, b, h) do { _Pragma("unroll") for (int m = 0; m < 4; ++m) _Pragma("unroll") for (int k = 0; k < 2; ++k) dst[m][k] = *(const PG8_LAS bf16x8*)(lds + PG8_SA(b, h) + aoff + m * 2048 + k * 1024); } while (0)
; #define PG8_LDB(dst, b, h) do { _Pragma("unroll") for (int n = 0; n < 2; ++n) _Pragma("unroll") for (int k = 0; k < 2; ++k) dst[n][k] = *(const PG8_LAS bf16x8*)(lds + PG8_SB(b, h) + boff + n * 2048 + k * 1024); } while (0)
; #define PG8_WAIT_V(n) asm volatile("s_waitcnt vmcnt(" #n ")" ::: "memory")
; #define PG8_WAIT_L(n) asm volatile("s_waitcnt lgkmcnt(" #n ")" ::: "memory")
; #define PG8_BAR __builtin_amdgcn_s_barrier()
; #define PG8_SCHED __builtin_amdgcn_sched_barrier(0)
; template <class Epi, class Sched, bool ALIGN_EPI = false, bool SP2 = false>
; __device__ __forceinline__ void gemm_phase(PG8_LAS unsigned char* lds, const Gemm g, const Sched& S, const Epi& E) {
;     ...
;         const bool has_next = S.next(ui + 1, nxt);
;         const char* nA = has_next ? (const char*)g.A + (size_t)nxt.pm * tstep : cA; const char* nB = has_next ? (const char*)g.Bt + (size_t)nxt.pn * tstep : cB;
;         for (int t = 0; t < nt; t += 2) {
;             const bool last = (t == nt - 2);
;             const char* a1 = cA + (size_t)(t + 1) * kstep;
;             const char* a2 = last ? nA : cA + (size_t)(t + 2) * kstep; const char* b2 = last ? nB : cB + (size_t)(t + 2) * kstep;
;             const char* a3 = a2 + kstep; const char* b3 = b2 + kstep;
;             if (last && has_next) S.a_ready(nxt);
;             if constexpr (SP2) {
;             PG8_LDB(B0, 0, 0); PG8_LDB(B1, 0, 1); PG8_SCHED; PG8_LDA(At, 0, 0); PG8_STAGE(PG8_SA(1, 1), a1 + hstep, voffA);
;             PG8_WAIT_V(8); PG8_WAIT_L(0); PG8_BAR; PG8_MMA(0, 0, At, B0); PG8_MMA(0, 1, At, B1); PG8_BAR; PG8_SCHED;
;             PG8_LDA(At, 0, 1); PG8_STAGE(PG8_SB(0, 0), b2, voffB); PG8_STAGE(PG8_SB(0, 1), b2 + hstep, voffB); PG8_STAGE(PG8_SA(0, 0), a2, voffA);
;             PG8_WAIT_V(8); PG8_WAIT_L(0); PG8_BAR; PG8_MMA(1, 0, At, B0); PG8_MMA(1, 1, At, B1); PG8_BAR; PG8_SCHED;
.LBB0_781:
	s_ashr_i32 s17, s16, 31
	s_lshl_b64 s[18:19], s[16:17], 19
	s_add_u32 s18, s8, s18
	s_addc_u32 s19, s9, s19
	s_and_b64 s[20:21], s[4:5], exec
	s_cselect_b32 s17, s19, s23
	s_cselect_b32 s47, s18, s22
	s_ashr_i32 s15, s14, 31
	s_lshl_b64 s[20:21], s[14:15], 19
	s_add_u32 s20, s28, s20
	s_addc_u32 s21, s29, s21
	s_and_b64 s[26:27], s[4:5], exec
	s_cselect_b32 s15, s21, s25
	s_cselect_b32 s48, s20, s24
	s_add_u32 s22, s22, 0x40080
	s_addc_u32 s23, s23, 0
	s_add_u32 s49, s24, 0x100
	s_addc_u32 s50, s25, 0
	s_mov_b32 s51, -2
	ds_read_b128 v[144:147], v151
	ds_read_b128 v[156:159], v151 offset:1024
	ds_read_b128 v[160:163], v151 offset:2048
	ds_read_b128 v[164:167], v151 offset:3072
	ds_read_b128 v[168:171], v152
	ds_read_b128 v[172:175], v152 offset:1024
	ds_read_b128 v[176:179], v152 offset:2048
	ds_read_b128 v[180:183], v152 offset:3072
	s_add_u32 s24, s22, 0xfffc0080
	s_addc_u32 s25, s23, -1
	s_cmp_eq_u32 s51, 12
	s_cselect_b32 s27, s17, s25
	s_cselect_b32 s26, s47, s24
	s_cselect_b32 s25, s15, s50
	s_cselect_b32 s24, s48, s49
	s_add_i32 m0, s34, 0xc000
	ds_read_b128 v[184:187], v153
	ds_read_b128 v[190:193], v153 offset:1024
	ds_read_b128 v[194:197], v153 offset:2048
	ds_read_b128 v[198:201], v153 offset:3072
	ds_read_b128 v[202:205], v153 offset:4096
	ds_read_b128 v[206:209], v153 offset:5120
	ds_read_b128 v[210:213], v153 offset:6144
	ds_read_b128 v[214:217], v153 offset:7168
	global_load_lds_dwordx4 v136, s[22:23]
	s_add_i32 m0, s34, 0xe000
	s_nop 0
	global_load_lds_dwordx4 v138, s[22:23]
	s_waitcnt vmcnt(16)
	s_waitcnt lgkmcnt(0)
	s_setprio 1
	s_barrier
	v_mfma_f32_16x16x32_bf16 v[116:119], v[144:147], v[184:187], 0
	v_mfma_f32_16x16x32_bf16 v[112:115], v[160:163], v[184:187], 0
	v_mfma_f32_16x16x32_bf16 v[100:103], v[144:147], v[194:197], 0
	v_mfma_f32_16x16x32_bf16 v[96:99], v[160:163], v[194:197], 0
	v_mfma_f32_16x16x32_bf16 v[84:87], v[144:147], v[202:205], 0
	v_mfma_f32_16x16x32_bf16 v[80:83], v[160:163], v[202:205], 0
	v_mfma_f32_16x16x32_bf16 v[72:75], v[144:147], v[210:213], 0
	v_mfma_f32_16x16x32_bf16 v[64:67], v[160:163], v[210:213], 0
	v_mfma_f32_16x16x32_bf16 v[116:119], v[156:159], v[190:193], v[116:119]
	v_mfma_f32_16x16x32_bf16 v[112:115], v[164:167], v[190:193], v[112:115]
	v_mfma_f32_16x16x32_bf16 v[100:103], v[156:159], v[198:201], v[100:103]
	v_mfma_f32_16x16x32_bf16 v[96:99], v[164:167], v[198:201], v[96:99]
	v_mfma_f32_16x16x32_bf16 v[84:87], v[156:159], v[206:209], v[84:87]
	v_mfma_f32_16x16x32_bf16 v[80:83], v[164:167], v[206:209], v[80:83]
	v_mfma_f32_16x16x32_bf16 v[72:75], v[156:159], v[214:217], v[72:75]
	v_mfma_f32_16x16x32_bf16 v[64:67], v[164:167], v[214:217], v[64:67]
	v_mfma_f32_16x16x32_bf16 v[124:127], v[168:171], v[184:187], 0
	v_mfma_f32_16x16x32_bf16 v[120:123], v[176:179], v[184:187], 0
	v_mfma_f32_16x16x32_bf16 v[108:111], v[168:171], v[194:197], 0
	v_mfma_f32_16x16x32_bf16 v[104:107], v[176:179], v[194:197], 0
	v_mfma_f32_16x16x32_bf16 v[92:95], v[168:171], v[202:205], 0
	v_mfma_f32_16x16x32_bf16 v[88:91], v[176:179], v[202:205], 0
	v_mfma_f32_16x16x32_bf16 v[76:79], v[168:171], v[210:213], 0
	v_mfma_f32_16x16x32_bf16 v[68:71], v[176:179], v[210:213], 0
	v_mfma_f32_16x16x32_bf16 v[124:127], v[172:175], v[190:193], v[124:127]
	v_mfma_f32_16x16x32_bf16 v[120:123], v[180:183], v[190:193], v[120:123]
	v_mfma_f32_16x16x32_bf16 v[108:111], v[172:175], v[198:201], v[108:111]
	v_mfma_f32_16x16x32_bf16 v[104:107], v[180:183], v[198:201], v[104:107]
	v_mfma_f32_16x16x32_bf16 v[92:95], v[172:175], v[206:209], v[92:95]
	v_mfma_f32_16x16x32_bf16 v[88:91], v[180:183], v[206:209], v[88:91]
	v_mfma_f32_16x16x32_bf16 v[76:79], v[172:175], v[214:217], v[76:79]
	v_mfma_f32_16x16x32_bf16 v[68:71], v[180:183], v[214:217], v[68:71]
	s_barrier
	s_setprio 0
	s_add_i32 s52, s43, s30
	v_lshl_add_u64 v[218:219], s[24:25], 0, v[132:133]
	s_mov_b32 m0, s52
	ds_read_b128 v[184:187], v153 offset:16384
	ds_read_b128 v[190:193], v153 offset:17408
	ds_read_b128 v[194:197], v153 offset:18432
	ds_read_b128 v[198:201], v153 offset:19456
	ds_read_b128 v[202:205], v153 offset:20480
	ds_read_b128 v[206:209], v153 offset:21504
	ds_read_b128 v[210:213], v153 offset:22528
	ds_read_b128 v[214:217], v153 offset:23552
	global_load_lds_dwordx4 v[218:219], off
	s_add_i32 m0, s52, 0x2000
	s_add_u32 s52, s24, 0x40000
	v_lshl_add_u64 v[220:221], s[24:25], 0, v[128:129]
	s_addc_u32 s53, s25, 0
	s_add_i32 s54, s44, s30
	global_load_lds_dwordx4 v[220:221], off
	s_mov_b32 m0, s54
	v_lshl_add_u64 v[224:225], s[26:27], 0, v[130:131]
	global_load_lds_dwordx4 v132, s[52:53]
	s_add_i32 m0, s54, 0x2000
	s_nop 0
	global_load_lds_dwordx4 v128, s[52:53]
	v_lshl_add_u64 v[222:223], s[26:27], 0, v[134:135]
	s_mov_b32 m0, s34
	s_nop 0
	global_load_lds_dwordx4 v[222:223], off
	s_mov_b32 m0, s35
	s_nop 0
	global_load_lds_dwordx4 v[224:225], off
	s_waitcnt vmcnt(16)
	s_waitcnt lgkmcnt(0)
	s_setprio 1
	s_barrier
; #define PG8_STAGE(bufoff, gbase, voff) do { _Pragma("unroll") for (int _i = 0; _i < 2; ++_i) \
;         __builtin_amdgcn_global_load_lds((const unsigned*)((const char*)(gbase) + (voff)[_i]), (PG8_LAS unsigned*)(lds + (bufoff) + ldsw + _i * 8192), 16, 0, 0); } while (0)
; #define PG8_LDA(dst, b, h) do { _Pragma("unroll") for (int m = 0; m < 4; ++m) _Pragma("unroll") for (int k = 0; k < 2; ++k) dst[m][k] = *(const PG8_LAS bf16x8*)(lds + PG8_SA(b, h) + aoff + m * 2048 + k * 1024); } while (0)
; #define PG8_LDB(dst, b, h) do { _Pragma("unroll") for (int n = 0; n < 2; ++n) _Pragma("unroll") for (int k = 0; k < 2; ++k) dst[n][k] = *(const PG8_LAS bf16x8*)(lds + PG8_SB(b, h) + boff + n * 2048 + k * 1024); } while (0)
; #define PG8_MMA(ai, bj, At, Bt) do { __builtin_amdgcn_s_setprio(1); _Pragma("unroll") for (int m = 0; m < 4; ++m) _Pragma("unroll") for (int n = 0; n < 2; ++n) _Pragma("unroll") for (int k = 0; k < 2; ++k) \
;         acc[ai][bj][m][n] = __builtin_amdgcn_mfma_f32_16x16x32_bf16(Bt[n][k], At[m][k], acc[ai][bj][m][n], 0, 0, 0); __builtin_amdgcn_s_setprio(0); } while (0)
; #define PG8_WAIT_V(n) asm volatile("s_waitcnt vmcnt(" #n ")" ::: "memory")
; #define PG8_WAIT_L(n) asm volatile("s_waitcnt lgkmcnt(" #n ")" ::: "memory")
; #define PG8_BAR __builtin_amdgcn_s_barrier()
; #define PG8_SCHED __builtin_amdgcn_sched_barrier(0)
; template <class Epi, class Sched, bool ALIGN_EPI = false, bool SP2 = false>
; __device__ __forceinline__ void gemm_phase(PG8_LAS unsigned char* lds, const Gemm g, const Sched& S, const Epi& E) {
;     ...
;             PG8_LDA(At, 0, 1); PG8_STAGE(PG8_SB(0, 0), b2, voffB); PG8_STAGE(PG8_SB(0, 1), b2 + hstep, voffB); PG8_STAGE(PG8_SA(0, 0), a2, voffA);
;             PG8_WAIT_V(8); PG8_WAIT_L(0); PG8_BAR; PG8_MMA(1, 0, At, B0); PG8_MMA(1, 1, At, B1); PG8_BAR; PG8_SCHED;
;             PG8_LDB(B0, 1, 0); PG8_LDB(B1, 1, 1); PG8_SCHED; PG8_LDA(At, 1, 0); PG8_STAGE(PG8_SA(0, 1), a2 + hstep, voffA);
;             PG8_WAIT_V(8); PG8_WAIT_L(0); PG8_BAR; PG8_MMA(0, 0, At, B0); PG8_MMA(0, 1, At, B1); PG8_BAR; PG8_SCHED;
	v_mfma_f32_16x16x32_bf16 v[56:59], v[144:147], v[184:187], 0
	v_mfma_f32_16x16x32_bf16 v[48:51], v[160:163], v[184:187], 0
	v_mfma_f32_16x16x32_bf16 v[40:43], v[144:147], v[194:197], 0
	v_mfma_f32_16x16x32_bf16 v[32:35], v[160:163], v[194:197], 0
	v_mfma_f32_16x16x32_bf16 v[24:27], v[144:147], v[202:205], 0
	v_mfma_f32_16x16x32_bf16 v[16:19], v[160:163], v[202:205], 0
	v_mfma_f32_16x16x32_bf16 v[8:11], v[144:147], v[210:213], 0
	v_mfma_f32_16x16x32_bf16 v[0:3], v[160:163], v[210:213], 0
	v_mfma_f32_16x16x32_bf16 v[56:59], v[156:159], v[190:193], v[56:59]
	v_mfma_f32_16x16x32_bf16 v[48:51], v[164:167], v[190:193], v[48:51]
	v_mfma_f32_16x16x32_bf16 v[40:43], v[156:159], v[198:201], v[40:43]
	v_mfma_f32_16x16x32_bf16 v[32:35], v[164:167], v[198:201], v[32:35]
	v_mfma_f32_16x16x32_bf16 v[24:27], v[156:159], v[206:209], v[24:27]
	v_mfma_f32_16x16x32_bf16 v[16:19], v[164:167], v[206:209], v[16:19]
	v_mfma_f32_16x16x32_bf16 v[8:11], v[156:159], v[214:217], v[8:11]
	v_mfma_f32_16x16x32_bf16 v[0:3], v[164:167], v[214:217], v[0:3]
	v_mfma_f32_16x16x32_bf16 v[60:63], v[168:171], v[184:187], 0
	v_mfma_f32_16x16x32_bf16 v[52:55], v[176:179], v[184:187], 0
	v_mfma_f32_16x16x32_bf16 v[44:47], v[168:171], v[194:197], 0
	v_mfma_f32_16x16x32_bf16 v[36:39], v[176:179], v[194:197], 0
	v_mfma_f32_16x16x32_bf16 v[28:31], v[168:171], v[202:205], 0
	v_mfma_f32_16x16x32_bf16 v[20:23], v[176:179], v[202:205], 0
	v_mfma_f32_16x16x32_bf16 v[12:15], v[168:171], v[210:213], 0
	v_mfma_f32_16x16x32_bf16 v[4:7], v[176:179], v[210:213], 0
	v_mfma_f32_16x16x32_bf16 v[60:63], v[172:175], v[190:193], v[60:63]
	v_mfma_f32_16x16x32_bf16 v[52:55], v[180:183], v[190:193], v[52:55]
	v_mfma_f32_16x16x32_bf16 v[44:47], v[172:175], v[198:201], v[44:47]
	v_mfma_f32_16x16x32_bf16 v[36:39], v[180:183], v[198:201], v[36:39]
	v_mfma_f32_16x16x32_bf16 v[28:31], v[172:175], v[206:209], v[28:31]
	v_mfma_f32_16x16x32_bf16 v[20:23], v[180:183], v[206:209], v[20:23]
	v_mfma_f32_16x16x32_bf16 v[12:15], v[172:175], v[214:217], v[12:15]
	v_mfma_f32_16x16x32_bf16 v[4:7], v[180:183], v[214:217], v[4:7]
	s_barrier
	s_setprio 0
	s_add_i32 s52, 0, 0x18000
	v_add_u32_e32 v155, s52, v149
	s_add_i32 s53, 0, 0x1c000
	ds_read_b128 v[144:147], v155
	ds_read_b128 v[156:159], v155 offset:1024
	ds_read_b128 v[160:163], v155 offset:2048
	ds_read_b128 v[164:167], v155 offset:3072
	v_add_u32_e32 v155, s53, v149
	ds_read_b128 v[168:171], v155
	ds_read_b128 v[172:175], v155 offset:1024
	ds_read_b128 v[176:179], v155 offset:2048
	ds_read_b128 v[180:183], v155 offset:3072
	s_add_u32 s26, s26, 0x40000
	s_addc_u32 s27, s27, 0
	s_mov_b32 m0, s36
	ds_read_b128 v[184:187], v153 offset:32768
	ds_read_b128 v[190:193], v153 offset:33792
	ds_read_b128 v[194:197], v153 offset:34816
	ds_read_b128 v[198:201], v153 offset:35840
	ds_read_b128 v[202:205], v153 offset:36864
	ds_read_b128 v[206:209], v153 offset:37888
	ds_read_b128 v[210:213], v153 offset:38912
	ds_read_b128 v[214:217], v153 offset:39936
	global_load_lds_dwordx4 v134, s[26:27]
	v_lshl_add_u64 v[226:227], s[26:27], 0, v[130:131]
	s_mov_b32 m0, s37
	s_nop 0
	global_load_lds_dwordx4 v[226:227], off
	s_waitcnt vmcnt(8)
	s_waitcnt lgkmcnt(0)
	s_setprio 1
	s_barrier
	v_mfma_f32_16x16x32_bf16 v[116:119], v[144:147], v[184:187], v[116:119]
	v_mfma_f32_16x16x32_bf16 v[112:115], v[160:163], v[184:187], v[112:115]
	v_mfma_f32_16x16x32_bf16 v[100:103], v[144:147], v[194:197], v[100:103]
	v_mfma_f32_16x16x32_bf16 v[96:99], v[160:163], v[194:197], v[96:99]
	v_mfma_f32_16x16x32_bf16 v[84:87], v[144:147], v[202:205], v[84:87]
	v_mfma_f32_16x16x32_bf16 v[80:83], v[160:163], v[202:205], v[80:83]
	v_mfma_f32_16x16x32_bf16 v[72:75], v[144:147], v[210:213], v[72:75]
	v_mfma_f32_16x16x32_bf16 v[64:67], v[160:163], v[210:213], v[64:67]
	v_mfma_f32_16x16x32_bf16 v[116:119], v[156:159], v[190:193], v[116:119]
	v_mfma_f32_16x16x32_bf16 v[112:115], v[164:167], v[190:193], v[112:115]
	v_mfma_f32_16x16x32_bf16 v[100:103], v[156:159], v[198:201], v[100:103]
	v_mfma_f32_16x16x32_bf16 v[96:99], v[164:167], v[198:201], v[96:99]
	v_mfma_f32_16x16x32_bf16 v[84:87], v[156:159], v[206:209], v[84:87]
	v_mfma_f32_16x16x32_bf16 v[80:83], v[164:167], v[206:209], v[80:83]
	v_mfma_f32_16x16x32_bf16 v[72:75], v[156:159], v[214:217], v[72:75]
	v_mfma_f32_16x16x32_bf16 v[64:67], v[164:167], v[214:217], v[64:67]
	v_mfma_f32_16x16x32_bf16 v[124:127], v[168:171], v[184:187], v[124:127]
	v_mfma_f32_16x16x32_bf16 v[120:123], v[176:179], v[184:187], v[120:123]
	v_mfma_f32_16x16x32_bf16 v[108:111], v[168:171], v[194:197], v[108:111]
	v_mfma_f32_16x16x32_bf16 v[104:107], v[176:179], v[194:197], v[104:107]
	v_mfma_f32_16x16x32_bf16 v[92:95], v[168:171], v[202:205], v[92:95]
	v_mfma_f32_16x16x32_bf16 v[88:91], v[176:179], v[202:205], v[88:91]
	v_mfma_f32_16x16x32_bf16 v[76:79], v[168:171], v[210:213], v[76:79]
	v_mfma_f32_16x16x32_bf16 v[68:71], v[176:179], v[210:213], v[68:71]
	v_mfma_f32_16x16x32_bf16 v[124:127], v[172:175], v[190:193], v[124:127]
	v_mfma_f32_16x16x32_bf16 v[120:123], v[180:183], v[190:193], v[120:123]
	v_mfma_f32_16x16x32_bf16 v[108:111], v[172:175], v[198:201], v[108:111]
	v_mfma_f32_16x16x32_bf16 v[104:107], v[180:183], v[198:201], v[104:107]
	v_mfma_f32_16x16x32_bf16 v[92:95], v[172:175], v[206:209], v[92:95]
	v_mfma_f32_16x16x32_bf16 v[88:91], v[180:183], v[206:209], v[88:91]
	v_mfma_f32_16x16x32_bf16 v[76:79], v[172:175], v[214:217], v[76:79]
	v_mfma_f32_16x16x32_bf16 v[68:71], v[180:183], v[214:217], v[68:71]
	s_barrier
; #define PG8_STAGE(bufoff, gbase, voff) do { _Pragma("unroll") for (int _i = 0; _i < 2; ++_i) \
;         __builtin_amdgcn_global_load_lds((const unsigned*)((const char*)(gbase) + (voff)[_i]), (PG8_LAS unsigned*)(lds + (bufoff) + ldsw + _i * 8192), 16, 0, 0); } while (0)
; #define PG8_LDA(dst, b, h) do { _Pragma("unroll") for (int m = 0; m < 4; ++m) _Pragma("unroll") for (int k = 0; k < 2; ++k) dst[m][k] = *(const PG8_LAS bf16x8*)(lds + PG8_SA(b, h) + aoff + m * 2048 + k * 1024); } while (0)
; #define PG8_LDB(dst, b, h) do { _Pragma("unroll") for (int n = 0; n < 2; ++n) _Pragma("unroll") for (int k = 0; k < 2; ++k) dst[n][k] = *(const PG8_LAS bf16x8*)(lds + PG8_SB(b, h) + boff + n * 2048 + k * 1024); } while (0)
; #define PG8_MMA(ai, bj, At, Bt) do { __builtin_amdgcn_s_setprio(1); _Pragma("unroll") for (int m = 0; m < 4; ++m) _Pragma("unroll") for (int n = 0; n < 2; ++n) _Pragma("unroll") for (int k = 0; k < 2; ++k) \
;         acc[ai][bj][m][n] = __builtin_amdgcn_mfma_f32_16x16x32_bf16(Bt[n][k], At[m][k], acc[ai][bj][m][n], 0, 0, 0); __builtin_amdgcn_s_setprio(0); } while (0)
; #define PG8_WAIT_V(n) asm volatile("s_waitcnt vmcnt(" #n ")" ::: "memory")
; template <class Epi, class Sched, bool ALIGN_EPI = false, bool SP2 = false>
; __device__ __forceinline__ void gemm_phase(PG8_LAS unsigned char* lds, const Gemm g, const Sched& S, const Epi& E) {
;     ...
;             PG8_LDB(B0, 0, 0); PG8_LDB(B1, 0, 1); PG8_SCHED; PG8_LDA(At, 0, 0); PG8_STAGE(PG8_SA(1, 1), a1 + hstep, voffA);
;             PG8_WAIT_V(8); PG8_WAIT_L(0); PG8_BAR; PG8_MMA(0, 0, At, B0); PG8_MMA(0, 1, At, B1); PG8_BAR; PG8_SCHED;
;             PG8_LDA(At, 0, 1); PG8_STAGE(PG8_SB(0, 0), b2, voffB); PG8_STAGE(PG8_SB(0, 1), b2 + hstep, voffB); PG8_STAGE(PG8_SA(0, 0), a2, voffA);
;             PG8_WAIT_V(8); PG8_WAIT_L(0); PG8_BAR; PG8_MMA(1, 0, At, B0); PG8_MMA(1, 1, At, B1); PG8_BAR; PG8_SCHED;
;             PG8_LDB(B0, 1, 0); PG8_LDB(B1, 1, 1); PG8_SCHED; PG8_LDA(At, 1, 0); PG8_STAGE(PG8_SA(0, 1), a2 + hstep, voffA);
;             PG8_WAIT_V(8); PG8_WAIT_L(0); PG8_BAR; PG8_MMA(0, 0, At, B0); PG8_MMA(0, 1, At, B1); PG8_BAR; PG8_SCHED;
;             PG8_LDA(At, 1, 1); PG8_STAGE(PG8_SB(1, 0), b3, voffB); PG8_STAGE(PG8_SB(1, 1), b3 + hstep, voffB); PG8_STAGE(PG8_SA(1, 0), a3, voffA);
;             PG8_WAIT_V(8); PG8_WAIT_L(0); PG8_BAR; PG8_MMA(1, 0, At, B0); PG8_MMA(1, 1, At, B1); PG8_BAR; PG8_SCHED;
	s_setprio 0
	s_add_i32 s26, s52, s30
	v_lshl_add_u64 v[218:219], v[218:219], 0, s[6:7]
	s_mov_b32 m0, s26
	ds_read_b128 v[184:187], v153 offset:49152
	ds_read_b128 v[190:193], v153 offset:50176
	ds_read_b128 v[194:197], v153 offset:51200
	ds_read_b128 v[198:201], v153 offset:52224
	ds_read_b128 v[202:205], v153 offset:53248
	ds_read_b128 v[206:209], v153 offset:54272
	ds_read_b128 v[210:213], v153 offset:55296
	ds_read_b128 v[214:217], v153 offset:56320
	global_load_lds_dwordx4 v[218:219], off
	s_add_i32 m0, s26, 0x2000
	s_add_u32 s24, s24, 0x40080
	v_lshl_add_u64 v[218:219], v[220:221], 0, s[6:7]
	s_addc_u32 s25, s25, 0
	s_add_i32 s26, s53, s30
	global_load_lds_dwordx4 v[218:219], off
	s_mov_b32 m0, s26
	s_nop 0
	global_load_lds_dwordx4 v132, s[24:25]
	s_add_i32 m0, s26, 0x2000
	s_nop 0
	global_load_lds_dwordx4 v128, s[24:25]
	v_lshl_add_u64 v[218:219], v[222:223], 0, s[6:7]
	s_mov_b32 m0, s39
	s_nop 0
	global_load_lds_dwordx4 v[218:219], off
	v_lshl_add_u64 v[218:219], v[224:225], 0, s[6:7]
	s_mov_b32 m0, s40
	s_nop 0
	global_load_lds_dwordx4 v[218:219], off
	s_waitcnt vmcnt(8)
	s_waitcnt lgkmcnt(0)
	s_setprio 1
	s_barrier
	v_mfma_f32_16x16x32_bf16 v[56:59], v[144:147], v[184:187], v[56:59]
	v_mfma_f32_16x16x32_bf16 v[48:51], v[160:163], v[184:187], v[48:51]
	v_mfma_f32_16x16x32_bf16 v[40:43], v[144:147], v[194:197], v[40:43]
	v_mfma_f32_16x16x32_bf16 v[32:35], v[160:163], v[194:197], v[32:35]
	v_mfma_f32_16x16x32_bf16 v[24:27], v[144:147], v[202:205], v[24:27]
	v_mfma_f32_16x16x32_bf16 v[16:19], v[160:163], v[202:205], v[16:19]
	v_mfma_f32_16x16x32_bf16 v[8:11], v[144:147], v[210:213], v[8:11]
	v_mfma_f32_16x16x32_bf16 v[0:3], v[160:163], v[210:213], v[0:3]
	v_mfma_f32_16x16x32_bf16 v[56:59], v[156:159], v[190:193], v[56:59]
	v_mfma_f32_16x16x32_bf16 v[48:51], v[164:167], v[190:193], v[48:51]
	v_mfma_f32_16x16x32_bf16 v[40:43], v[156:159], v[198:201], v[40:43]
	v_mfma_f32_16x16x32_bf16 v[32:35], v[164:167], v[198:201], v[32:35]
	v_mfma_f32_16x16x32_bf16 v[24:27], v[156:159], v[206:209], v[24:27]
	v_mfma_f32_16x16x32_bf16 v[16:19], v[164:167], v[206:209], v[16:19]
	v_mfma_f32_16x16x32_bf16 v[8:11], v[156:159], v[214:217], v[8:11]
	v_mfma_f32_16x16x32_bf16 v[0:3], v[164:167], v[214:217], v[0:3]
	v_mfma_f32_16x16x32_bf16 v[60:63], v[168:171], v[184:187], v[60:63]
	v_mfma_f32_16x16x32_bf16 v[52:55], v[176:179], v[184:187], v[52:55]
	v_mfma_f32_16x16x32_bf16 v[44:47], v[168:171], v[194:197], v[44:47]
	v_mfma_f32_16x16x32_bf16 v[36:39], v[176:179], v[194:197], v[36:39]
	v_mfma_f32_16x16x32_bf16 v[28:31], v[168:171], v[202:205], v[28:31]
	v_mfma_f32_16x16x32_bf16 v[20:23], v[176:179], v[202:205], v[20:23]
	v_mfma_f32_16x16x32_bf16 v[12:15], v[168:171], v[210:213], v[12:15]
	v_mfma_f32_16x16x32_bf16 v[4:7], v[176:179], v[210:213], v[4:7]
	v_mfma_f32_16x16x32_bf16 v[60:63], v[172:175], v[190:193], v[60:63]
	v_mfma_f32_16x16x32_bf16 v[52:55], v[180:183], v[190:193], v[52:55]
	v_mfma_f32_16x16x32_bf16 v[44:47], v[172:175], v[198:201], v[44:47]
	v_mfma_f32_16x16x32_bf16 v[36:39], v[180:183], v[198:201], v[36:39]
	v_mfma_f32_16x16x32_bf16 v[28:31], v[172:175], v[206:209], v[28:31]
	v_mfma_f32_16x16x32_bf16 v[20:23], v[180:183], v[206:209], v[20:23]
	v_mfma_f32_16x16x32_bf16 v[12:15], v[172:175], v[214:217], v[12:15]
	v_mfma_f32_16x16x32_bf16 v[4:7], v[180:183], v[214:217], v[4:7]
	s_barrier
	s_setprio 0
	s_add_i32 s51, s51, 2
	s_add_u32 s22, s22, 0x100
	s_addc_u32 s23, s23, 0
	s_add_u32 s49, s49, 0x100
	s_addc_u32 s50, s50, 0
.LBB0_782:
	ds_read_b128 v[144:147], v151
	ds_read_b128 v[156:159], v151 offset:1024
	ds_read_b128 v[160:163], v151 offset:2048
	ds_read_b128 v[164:167], v151 offset:3072
	ds_read_b128 v[168:171], v152
	ds_read_b128 v[172:175], v152 offset:1024
	ds_read_b128 v[176:179], v152 offset:2048
	ds_read_b128 v[180:183], v152 offset:3072
	s_add_u32 s24, s22, 0xfffc0080
	s_addc_u32 s25, s23, -1
	s_cmp_eq_u32 s51, 12
	s_cselect_b32 s27, s17, s25
	s_cselect_b32 s26, s47, s24
	s_cselect_b32 s25, s15, s50
	s_cselect_b32 s24, s48, s49
	s_add_i32 m0, s34, 0xc000
	ds_read_b128 v[184:187], v153
	ds_read_b128 v[190:193], v153 offset:1024
	ds_read_b128 v[194:197], v153 offset:2048
	ds_read_b128 v[198:201], v153 offset:3072
	ds_read_b128 v[202:205], v153 offset:4096
	ds_read_b128 v[206:209], v153 offset:5120
	ds_read_b128 v[210:213], v153 offset:6144
	ds_read_b128 v[214:217], v153 offset:7168
	global_load_lds_dwordx4 v136, s[22:23]
	s_add_i32 m0, s34, 0xe000
	s_nop 0
	global_load_lds_dwordx4 v138, s[22:23]
	s_waitcnt vmcnt(8)
	s_waitcnt lgkmcnt(0)
	s_setprio 1
	s_barrier
; #define PG8_STAGE(bufoff, gbase, voff) do { _Pragma("unroll") for (int _i = 0; _i < 2; ++_i) \
;         __builtin_amdgcn_global_load_lds((const unsigned*)((const char*)(gbase) + (voff)[_i]), (PG8_LAS unsigned*)(lds + (bufoff) + ldsw + _i * 8192), 16, 0, 0); } while (0)
; #define PG8_LDA(dst, b, h) do { _Pragma("unroll") for (int m = 0; m < 4; ++m) _Pragma("unroll") for (int k = 0; k < 2; ++k) dst[m][k] = *(const PG8_LAS bf16x8*)(lds + PG8_SA(b, h) + aoff + m * 2048 + k * 1024); } while (0)
; #define PG8_LDB(dst, b, h) do { _Pragma("unroll") for (int n = 0; n < 2; ++n) _Pragma("unroll") for (int k = 0; k < 2; ++k) dst[n][k] = *(const PG8_LAS bf16x8*)(lds + PG8_SB(b, h) + boff + n * 2048 + k * 1024); } while (0)
; #define PG8_MMA(ai, bj, At, Bt) do { __builtin_amdgcn_s_setprio(1); _Pragma("unroll") for (int m = 0; m < 4; ++m) _Pragma("unroll") for (int n = 0; n < 2; ++n) _Pragma("unroll") for (int k = 0; k < 2; ++k) \
;         acc[ai][bj][m][n] = __builtin_amdgcn_mfma_f32_16x16x32_bf16(Bt[n][k], At[m][k], acc[ai][bj][m][n], 0, 0, 0); __builtin_amdgcn_s_setprio(0); } while (0)
; #define PG8_WAIT_V(n) asm volatile("s_waitcnt vmcnt(" #n ")" ::: "memory")
; #define PG8_WAIT_L(n) asm volatile("s_waitcnt lgkmcnt(" #n ")" ::: "memory")
; #define PG8_BAR __builtin_amdgcn_s_barrier()
; #define PG8_SCHED __builtin_amdgcn_sched_barrier(0)
; template <class Epi, class Sched, bool ALIGN_EPI = false, bool SP2 = false>
; __device__ __forceinline__ void gemm_phase(PG8_LAS unsigned char* lds, const Gemm g, const Sched& S, const Epi& E) {
;     ...
;             PG8_LDB(B0, 0, 0); PG8_LDB(B1, 0, 1); PG8_SCHED; PG8_LDA(At, 0, 0); PG8_STAGE(PG8_SA(1, 1), a1 + hstep, voffA);
;             PG8_WAIT_V(8); PG8_WAIT_L(0); PG8_BAR; PG8_MMA(0, 0, At, B0); PG8_MMA(0, 1, At, B1); PG8_BAR; PG8_SCHED;
;             PG8_LDA(At, 0, 1); PG8_STAGE(PG8_SB(0, 0), b2, voffB); PG8_STAGE(PG8_SB(0, 1), b2 + hstep, voffB); PG8_STAGE(PG8_SA(0, 0), a2, voffA);
;             PG8_WAIT_V(8); PG8_WAIT_L(0); PG8_BAR; PG8_MMA(1, 0, At, B0); PG8_MMA(1, 1, At, B1); PG8_BAR; PG8_SCHED;
	v_mfma_f32_16x16x32_bf16 v[116:119], v[144:147], v[184:187], v[116:119]
	v_mfma_f32_16x16x32_bf16 v[112:115], v[160:163], v[184:187], v[112:115]
	v_mfma_f32_16x16x32_bf16 v[100:103], v[144:147], v[194:197], v[100:103]
	v_mfma_f32_16x16x32_bf16 v[96:99], v[160:163], v[194:197], v[96:99]
	v_mfma_f32_16x16x32_bf16 v[84:87], v[144:147], v[202:205], v[84:87]
	v_mfma_f32_16x16x32_bf16 v[80:83], v[160:163], v[202:205], v[80:83]
	v_mfma_f32_16x16x32_bf16 v[72:75], v[144:147], v[210:213], v[72:75]
	v_mfma_f32_16x16x32_bf16 v[64:67], v[160:163], v[210:213], v[64:67]
	v_mfma_f32_16x16x32_bf16 v[116:119], v[156:159], v[190:193], v[116:119]
	v_mfma_f32_16x16x32_bf16 v[112:115], v[164:167], v[190:193], v[112:115]
	v_mfma_f32_16x16x32_bf16 v[100:103], v[156:159], v[198:201], v[100:103]
	v_mfma_f32_16x16x32_bf16 v[96:99], v[164:167], v[198:201], v[96:99]
	v_mfma_f32_16x16x32_bf16 v[84:87], v[156:159], v[206:209], v[84:87]
	v_mfma_f32_16x16x32_bf16 v[80:83], v[164:167], v[206:209], v[80:83]
	v_mfma_f32_16x16x32_bf16 v[72:75], v[156:159], v[214:217], v[72:75]
	v_mfma_f32_16x16x32_bf16 v[64:67], v[164:167], v[214:217], v[64:67]
	v_mfma_f32_16x16x32_bf16 v[124:127], v[168:171], v[184:187], v[124:127]
	v_mfma_f32_16x16x32_bf16 v[120:123], v[176:179], v[184:187], v[120:123]
	v_mfma_f32_16x16x32_bf16 v[108:111], v[168:171], v[194:197], v[108:111]
	v_mfma_f32_16x16x32_bf16 v[104:107], v[176:179], v[194:197], v[104:107]
	v_mfma_f32_16x16x32_bf16 v[92:95], v[168:171], v[202:205], v[92:95]
	v_mfma_f32_16x16x32_bf16 v[88:91], v[176:179], v[202:205], v[88:91]
	v_mfma_f32_16x16x32_bf16 v[76:79], v[168:171], v[210:213], v[76:79]
	v_mfma_f32_16x16x32_bf16 v[68:71], v[176:179], v[210:213], v[68:71]
	v_mfma_f32_16x16x32_bf16 v[124:127], v[172:175], v[190:193], v[124:127]
	v_mfma_f32_16x16x32_bf16 v[120:123], v[180:183], v[190:193], v[120:123]
	v_mfma_f32_16x16x32_bf16 v[108:111], v[172:175], v[198:201], v[108:111]
	v_mfma_f32_16x16x32_bf16 v[104:107], v[180:183], v[198:201], v[104:107]
	v_mfma_f32_16x16x32_bf16 v[92:95], v[172:175], v[206:209], v[92:95]
	v_mfma_f32_16x16x32_bf16 v[88:91], v[180:183], v[206:209], v[88:91]
	v_mfma_f32_16x16x32_bf16 v[76:79], v[172:175], v[214:217], v[76:79]
	v_mfma_f32_16x16x32_bf16 v[68:71], v[180:183], v[214:217], v[68:71]
	s_barrier
	s_setprio 0
	s_add_i32 s52, s43, s30
	v_lshl_add_u64 v[218:219], s[24:25], 0, v[132:133]
	s_mov_b32 m0, s52
	ds_read_b128 v[184:187], v153 offset:16384
	ds_read_b128 v[190:193], v153 offset:17408
	ds_read_b128 v[194:197], v153 offset:18432
	ds_read_b128 v[198:201], v153 offset:19456
	ds_read_b128 v[202:205], v153 offset:20480
	ds_read_b128 v[206:209], v153 offset:21504
	ds_read_b128 v[210:213], v153 offset:22528
	ds_read_b128 v[214:217], v153 offset:23552
	global_load_lds_dwordx4 v[218:219], off
	s_add_i32 m0, s52, 0x2000
	s_add_u32 s52, s24, 0x40000
	v_lshl_add_u64 v[220:221], s[24:25], 0, v[128:129]
	s_addc_u32 s53, s25, 0
	s_add_i32 s54, s44, s30
	global_load_lds_dwordx4 v[220:221], off
	s_mov_b32 m0, s54
	v_lshl_add_u64 v[224:225], s[26:27], 0, v[130:131]
	global_load_lds_dwordx4 v132, s[52:53]
	s_add_i32 m0, s54, 0x2000
	s_nop 0
	global_load_lds_dwordx4 v128, s[52:53]
	v_lshl_add_u64 v[222:223], s[26:27], 0, v[134:135]
	s_mov_b32 m0, s34
	s_nop 0
	global_load_lds_dwordx4 v[222:223], off
	s_mov_b32 m0, s35
	s_nop 0
	global_load_lds_dwordx4 v[224:225], off
	s_waitcnt vmcnt(8)
	s_waitcnt lgkmcnt(0)
	s_setprio 1
	s_barrier
	v_mfma_f32_16x16x32_bf16 v[56:59], v[144:147], v[184:187], v[56:59]
	v_mfma_f32_16x16x32_bf16 v[48:51], v[160:163], v[184:187], v[48:51]
	v_mfma_f32_16x16x32_bf16 v[40:43], v[144:147], v[194:197], v[40:43]
	v_mfma_f32_16x16x32_bf16 v[32:35], v[160:163], v[194:197], v[32:35]
	v_mfma_f32_16x16x32_bf16 v[24:27], v[144:147], v[202:205], v[24:27]
	v_mfma_f32_16x16x32_bf16 v[16:19], v[160:163], v[202:205], v[16:19]
	v_mfma_f32_16x16x32_bf16 v[8:11], v[144:147], v[210:213], v[8:11]
	v_mfma_f32_16x16x32_bf16 v[0:3], v[160:163], v[210:213], v[0:3]
	v_mfma_f32_16x16x32_bf16 v[56:59], v[156:159], v[190:193], v[56:59]
	v_mfma_f32_16x16x32_bf16 v[48:51], v[164:167], v[190:193], v[48:51]
	v_mfma_f32_16x16x32_bf16 v[40:43], v[156:159], v[198:201], v[40:43]
	v_mfma_f32_16x16x32_bf16 v[32:35], v[164:167], v[198:201], v[32:35]
	v_mfma_f32_16x16x32_bf16 v[24:27], v[156:159], v[206:209], v[24:27]
	v_mfma_f32_16x16x32_bf16 v[16:19], v[164:167], v[206:209], v[16:19]
	v_mfma_f32_16x16x32_bf16 v[8:11], v[156:159], v[214:217], v[8:11]
	v_mfma_f32_16x16x32_bf16 v[0:3], v[164:167], v[214:217], v[0:3]
	v_mfma_f32_16x16x32_bf16 v[60:63], v[168:171], v[184:187], v[60:63]
	v_mfma_f32_16x16x32_bf16 v[52:55], v[176:179], v[184:187], v[52:55]
	v_mfma_f32_16x16x32_bf16 v[44:47], v[168:171], v[194:197], v[44:47]
	v_mfma_f32_16x16x32_bf16 v[36:39], v[176:179], v[194:197], v[36:39]
	v_mfma_f32_16x16x32_bf16 v[28:31], v[168:171], v[202:205], v[28:31]
	v_mfma_f32_16x16x32_bf16 v[20:23], v[176:179], v[202:205], v[20:23]
	v_mfma_f32_16x16x32_bf16 v[12:15], v[168:171], v[210:213], v[12:15]
	v_mfma_f32_16x16x32_bf16 v[4:7], v[176:179], v[210:213], v[4:7]
	v_mfma_f32_16x16x32_bf16 v[60:63], v[172:175], v[190:193], v[60:63]
	v_mfma_f32_16x16x32_bf16 v[52:55], v[180:183], v[190:193], v[52:55]
	v_mfma_f32_16x16x32_bf16 v[44:47], v[172:175], v[198:201], v[44:47]
	v_mfma_f32_16x16x32_bf16 v[36:39], v[180:183], v[198:201], v[36:39]
	v_mfma_f32_16x16x32_bf16 v[28:31], v[172:175], v[206:209], v[28:31]
	v_mfma_f32_16x16x32_bf16 v[20:23], v[180:183], v[206:209], v[20:23]
	v_mfma_f32_16x16x32_bf16 v[12:15], v[172:175], v[214:217], v[12:15]
	v_mfma_f32_16x16x32_bf16 v[4:7], v[180:183], v[214:217], v[4:7]
	s_barrier
; #define PG8_STAGE(bufoff, gbase, voff) do { _Pragma("unroll") for (int _i = 0; _i < 2; ++_i) \
;         __builtin_amdgcn_global_load_lds((const unsigned*)((const char*)(gbase) + (voff)[_i]), (PG8_LAS unsigned*)(lds + (bufoff) + ldsw + _i * 8192), 16, 0, 0); } while (0)
; #define PG8_LDA(dst, b, h) do { _Pragma("unroll") for (int m = 0; m < 4; ++m) _Pragma("unroll") for (int k = 0; k < 2; ++k) dst[m][k] = *(const PG8_LAS bf16x8*)(lds + PG8_SA(b, h) + aoff + m * 2048 + k * 1024); } while (0)
; #define PG8_LDB(dst, b, h) do { _Pragma("unroll") for (int n = 0; n < 2; ++n) _Pragma("unroll") for (int k = 0; k < 2; ++k) dst[n][k] = *(const PG8_LAS bf16x8*)(lds + PG8_SB(b, h) + boff + n * 2048 + k * 1024); } while (0)
; #define PG8_MMA(ai, bj, At, Bt) do { __builtin_amdgcn_s_setprio(1); _Pragma("unroll") for (int m = 0; m < 4; ++m) _Pragma("unroll") for (int n = 0; n < 2; ++n) _Pragma("unroll") for (int k = 0; k < 2; ++k) \
;         acc[ai][bj][m][n] = __builtin_amdgcn_mfma_f32_16x16x32_bf16(Bt[n][k], At[m][k], acc[ai][bj][m][n], 0, 0, 0); __builtin_amdgcn_s_setprio(0); } while (0)
; #define PG8_WAIT_V(n) asm volatile("s_waitcnt vmcnt(" #n ")" ::: "memory")
; #define PG8_WAIT_L(n) asm volatile("s_waitcnt lgkmcnt(" #n ")" ::: "memory")
; #define PG8_BAR __builtin_amdgcn_s_barrier()
; #define PG8_SCHED __builtin_amdgcn_sched_barrier(0)
; template <class Epi, class Sched, bool ALIGN_EPI = false, bool SP2 = false>
; __device__ __forceinline__ void gemm_phase(PG8_LAS unsigned char* lds, const Gemm g, const Sched& S, const Epi& E) {
;     ...
;         for (int t = 0; t < nt; t += 2) {
;     ...
;             PG8_LDB(B0, 1, 0); PG8_LDB(B1, 1, 1); PG8_SCHED; PG8_LDA(At, 1, 0); PG8_STAGE(PG8_SA(0, 1), a2 + hstep, voffA);
;             PG8_WAIT_V(8); PG8_WAIT_L(0); PG8_BAR; PG8_MMA(0, 0, At, B0); PG8_MMA(0, 1, At, B1); PG8_BAR; PG8_SCHED;
;             PG8_LDA(At, 1, 1); PG8_STAGE(PG8_SB(1, 0), b3, voffB); PG8_STAGE(PG8_SB(1, 1), b3 + hstep, voffB); PG8_STAGE(PG8_SA(1, 0), a3, voffA);
;             PG8_WAIT_V(8); PG8_WAIT_L(0); PG8_BAR; PG8_MMA(1, 0, At, B0); PG8_MMA(1, 1, At, B1); PG8_BAR; PG8_SCHED;
	s_setprio 0
	s_add_i32 s52, 0, 0x18000
	v_add_u32_e32 v155, s52, v149
	s_add_i32 s53, 0, 0x1c000
	ds_read_b128 v[144:147], v155
	ds_read_b128 v[156:159], v155 offset:1024
	ds_read_b128 v[160:163], v155 offset:2048
	ds_read_b128 v[164:167], v155 offset:3072
	v_add_u32_e32 v155, s53, v149
	ds_read_b128 v[168:171], v155
	ds_read_b128 v[172:175], v155 offset:1024
	ds_read_b128 v[176:179], v155 offset:2048
	ds_read_b128 v[180:183], v155 offset:3072
	s_add_u32 s26, s26, 0x40000
	s_addc_u32 s27, s27, 0
	s_mov_b32 m0, s36
	ds_read_b128 v[184:187], v153 offset:32768
	ds_read_b128 v[190:193], v153 offset:33792
	ds_read_b128 v[194:197], v153 offset:34816
	ds_read_b128 v[198:201], v153 offset:35840
	ds_read_b128 v[202:205], v153 offset:36864
	ds_read_b128 v[206:209], v153 offset:37888
	ds_read_b128 v[210:213], v153 offset:38912
	ds_read_b128 v[214:217], v153 offset:39936
	global_load_lds_dwordx4 v134, s[26:27]
	v_lshl_add_u64 v[226:227], s[26:27], 0, v[130:131]
	s_mov_b32 m0, s37
	s_nop 0
	global_load_lds_dwordx4 v[226:227], off
	s_waitcnt vmcnt(8)
	s_waitcnt lgkmcnt(0)
	s_setprio 1
	s_barrier
	v_mfma_f32_16x16x32_bf16 v[116:119], v[144:147], v[184:187], v[116:119]
	v_mfma_f32_16x16x32_bf16 v[112:115], v[160:163], v[184:187], v[112:115]
	v_mfma_f32_16x16x32_bf16 v[100:103], v[144:147], v[194:197], v[100:103]
	v_mfma_f32_16x16x32_bf16 v[96:99], v[160:163], v[194:197], v[96:99]
	v_mfma_f32_16x16x32_bf16 v[84:87], v[144:147], v[202:205], v[84:87]
	v_mfma_f32_16x16x32_bf16 v[80:83], v[160:163], v[202:205], v[80:83]
	v_mfma_f32_16x16x32_bf16 v[72:75], v[144:147], v[210:213], v[72:75]
	v_mfma_f32_16x16x32_bf16 v[64:67], v[160:163], v[210:213], v[64:67]
	v_mfma_f32_16x16x32_bf16 v[116:119], v[156:159], v[190:193], v[116:119]
	v_mfma_f32_16x16x32_bf16 v[112:115], v[164:167], v[190:193], v[112:115]
	v_mfma_f32_16x16x32_bf16 v[100:103], v[156:159], v[198:201], v[100:103]
	v_mfma_f32_16x16x32_bf16 v[96:99], v[164:167], v[198:201], v[96:99]
	v_mfma_f32_16x16x32_bf16 v[84:87], v[156:159], v[206:209], v[84:87]
	v_mfma_f32_16x16x32_bf16 v[80:83], v[164:167], v[206:209], v[80:83]
	v_mfma_f32_16x16x32_bf16 v[72:75], v[156:159], v[214:217], v[72:75]
	v_mfma_f32_16x16x32_bf16 v[64:67], v[164:167], v[214:217], v[64:67]
	v_mfma_f32_16x16x32_bf16 v[124:127], v[168:171], v[184:187], v[124:127]
	v_mfma_f32_16x16x32_bf16 v[120:123], v[176:179], v[184:187], v[120:123]
	v_mfma_f32_16x16x32_bf16 v[108:111], v[168:171], v[194:197], v[108:111]
	v_mfma_f32_16x16x32_bf16 v[104:107], v[176:179], v[194:197], v[104:107]
	v_mfma_f32_16x16x32_bf16 v[92:95], v[168:171], v[202:205], v[92:95]
	v_mfma_f32_16x16x32_bf16 v[88:91], v[176:179], v[202:205], v[88:91]
	v_mfma_f32_16x16x32_bf16 v[76:79], v[168:171], v[210:213], v[76:79]
	v_mfma_f32_16x16x32_bf16 v[68:71], v[176:179], v[210:213], v[68:71]
	v_mfma_f32_16x16x32_bf16 v[124:127], v[172:175], v[190:193], v[124:127]
	v_mfma_f32_16x16x32_bf16 v[120:123], v[180:183], v[190:193], v[120:123]
	v_mfma_f32_16x16x32_bf16 v[108:111], v[172:175], v[198:201], v[108:111]
	v_mfma_f32_16x16x32_bf16 v[104:107], v[180:183], v[198:201], v[104:107]
	v_mfma_f32_16x16x32_bf16 v[92:95], v[172:175], v[206:209], v[92:95]
	v_mfma_f32_16x16x32_bf16 v[88:91], v[180:183], v[206:209], v[88:91]
	v_mfma_f32_16x16x32_bf16 v[76:79], v[172:175], v[214:217], v[76:79]
	v_mfma_f32_16x16x32_bf16 v[68:71], v[180:183], v[214:217], v[68:71]
	s_barrier
	s_setprio 0
	s_add_i32 s26, s52, s30
	v_lshl_add_u64 v[218:219], v[218:219], 0, s[6:7]
	s_mov_b32 m0, s26
	ds_read_b128 v[184:187], v153 offset:49152
	ds_read_b128 v[190:193], v153 offset:50176
	ds_read_b128 v[194:197], v153 offset:51200
	ds_read_b128 v[198:201], v153 offset:52224
	ds_read_b128 v[202:205], v153 offset:53248
	ds_read_b128 v[206:209], v153 offset:54272
	ds_read_b128 v[210:213], v153 offset:55296
	ds_read_b128 v[214:217], v153 offset:56320
	global_load_lds_dwordx4 v[218:219], off
	s_add_i32 m0, s26, 0x2000
	s_add_u32 s24, s24, 0x40080
	v_lshl_add_u64 v[218:219], v[220:221], 0, s[6:7]
	s_addc_u32 s25, s25, 0
	s_add_i32 s26, s53, s30
	global_load_lds_dwordx4 v[218:219], off
	s_mov_b32 m0, s26
	s_nop 0
	global_load_lds_dwordx4 v132, s[24:25]
	s_add_i32 m0, s26, 0x2000
	s_nop 0
	global_load_lds_dwordx4 v128, s[24:25]
	v_lshl_add_u64 v[218:219], v[222:223], 0, s[6:7]
	s_mov_b32 m0, s39
	s_nop 0
	global_load_lds_dwordx4 v[218:219], off
	v_lshl_add_u64 v[218:219], v[224:225], 0, s[6:7]
	s_mov_b32 m0, s40
	s_nop 0
	global_load_lds_dwordx4 v[218:219], off
	s_waitcnt vmcnt(8)
	s_waitcnt lgkmcnt(0)
	s_setprio 1
	s_barrier
	v_mfma_f32_16x16x32_bf16 v[56:59], v[144:147], v[184:187], v[56:59]
	v_mfma_f32_16x16x32_bf16 v[48:51], v[160:163], v[184:187], v[48:51]
	v_mfma_f32_16x16x32_bf16 v[40:43], v[144:147], v[194:197], v[40:43]
	v_mfma_f32_16x16x32_bf16 v[32:35], v[160:163], v[194:197], v[32:35]
	v_mfma_f32_16x16x32_bf16 v[24:27], v[144:147], v[202:205], v[24:27]
	v_mfma_f32_16x16x32_bf16 v[16:19], v[160:163], v[202:205], v[16:19]
	v_mfma_f32_16x16x32_bf16 v[8:11], v[144:147], v[210:213], v[8:11]
	v_mfma_f32_16x16x32_bf16 v[0:3], v[160:163], v[210:213], v[0:3]
	v_mfma_f32_16x16x32_bf16 v[56:59], v[156:159], v[190:193], v[56:59]
	v_mfma_f32_16x16x32_bf16 v[48:51], v[164:167], v[190:193], v[48:51]
	v_mfma_f32_16x16x32_bf16 v[40:43], v[156:159], v[198:201], v[40:43]
	v_mfma_f32_16x16x32_bf16 v[32:35], v[164:167], v[198:201], v[32:35]
	v_mfma_f32_16x16x32_bf16 v[24:27], v[156:159], v[206:209], v[24:27]
	v_mfma_f32_16x16x32_bf16 v[16:19], v[164:167], v[206:209], v[16:19]
	v_mfma_f32_16x16x32_bf16 v[8:11], v[156:159], v[214:217], v[8:11]
	v_mfma_f32_16x16x32_bf16 v[0:3], v[164:167], v[214:217], v[0:3]
	v_mfma_f32_16x16x32_bf16 v[60:63], v[168:171], v[184:187], v[60:63]
	v_mfma_f32_16x16x32_bf16 v[52:55], v[176:179], v[184:187], v[52:55]
	v_mfma_f32_16x16x32_bf16 v[44:47], v[168:171], v[194:197], v[44:47]
	v_mfma_f32_16x16x32_bf16 v[36:39], v[176:179], v[194:197], v[36:39]
	v_mfma_f32_16x16x32_bf16 v[28:31], v[168:171], v[202:205], v[28:31]
	v_mfma_f32_16x16x32_bf16 v[20:23], v[176:179], v[202:205], v[20:23]
	v_mfma_f32_16x16x32_bf16 v[12:15], v[168:171], v[210:213], v[12:15]
	v_mfma_f32_16x16x32_bf16 v[4:7], v[176:179], v[210:213], v[4:7]
	v_mfma_f32_16x16x32_bf16 v[60:63], v[172:175], v[190:193], v[60:63]
	v_mfma_f32_16x16x32_bf16 v[52:55], v[180:183], v[190:193], v[52:55]
	v_mfma_f32_16x16x32_bf16 v[44:47], v[172:175], v[198:201], v[44:47]
	v_mfma_f32_16x16x32_bf16 v[36:39], v[180:183], v[198:201], v[36:39]
	v_mfma_f32_16x16x32_bf16 v[28:31], v[172:175], v[206:209], v[28:31]
	v_mfma_f32_16x16x32_bf16 v[20:23], v[180:183], v[206:209], v[20:23]
	v_mfma_f32_16x16x32_bf16 v[12:15], v[172:175], v[214:217], v[12:15]
	v_mfma_f32_16x16x32_bf16 v[4:7], v[180:183], v[214:217], v[4:7]
	s_barrier
	s_setprio 0
	s_add_i32 s51, s51, 2
	s_add_u32 s22, s22, 0x100
	s_addc_u32 s23, s23, 0
	s_add_u32 s49, s49, 0x100
	s_addc_u32 s50, s50, 0
	s_cmp_gt_u32 s51, 13
	s_cbranch_scc0 .LBB0_782
	s_and_b64 vcc, exec, s[12:13]
	s_cbranch_vccz .LBB0_785
	s_barrier
